# v33: + gdn_prep conv loads de-serialised; P6 E3/E4 slot re-loads issued ~35 deep (private dest ring)
# speedup vs baseline: 1.0951x; 1.0353x over previous
.LBB0_2870:
	s_or_saveexec_b64 s[36:37], s[0:1]
	v_mov_b32_e32 v54, 0
	v_mov_b32_e32 v55, 0
	v_mov_b32_e32 v60, 0
	v_mov_b32_e32 v61, 0
	v_mov_b32_e32 v6, 0
	v_mov_b32_e32 v7, 0
	v_mov_b32_e32 v10, 0
	v_mov_b32_e32 v11, 0
	s_xor_b64 exec, exec, s[36:37]
	s_cbranch_execz .LBB0_2872
	s_waitcnt vmcnt(0)
	v_mov_b32_e32 v232, v66
	v_or_b32_e32 v230,4,v41
	v_cndmask_b32_e64 v230,0,v230,s[34:35]
	v_add_u32_e32 v230,s41,v230
	v_ashrrev_i32_e32 v231,31,v230
	v_lshlrev_b64 v[230:231],12,v[230:231]
	v_lshl_add_u64 v[230:231],s[42:43],0,v[230:231]
	v_mov_b32_e32 v233,v21
	v_lshl_add_u64 v[234:235],v[230:231],0,v[232:233]
	global_load_ushort v190, v[234:235], off
	v_mov_b32_e32 v230, v66
	v_mov_b32_e32 v232, v40
	v_mov_b32_e32 v231,v21
	v_add_u32_e32 v233,s41,v41
	v_add_u32_e32 v234,5,v233
	v_ashrrev_i32_e32 v235,31,v234
	v_lshlrev_b64 v[234:235],12,v[234:235]
	v_lshl_add_u64 v[236:237],s[42:43],0,v[234:235]
	v_lshl_add_u64 v[234:235],v[236:237],0,v[230:231]
	global_load_ushort v191, v[234:235], off
	v_mov_b32_e32 v230, v66
	v_mov_b32_e32 v232, v40
	v_mov_b32_e32 v231,v21
	v_add_u32_e32 v233,s41,v41
	v_add_u32_e32 v234,6,v233
	v_ashrrev_i32_e32 v235,31,v234
	v_lshlrev_b64 v[234:235],12,v[234:235]
	v_lshl_add_u64 v[234:235],s[42:43],0,v[234:235]
	v_lshl_add_u64 v[236:237],v[234:235],0,v[230:231]
	global_load_ushort v192, v[236:237], off
	v_mov_b32_e32 v230, v66
	v_mov_b32_e32 v232, v40
	v_mov_b32_e32 v231,v21
	v_add_u32_e32 v233,s41,v41
	v_add_u32_e32 v234,7,v233
	v_ashrrev_i32_e32 v235,31,v234
	v_lshlrev_b64 v[234:235],12,v[234:235]
	v_lshl_add_u64 v[234:235],s[42:43],0,v[234:235]
	v_lshl_add_u64 v[236:237],v[234:235],0,v[230:231]
	global_load_ushort v193, v[236:237], off
	v_add_u32_e32 v230,0x740,v20
	v_mov_b32_e32 v231,v21
	v_lshl_add_u64 v[232:233],v[44:45],0,v[230:231]
	global_load_ushort v194, v[232:233], off
	global_load_ushort v195, v[14:15], off offset:1856
	global_load_ushort v196, v[4:5], off offset:1856
	s_movk_i32 s100,0x5000
	v_add_co_u32_e64 v230,s[100:101],s100,v48
	s_nop 1
	v_addc_co_u32_e64 v231,s[100:101],0,v49,s[100:101]
	global_load_dword v197, v[230:231], off
	global_load_dword v198, v[58:59], off offset:2048
	s_movk_i32 s100,0x2000
	v_add_co_u32_e64 v230,s[100:101],s100,v48
	s_nop 1
	v_addc_co_u32_e64 v231,s[100:101],0,v49,s[100:101]
	global_load_dword v199, v[230:231], off
	global_load_dword v200, v[48:49], off offset:2048
	v_lshl_add_u64 v[230:231],v[56:57],0,v[20:21]
	global_load_ushort v201, v[230:231], off offset:1856
	v_add_u32_e32 v230,0x740,v20
	v_mov_b32_e32 v231,v21
	v_lshl_add_u64 v[232:233],v[52:53],0,v[230:231]
	global_load_ushort v202, v[232:233], off
	v_add_u32_e32 v230,0x740,v20
	v_mov_b32_e32 v231,v21
	v_lshl_add_u64 v[232:233],v[0:1],0,v[230:231]
	global_load_ushort v203, v[232:233], off
	v_add_u32_e32 v230,0x740,v20
	v_mov_b32_e32 v231,v21
	v_lshl_add_u64 v[232:233],v[2:3],0,v[230:231]
	global_load_ushort v204, v[232:233], off
	v_or_b32_e32 v230,4,v41
	v_cndmask_b32_e64 v230,0,v230,s[34:35]
	v_add_u32_e32 v230,s41,v230
	v_ashrrev_i32_e32 v231,31,v230
	v_lshlrev_b64 v[230:231],12,v[230:231]
	v_lshl_add_u64 v[230:231],s[42:43],0,v[230:231]
	v_add_u32_e32 v232,0x740,v20
	v_mov_b32_e32 v233,v21
	v_lshl_add_u64 v[234:235],v[230:231],0,v[232:233]
	global_load_ushort v205, v[234:235], off
	v_mov_b32_e32 v230, v40
	v_add_u32_e32 v231,s41,v41
	v_add_u32_e32 v232,5,v231
	v_ashrrev_i32_e32 v233,31,v232
	v_lshlrev_b64 v[232:233],12,v[232:233]
	v_lshl_add_u64 v[234:235],s[42:43],0,v[232:233]
	v_add_u32_e32 v236,0x740,v20
	v_mov_b32_e32 v237,v21
	v_lshl_add_u64 v[240:241],v[234:235],0,v[236:237]
	global_load_ushort v206, v[240:241], off
	v_mov_b32_e32 v230, v40
	v_add_u32_e32 v231,s41,v41
	v_add_u32_e32 v232,6,v231
	v_ashrrev_i32_e32 v233,31,v232
	v_lshlrev_b64 v[232:233],12,v[232:233]
	v_lshl_add_u64 v[232:233],s[42:43],0,v[232:233]
	v_add_u32_e32 v234,0x740,v20
	v_mov_b32_e32 v235,v21
	v_lshl_add_u64 v[236:237],v[232:233],0,v[234:235]
	global_load_ushort v207, v[236:237], off
	v_mov_b32_e32 v230, v40
	v_add_u32_e32 v231,s41,v41
	v_add_u32_e32 v232,7,v231
	v_ashrrev_i32_e32 v233,31,v232
	v_lshlrev_b64 v[232:233],12,v[232:233]
	v_lshl_add_u64 v[232:233],s[42:43],0,v[232:233]
	v_add_u32_e32 v234,0x740,v20
	v_mov_b32_e32 v235,v21
	v_lshl_add_u64 v[236:237],v[232:233],0,v[234:235]
	global_load_ushort v214, v[236:237], off
	s_movk_i32 s100,0x5000
	v_add_co_u32_e64 v230,s[100:101],s100,v48
	s_nop 1
	v_addc_co_u32_e64 v231,s[100:101],0,v49,s[100:101]
	global_load_dword v248, v[230:231], off offset:2048
	global_load_dword v250, v[46:47], off
	global_load_ushort v215, v[14:15], off offset:2880
	global_load_ushort v216, v[4:5], off offset:2880
	v_lshl_add_u64 v[230:231],v[56:57],0,v[20:21]
	global_load_ushort v217, v[230:231], off offset:2880
	v_mov_b32_e32 v231, v21
	v_add_u32_e32 v230,0xb40,v20
	v_lshl_add_u64 v[232:233],v[44:45],0,v[230:231]
	global_load_ushort v218, v[232:233], off
	v_mov_b32_e32 v231, v21
	v_add_u32_e32 v230,0xb40,v20
	v_lshl_add_u64 v[232:233],v[52:53],0,v[230:231]
	global_load_ushort v219, v[232:233], off
	v_mov_b32_e32 v231, v21
	v_add_u32_e32 v230,0xb40,v20
	v_lshl_add_u64 v[232:233],v[2:3],0,v[230:231]
	global_load_ushort v220, v[232:233], off
	v_mov_b32_e32 v231, v21
	v_add_u32_e32 v230,0xb40,v20
	v_lshl_add_u64 v[232:233],v[0:1],0,v[230:231]
	global_load_ushort v221, v[232:233], off
	v_mov_b32_e32 v230, v40
	v_mov_b32_e32 v237, v21
	v_add_u32_e32 v231,s41,v41
	v_add_u32_e32 v232,5,v231
	v_ashrrev_i32_e32 v233,31,v232
	v_lshlrev_b64 v[232:233],12,v[232:233]
	v_lshl_add_u64 v[234:235],s[42:43],0,v[232:233]
	v_add_u32_e32 v236,0xb40,v20
	v_lshl_add_u64 v[240:241],v[234:235],0,v[236:237]
	global_load_ushort v222, v[240:241], off
	v_mov_b32_e32 v233, v21
	v_or_b32_e32 v230,4,v41
	v_cndmask_b32_e64 v230,0,v230,s[34:35]
	v_add_u32_e32 v230,s41,v230
	v_ashrrev_i32_e32 v231,31,v230
	v_lshlrev_b64 v[230:231],12,v[230:231]
	v_lshl_add_u64 v[230:231],s[42:43],0,v[230:231]
	v_add_u32_e32 v232,0xb40,v20
	v_lshl_add_u64 v[234:235],v[230:231],0,v[232:233]
	global_load_ushort v223, v[234:235], off
	v_mov_b32_e32 v230, v40
	v_mov_b32_e32 v235, v21
	v_add_u32_e32 v231,s41,v41
	v_add_u32_e32 v232,7,v231
	v_ashrrev_i32_e32 v233,31,v232
	v_lshlrev_b64 v[232:233],12,v[232:233]
	v_lshl_add_u64 v[232:233],s[42:43],0,v[232:233]
	v_add_u32_e32 v234,0xb40,v20
	v_lshl_add_u64 v[236:237],v[232:233],0,v[234:235]
	global_load_ushort v224, v[236:237], off
	v_mov_b32_e32 v230, v40
	v_mov_b32_e32 v235, v21
	v_add_u32_e32 v231,s41,v41
	v_add_u32_e32 v232,6,v231
	v_ashrrev_i32_e32 v233,31,v232
	v_lshlrev_b64 v[232:233],12,v[232:233]
	v_lshl_add_u64 v[232:233],s[42:43],0,v[232:233]
	v_add_u32_e32 v234,0xb40,v20
	v_lshl_add_u64 v[236:237],v[232:233],0,v[234:235]
	global_load_ushort v225, v[236:237], off
	v_or_b32_e32 v6, 4, v41
	v_cndmask_b32_e64 v6, 0, v6, s[34:35]
	v_add_u32_e32 v6, s41, v6
	v_ashrrev_i32_e32 v7, 31, v6
	v_lshlrev_b64 v[6:7], 12, v[6:7]
	v_lshl_add_u64 v[6:7], s[42:43], 0, v[6:7]
	v_mov_b32_e32 v67, v21
	v_lshl_add_u64 v[10:11], v[6:7], 0, v[66:67]
	v_mov_b32_e32 v10, v63
	v_mov_b32_e32 v11, v62
	v_mov_b32_e32 v68, v9
	v_mov_b32_e32 v54, v13
	v_add_u32_e32 v41, s41, v41
	s_movk_i32 s0, 0x5000
	s_waitcnt vmcnt(31)
	v_lshlrev_b32_e32 v55, 16, v190
	v_pk_mul_f32 v[8:9], v[10:11], v[68:69]
	v_mov_b32_e32 v10, v65
	v_mov_b32_e32 v11, v64
	v_pk_mul_f32 v[10:11], v[10:11], v[54:55]
	v_add_f32_e32 v8, v8, v9
	v_add_f32_e32 v8, v8, v10
	v_add_f32_e32 v8, v8, v11
	v_mul_f32_e32 v9, 0xbfb8aa3b, v8
	v_exp_f32_e32 v9, v9
	s_nop 0
	v_add_f32_e32 v9, 1.0, v9
	v_rcp_f32_e32 v9, v9
	s_nop 0
	v_mul_f32_e32 v12, v8, v9
	v_add_u32_e32 v8, 5, v41
	v_ashrrev_i32_e32 v9, 31, v8
	v_lshlrev_b64 v[8:9], 12, v[8:9]
	v_lshl_add_u64 v[10:11], s[42:43], 0, v[8:9]
	v_lshl_add_u64 v[8:9], v[10:11], 0, v[66:67]
	s_waitcnt vmcnt(30)
	v_lshlrev_b32_e32 v43, 16, v191
	v_mul_f32_e32 v8, v62, v13
	v_fmac_f32_e32 v8, v63, v69
	v_fmac_f32_e32 v8, v65, v55
	v_fmac_f32_e32 v8, v64, v43
	v_mul_f32_e32 v9, 0xbfb8aa3b, v8
	v_exp_f32_e32 v9, v9
	s_nop 0
	v_add_f32_e32 v9, 1.0, v9
	v_rcp_f32_e32 v9, v9
	s_nop 0
	v_mul_f32_e32 v8, v8, v9
	ds_write2_b32 v176, v12, v8 offset0:4 offset1:69
	v_add_u32_e32 v8, 6, v41
	v_ashrrev_i32_e32 v9, 31, v8
	v_lshlrev_b64 v[8:9], 12, v[8:9]
	v_lshl_add_u64 v[8:9], s[42:43], 0, v[8:9]
	v_lshl_add_u64 v[60:61], v[8:9], 0, v[66:67]
	s_waitcnt vmcnt(29)
	v_lshlrev_b32_e32 v54, 16, v192
	v_mul_f32_e32 v12, v62, v55
	v_fmac_f32_e32 v12, v63, v13
	v_fmac_f32_e32 v12, v65, v43
	v_fmac_f32_e32 v12, v64, v54
	v_mul_f32_e32 v13, 0xbfb8aa3b, v12
	v_exp_f32_e32 v13, v13
	v_mul_f32_e32 v43, v62, v43
	v_fmac_f32_e32 v43, v63, v55
	v_fmac_f32_e32 v43, v65, v54
	v_add_f32_e32 v13, 1.0, v13
	v_rcp_f32_e32 v13, v13
	v_add_co_u32_e64 v62, s[0:1], s0, v48
	v_mul_f32_e32 v68, v12, v13
	v_add_u32_e32 v12, 7, v41
	v_ashrrev_i32_e32 v13, 31, v12
	v_lshlrev_b64 v[12:13], 12, v[12:13]
	v_lshl_add_u64 v[12:13], s[42:43], 0, v[12:13]
	v_lshl_add_u64 v[60:61], v[12:13], 0, v[66:67]
	v_add_u32_e32 v60, 0x740, v20
	v_mov_b32_e32 v61, v21
	v_lshl_add_u64 v[54:55], v[44:45], 0, v[60:61]
	v_addc_co_u32_e64 v63, s[0:1], 0, v49, s[0:1]
	s_movk_i32 s0, 0x2000
	s_waitcnt vmcnt(28)
	v_lshlrev_b32_e32 v41, 16, v193
	v_fmac_f32_e32 v43, v64, v41
	v_mul_f32_e32 v41, 0xbfb8aa3b, v43
	v_exp_f32_e32 v41, v41
	s_nop 0
	v_add_f32_e32 v41, 1.0, v41
	v_rcp_f32_e32 v41, v41
	s_nop 0
	v_mul_f32_e32 v41, v43, v41
	s_waitcnt vmcnt(27)
	v_lshlrev_b32_e32 v43, 16, v194
	s_waitcnt vmcnt(26)
	v_lshlrev_b32_e32 v54, 16, v195
	v_cndmask_b32_e64 v64, 0, v54, s[28:29]
	v_add_co_u32_e64 v58, s[0:1], s0, v48
	s_waitcnt vmcnt(25)
	v_lshlrev_b32_e32 v54, 16, v196
	v_cndmask_b32_e64 v65, 0, v54, s[30:31]
	v_addc_co_u32_e64 v59, s[0:1], 0, v49, s[0:1]
	v_lshl_add_u64 v[54:55], v[56:57], 0, v[20:21]
	v_add_u32_e32 v20, 0xb40, v20
	s_waitcnt vmcnt(20)
	v_lshlrev_b32_e32 v48, 16, v201
	v_cndmask_b32_e32 v48, 0, v48, vcc
	v_mul_f32_e32 v48, v200, v48
	v_fmac_f32_e32 v48, v199, v65
	v_fmac_f32_e32 v48, v198, v64
	v_fmac_f32_e32 v48, v197, v43
	v_mul_f32_e32 v49, 0xbfb8aa3b, v48
	v_exp_f32_e32 v49, v49
	s_nop 0
	v_add_f32_e32 v49, 1.0, v49
	v_rcp_f32_e32 v49, v49
	s_nop 0
	v_mul_f32_e32 v56, v48, v49
	v_lshl_add_u64 v[48:49], v[52:53], 0, v[60:61]
	v_lshl_add_u64 v[52:53], v[52:53], 0, v[20:21]
	s_waitcnt vmcnt(19)
	v_lshlrev_b32_e32 v57, 16, v202
	v_mul_f32_e32 v48, v200, v65
	v_fmac_f32_e32 v48, v199, v64
	v_fmac_f32_e32 v48, v198, v43
	v_fmac_f32_e32 v48, v197, v57
	v_mul_f32_e32 v49, 0xbfb8aa3b, v48
	v_exp_f32_e32 v49, v49
	s_nop 0
	v_add_f32_e32 v49, 1.0, v49
	v_rcp_f32_e32 v49, v49
	s_nop 0
	v_mul_f32_e32 v65, v48, v49
	v_lshl_add_u64 v[48:49], v[0:1], 0, v[60:61]
	v_lshl_add_u64 v[0:1], v[0:1], 0, v[20:21]
	s_waitcnt vmcnt(18)
	v_lshlrev_b32_e32 v185, 16, v203
	v_mul_f32_e32 v48, v64, v200
	v_fmac_f32_e32 v48, v199, v43
	v_fmac_f32_e32 v48, v198, v57
	v_fmac_f32_e32 v48, v197, v185
	v_mul_f32_e32 v49, 0xbfb8aa3b, v48
	v_exp_f32_e32 v49, v49
	s_nop 0
	v_add_f32_e32 v49, 1.0, v49
	v_rcp_f32_e32 v49, v49
	s_nop 0
	v_mul_f32_e32 v64, v48, v49
	v_lshl_add_u64 v[48:49], v[2:3], 0, v[60:61]
	v_lshl_add_u64 v[2:3], v[2:3], 0, v[20:21]
	s_waitcnt vmcnt(17)
	v_lshlrev_b32_e32 v186, 16, v204
	v_mul_f32_e32 v48, v199, v57
	v_fmac_f32_e32 v48, v200, v43
	v_fmac_f32_e32 v48, v198, v185
	v_fmac_f32_e32 v48, v197, v186
	v_mul_f32_e32 v43, 0xbfb8aa3b, v48
	v_exp_f32_e32 v43, v43
	s_nop 0
	v_add_f32_e32 v43, 1.0, v43
	v_rcp_f32_e32 v43, v43
	s_nop 0
	v_mul_f32_e32 v43, v48, v43
	v_lshl_add_u64 v[48:49], v[6:7], 0, v[60:61]
	s_waitcnt vmcnt(16)
	v_lshlrev_b32_e32 v187, 16, v205
	v_mul_f32_e32 v48, v199, v185
	v_fmac_f32_e32 v48, v200, v57
	v_fmac_f32_e32 v48, v198, v186
	v_fmac_f32_e32 v48, v197, v187
	v_mul_f32_e32 v49, 0xbfb8aa3b, v48
	v_exp_f32_e32 v49, v49
	s_nop 0
	v_add_f32_e32 v49, 1.0, v49
	v_rcp_f32_e32 v49, v49
	s_nop 0
	v_mul_f32_e32 v57, v48, v49
	v_lshl_add_u64 v[48:49], v[10:11], 0, v[60:61]
	s_waitcnt vmcnt(15)
	v_lshlrev_b32_e32 v188, 16, v206
	v_mul_f32_e32 v48, v199, v186
	v_fmac_f32_e32 v48, v200, v185
	v_fmac_f32_e32 v48, v198, v187
	v_fmac_f32_e32 v48, v197, v188
	v_mul_f32_e32 v49, 0xbfb8aa3b, v48
	v_exp_f32_e32 v49, v49
	s_nop 0
	v_add_f32_e32 v49, 1.0, v49
	v_rcp_f32_e32 v49, v49
	s_nop 0
	v_mul_f32_e32 v185, v48, v49
	v_lshl_add_u64 v[48:49], v[8:9], 0, v[60:61]
	s_waitcnt vmcnt(14)
	v_lshlrev_b32_e32 v189, 16, v207
	v_mul_f32_e32 v48, v199, v187
	v_fmac_f32_e32 v48, v200, v186
	v_fmac_f32_e32 v48, v198, v188
	v_fmac_f32_e32 v48, v197, v189
	v_mul_f32_e32 v49, 0xbfb8aa3b, v48
	v_exp_f32_e32 v49, v49
	s_nop 0
	v_add_f32_e32 v49, 1.0, v49
	v_rcp_f32_e32 v49, v49
	s_nop 0
	v_mul_f32_e32 v186, v48, v49
	v_lshl_add_u64 v[48:49], v[12:13], 0, v[60:61]
	v_mul_f32_e32 v49, v199, v188
	v_fmac_f32_e32 v49, v200, v187
	v_fmac_f32_e32 v49, v198, v189
	s_waitcnt vmcnt(13)
	v_lshlrev_b32_e32 v48, 16, v214
	v_fmac_f32_e32 v49, v197, v48
	v_mul_f32_e32 v48, 0xbfb8aa3b, v49
	v_exp_f32_e32 v48, v48
	s_nop 0
	v_add_f32_e32 v48, 1.0, v48
	v_rcp_f32_e32 v48, v48
	s_nop 0
	v_mul_f32_e32 v48, v49, v48
	ds_write2_b32 v176, v68, v41 offset0:134 offset1:199
	ds_write2_b32 v177, v56, v65 offset0:64 offset1:129
	ds_write2_b32 v178, v64, v43 offset0:66 offset1:131
	ds_write2_b32 v179, v57, v185 offset0:68 offset1:133
	ds_write2_b32 v180, v186, v48 offset0:70 offset1:135
	v_lshl_add_u64 v[56:57], v[44:45], 0, v[20:21]
	s_nop 0
	s_nop 0
	global_load_dword v48, v[58:59], off offset:2048
	s_nop 0
	global_load_dword v50, v[50:51], off
	s_nop 0
	s_nop 0
	s_nop 0
	s_nop 0
	s_nop 0
	s_waitcnt vmcnt(12)
	v_lshlrev_b32_e32 v14, 16, v215
	s_waitcnt vmcnt(11)
	v_lshlrev_b32_e32 v4, 16, v216
	s_waitcnt vmcnt(10)
	v_lshlrev_b32_e32 v15, 16, v217
	v_cndmask_b32_e64 v4, 0, v4, s[30:31]
	v_cndmask_b32_e64 v5, 0, v14, s[28:29]
	v_cndmask_b32_e32 v14, 0, v15, vcc
	v_mov_b32_e32 v15, v4
	s_waitcnt vmcnt(8)
	v_lshlrev_b32_e32 v53, 16, v219
	v_lshlrev_b32_e32 v52, 16, v218
	s_waitcnt vmcnt(0)
	v_pk_mul_f32 v[14:15], v[50:51], v[14:15] op_sel_hi:[0,1]
	v_pk_fma_f32 v[14:15], v[48:49], v[4:5], v[14:15] op_sel_hi:[0,1,1]
	v_pk_mov_b32 v[54:55], v[4:5], v[52:53] op_sel:[1,0]
	v_mov_b32_e32 v51, v48
	v_pk_fma_f32 v[14:15], v[250:251], v[54:55], v[14:15] op_sel_hi:[0,1,1]
	v_pk_fma_f32 v[14:15], v[248:249], v[52:53], v[14:15] op_sel_hi:[0,1,1]
	v_mul_f32_e32 v4, 0xbfb8aa3b, v14
	v_exp_f32_e32 v4, v4
	v_lshlrev_b32_e32 v3, 16, v221
	v_lshlrev_b32_e32 v2, 16, v220
	v_add_f32_e32 v4, 1.0, v4
	v_rcp_f32_e32 v54, v4
	v_mul_f32_e32 v4, 0xbfb8aa3b, v15
	v_exp_f32_e32 v4, v4
	s_nop 0
	v_add_f32_e32 v4, 1.0, v4
	v_rcp_f32_e32 v55, v4
	v_mov_b32_e32 v4, v53
	v_pk_mul_f32 v[0:1], v[4:5], v[50:51] op_sel:[0,1] op_sel_hi:[1,0]
	v_pk_mul_f32 v[54:55], v[14:15], v[54:55]
	v_pk_fma_f32 v[0:1], v[50:51], v[52:53], v[0:1] op_sel_hi:[1,0,1]
	v_mov_b32_e32 v52, v3
	v_pk_fma_f32 v[0:1], v[250:251], v[52:53], v[0:1] op_sel_hi:[0,1,1]
	v_pk_fma_f32 v[0:1], v[248:249], v[2:3], v[0:1] op_sel_hi:[0,1,1]
	v_mul_f32_e32 v4, 0xbfb8aa3b, v1
	v_exp_f32_e32 v4, v4
	s_nop 0
	v_add_f32_e32 v4, 1.0, v4
	v_rcp_f32_e32 v5, v4
	v_mul_f32_e32 v4, 0xbfb8aa3b, v0
	v_exp_f32_e32 v4, v4
	s_nop 0
	v_add_f32_e32 v4, 1.0, v4
	v_rcp_f32_e32 v4, v4
	s_nop 0
	v_pk_mul_f32 v[60:61], v[0:1], v[4:5]
	v_lshl_add_u64 v[0:1], v[6:7], 0, v[20:21]
	v_lshl_add_u64 v[4:5], v[10:11], 0, v[20:21]
	s_nop 0
	v_lshlrev_b32_e32 v1, 16, v223
	v_lshlrev_b32_e32 v0, 16, v222
	v_pk_mul_f32 v[4:5], v[48:49], v[2:3] op_sel_hi:[0,1]
	v_pk_fma_f32 v[4:5], v[50:51], v[52:53], v[4:5] op_sel_hi:[0,1,1]
	v_pk_mov_b32 v[2:3], v[0:1], v[2:3] op_sel:[1,0]
	s_nop 0
	v_pk_fma_f32 v[4:5], v[250:251], v[2:3], v[4:5] op_sel_hi:[0,1,1]
	v_pk_fma_f32 v[4:5], v[248:249], v[0:1], v[4:5] op_sel_hi:[0,1,1]
	v_mul_f32_e32 v6, 0xbfb8aa3b, v5
	v_exp_f32_e32 v6, v6
	s_nop 0
	v_add_f32_e32 v6, 1.0, v6
	v_rcp_f32_e32 v7, v6
	v_mul_f32_e32 v6, 0xbfb8aa3b, v4
	v_exp_f32_e32 v6, v6
	s_nop 0
	v_add_f32_e32 v6, 1.0, v6
	v_rcp_f32_e32 v6, v6
	s_nop 0
	v_pk_mul_f32 v[6:7], v[4:5], v[6:7]
	v_lshl_add_u64 v[4:5], v[8:9], 0, v[20:21]
	v_lshl_add_u64 v[8:9], v[12:13], 0, v[20:21]
	s_nop 0
	v_lshlrev_b32_e32 v5, 16, v225
	v_lshlrev_b32_e32 v4, 16, v224
	v_pk_mul_f32 v[8:9], v[48:49], v[0:1] op_sel_hi:[0,1]
	v_pk_fma_f32 v[2:3], v[50:51], v[2:3], v[8:9] op_sel_hi:[0,1,1]
	v_pk_mov_b32 v[0:1], v[4:5], v[0:1] op_sel:[1,0]
	s_nop 0
	v_pk_fma_f32 v[0:1], v[250:251], v[0:1], v[2:3] op_sel_hi:[0,1,1]
	v_pk_fma_f32 v[0:1], v[248:249], v[4:5], v[0:1] op_sel_hi:[0,1,1]
	v_mul_f32_e32 v2, 0xbfb8aa3b, v1
	v_exp_f32_e32 v2, v2
	s_nop 0
	v_add_f32_e32 v2, 1.0, v2
	v_rcp_f32_e32 v3, v2
	v_mul_f32_e32 v2, 0xbfb8aa3b, v0
	v_exp_f32_e32 v2, v2
	s_nop 0
	v_add_f32_e32 v2, 1.0, v2
	v_rcp_f32_e32 v2, v2
	s_nop 0
	v_pk_mul_f32 v[10:11], v[0:1], v[2:3]

.LBB0_3373:
	s_waitcnt vmcnt(0)
	v_mov_b32_e32 v0, v208
	v_mov_b32_e32 v2, v1
	v_lshrrev_b32_e32 v3, 1, v0
	v_and_b32_e32 v3, 0x3fff80, v3
	v_lshrrev_b32_e32 v4, 3, v0
	v_add_u32_e32 v3, s0, v3
	v_and_b32_e32 v0, 0xdf, v0
	v_and_or_b32 v3, v4, 4, v3
	v_or_b32_e32 v0, s6, v0
	v_lshlrev_b32_e32 v5, 10, v3
	v_add_u32_e32 v4, v0, v2
	v_add_u32_e32 v0, v5, v4
	v_lshlrev_b64 v[2:3], 1, v[0:1]
	v_lshl_add_u64 v[6:7], s[18:19], 0, v[2:3]
	v_lshl_add_u64 v[2:3], s[62:63], 0, v[2:3]
	global_load_ushort v192, v[6:7], off
	global_load_ushort v193, v[2:3], off
	v_mov_b32_e32 v233, v1
	v_or_b32_e32 v230,0x400,v5
	v_add_u32_e32 v232,v230,v4
	v_lshlrev_b64 v[234:235],1,v[232:233]
	v_lshl_add_u64 v[236:237],s[18:19],0,v[234:235]
	global_load_ushort v194, v[236:237], off
	v_mov_b32_e32 v233, v1
	v_or_b32_e32 v231,0x800,v5
	v_add_u32_e32 v232,v231,v4
	v_lshlrev_b64 v[234:235],1,v[232:233]
	v_lshl_add_u64 v[236:237],s[18:19],0,v[234:235]
	global_load_ushort v195, v[236:237], off
	v_mov_b32_e32 v233, v1
	v_or_b32_e32 v231,0x2000,v5
	v_add_u32_e32 v232,v231,v4
	v_lshlrev_b64 v[234:235],1,v[232:233]
	v_lshl_add_u64 v[236:237],s[18:19],0,v[234:235]
	global_load_ushort v196, v[236:237], off
	v_mov_b32_e32 v233, v1
	v_or_b32_e32 v231,0x4000,v5
	v_add_u32_e32 v232,v231,v4
	v_lshlrev_b64 v[234:235],1,v[232:233]
	v_lshl_add_u64 v[236:237],s[18:19],0,v[234:235]
	global_load_ushort v197, v[236:237], off
	v_mov_b32_e32 v233, v1
	v_or_b32_e32 v230,0x400,v5
	v_add_u32_e32 v232,v230,v4
	v_lshlrev_b64 v[234:235],1,v[232:233]
	v_lshl_add_u64 v[234:235],s[62:63],0,v[234:235]
	global_load_ushort v198, v[234:235], off
	v_mov_b32_e32 v233, v1
	v_or_b32_e32 v230,0xc00,v5
	v_add_u32_e32 v232,v230,v4
	v_lshlrev_b64 v[234:235],1,v[232:233]
	v_lshl_add_u64 v[236:237],s[18:19],0,v[234:235]
	global_load_ushort v199, v[236:237], off
	v_mov_b32_e32 v233, v1
	v_or_b32_e32 v231,0x2800,v5
	v_add_u32_e32 v232,v231,v4
	v_lshlrev_b64 v[234:235],1,v[232:233]
	v_lshl_add_u64 v[236:237],s[18:19],0,v[234:235]
	global_load_ushort v201, v[236:237], off
	v_mov_b32_e32 v233, v1
	v_or_b32_e32 v231,0x6000,v5
	v_add_u32_e32 v232,v231,v4
	v_lshlrev_b64 v[234:235],1,v[232:233]
	v_lshl_add_u64 v[236:237],s[18:19],0,v[234:235]
	global_load_ushort v202, v[236:237], off
	v_mov_b32_e32 v233, v1
	v_or_b32_e32 v231,0x800,v5
	v_add_u32_e32 v232,v231,v4
	v_lshlrev_b64 v[234:235],1,v[232:233]
	v_lshl_add_u64 v[236:237],s[62:63],0,v[234:235]
	global_load_ushort v203, v[236:237], off
	v_mov_b32_e32 v233, v1
	v_or_b32_e32 v230,0x2400,v5
	v_add_u32_e32 v232,v230,v4
	v_lshlrev_b64 v[234:235],1,v[232:233]
	v_lshl_add_u64 v[236:237],s[18:19],0,v[234:235]
	global_load_ushort v204, v[236:237], off
	v_mov_b32_e32 v233, v1
	v_or_b32_e32 v231,0x4800,v5
	v_add_u32_e32 v232,v231,v4
	v_lshlrev_b64 v[234:235],1,v[232:233]
	v_lshl_add_u64 v[236:237],s[18:19],0,v[234:235]
	global_load_ushort v205, v[236:237], off
	v_mov_b32_e32 v233, v1
	v_or_b32_e32 v230,0xc00,v5
	v_add_u32_e32 v232,v230,v4
	v_lshlrev_b64 v[234:235],1,v[232:233]
	v_lshl_add_u64 v[236:237],s[62:63],0,v[234:235]
	global_load_ushort v206, v[236:237], off
	v_mov_b32_e32 v233, v1
	v_or_b32_e32 v230,0x2c00,v5
	v_add_u32_e32 v232,v230,v4
	v_lshlrev_b64 v[234:235],1,v[232:233]
	v_lshl_add_u64 v[236:237],s[18:19],0,v[234:235]
	global_load_ushort v207, v[236:237], off
	v_mov_b32_e32 v233, v1
	v_or_b32_e32 v230,0x6800,v5
	v_add_u32_e32 v232,v230,v4
	v_lshlrev_b64 v[234:235],1,v[232:233]
	v_lshl_add_u64 v[236:237],s[18:19],0,v[234:235]
	global_load_ushort v209, v[236:237], off
	v_mov_b32_e32 v233, v1
	v_or_b32_e32 v231,0x2000,v5
	v_add_u32_e32 v232,v231,v4
	v_lshlrev_b64 v[234:235],1,v[232:233]
	v_lshl_add_u64 v[236:237],s[62:63],0,v[234:235]
	global_load_ushort v210, v[236:237], off
	v_mov_b32_e32 v233, v1
	v_or_b32_e32 v230,0x4400,v5
	v_add_u32_e32 v232,v230,v4
	v_lshlrev_b64 v[234:235],1,v[232:233]
	v_lshl_add_u64 v[236:237],s[18:19],0,v[234:235]
	global_load_ushort v211, v[236:237], off
	v_mov_b32_e32 v233, v1
	v_or_b32_e32 v230,0x2400,v5
	v_add_u32_e32 v232,v230,v4
	v_lshlrev_b64 v[234:235],1,v[232:233]
	v_lshl_add_u64 v[236:237],s[62:63],0,v[234:235]
	global_load_ushort v212, v[236:237], off
	v_mov_b32_e32 v233, v1
	v_or_b32_e32 v230,0x4c00,v5
	v_add_u32_e32 v232,v230,v4
	v_lshlrev_b64 v[234:235],1,v[232:233]
	v_lshl_add_u64 v[236:237],s[18:19],0,v[234:235]
	global_load_ushort v213, v[236:237], off
	v_mov_b32_e32 v233, v1
	v_or_b32_e32 v231,0x2800,v5
	v_add_u32_e32 v232,v231,v4
	v_lshlrev_b64 v[234:235],1,v[232:233]
	v_lshl_add_u64 v[236:237],s[62:63],0,v[234:235]
	global_load_ushort v214, v[236:237], off
	v_mov_b32_e32 v233, v1
	v_or_b32_e32 v231,0x6400,v5
	v_add_u32_e32 v232,v231,v4
	v_lshlrev_b64 v[234:235],1,v[232:233]
	v_lshl_add_u64 v[236:237],s[18:19],0,v[234:235]
	global_load_ushort v215, v[236:237], off
	v_mov_b32_e32 v233, v1
	v_or_b32_e32 v230,0x2c00,v5
	v_add_u32_e32 v232,v230,v4
	v_lshlrev_b64 v[234:235],1,v[232:233]
	v_lshl_add_u64 v[236:237],s[62:63],0,v[234:235]
	global_load_ushort v216, v[236:237], off
	v_mov_b32_e32 v233, v1
	v_or_b32_e32 v230,0x6c00,v5
	v_add_u32_e32 v232,v230,v4
	v_lshlrev_b64 v[234:235],1,v[232:233]
	v_lshl_add_u64 v[236:237],s[18:19],0,v[234:235]
	global_load_ushort v217, v[236:237], off
	v_mov_b32_e32 v233, v1
	v_or_b32_e32 v231,0x4000,v5
	v_add_u32_e32 v232,v231,v4
	v_lshlrev_b64 v[234:235],1,v[232:233]
	v_lshl_add_u64 v[236:237],s[62:63],0,v[234:235]
	global_load_ushort v218, v[236:237], off
	v_mov_b32_e32 v233, v1
	v_or_b32_e32 v230,0x4400,v5
	v_add_u32_e32 v232,v230,v4
	v_lshlrev_b64 v[234:235],1,v[232:233]
	v_lshl_add_u64 v[236:237],s[62:63],0,v[234:235]
	global_load_ushort v219, v[236:237], off
	v_mov_b32_e32 v233, v1
	v_or_b32_e32 v231,0x4800,v5
	v_add_u32_e32 v232,v231,v4
	v_lshlrev_b64 v[234:235],1,v[232:233]
	v_lshl_add_u64 v[236:237],s[62:63],0,v[234:235]
	global_load_ushort v220, v[236:237], off
	v_mov_b32_e32 v233, v1
	v_or_b32_e32 v230,0x4c00,v5
	v_add_u32_e32 v232,v230,v4
	v_lshlrev_b64 v[234:235],1,v[232:233]
	v_lshl_add_u64 v[236:237],s[62:63],0,v[234:235]
	global_load_ushort v221, v[236:237], off
	v_mov_b32_e32 v233, v1
	v_or_b32_e32 v231,0x6000,v5
	v_add_u32_e32 v232,v231,v4
	v_lshlrev_b64 v[234:235],1,v[232:233]
	v_lshl_add_u64 v[236:237],s[62:63],0,v[234:235]
	global_load_ushort v222, v[236:237], off
	v_mov_b32_e32 v233, v1
	v_or_b32_e32 v231,0x6400,v5
	v_add_u32_e32 v232,v231,v4
	v_lshlrev_b64 v[234:235],1,v[232:233]
	v_lshl_add_u64 v[236:237],s[62:63],0,v[234:235]
	global_load_ushort v223, v[236:237], off
	v_mov_b32_e32 v233, v1
	v_or_b32_e32 v230,0x6800,v5
	v_add_u32_e32 v232,v230,v4
	v_lshlrev_b64 v[234:235],1,v[232:233]
	v_lshl_add_u64 v[236:237],s[62:63],0,v[234:235]
	global_load_ushort v224, v[236:237], off
	v_mov_b32_e32 v233, v1
	v_or_b32_e32 v230,0x6c00,v5
	v_add_u32_e32 v232,v230,v4
	v_lshlrev_b64 v[234:235],1,v[232:233]
	v_lshl_add_u64 v[236:237],s[62:63],0,v[234:235]
	global_load_ushort v225, v[236:237], off
	v_mov_b32_e32 v235, v1
	v_or_b32_e32 v230,0x6c00,v5
	v_add_u32_e32 v232,32,v4
	v_add_u32_e32 v234,v230,v232
	v_lshlrev_b64 v[236:237],1,v[234:235]
	v_lshl_add_u64 v[240:241],s[18:19],0,v[236:237]
	global_load_ushort v226, v[240:241], off
	v_mov_b32_e32 v233, v1
	v_add_u32_e32 v230,32,v4
	v_add_u32_e32 v232,v5,v230
	v_lshlrev_b64 v[234:235],1,v[232:233]
	v_lshl_add_u64 v[236:237],s[18:19],0,v[234:235]
	global_load_ushort v227, v[236:237], off
	v_mov_b32_e32 v233, v1
	v_add_u32_e32 v230,32,v4
	v_add_u32_e32 v232,v5,v230
	v_lshlrev_b64 v[234:235],1,v[232:233]
	v_lshl_add_u64 v[234:235],s[62:63],0,v[234:235]
	global_load_ushort v228, v[234:235], off
	v_mov_b32_e32 v235, v1
	v_or_b32_e32 v230,0x400,v5
	v_add_u32_e32 v232,32,v4
	v_add_u32_e32 v234,v230,v232
	v_lshlrev_b64 v[236:237],1,v[234:235]
	v_lshl_add_u64 v[240:241],s[18:19],0,v[236:237]
	global_load_ushort v229, v[240:241], off
	v_or_b32_e32 v170, 0x400, v5
	v_or_b32_e32 v171, 0x800, v5
	v_add_u32_e32 v0, v170, v4
	v_or_b32_e32 v172, 0xc00, v5
	v_lshlrev_b64 v[2:3], 1, v[0:1]
	v_add_u32_e32 v0, v171, v4
	v_or_b32_e32 v173, 0x2000, v5
	v_lshlrev_b64 v[10:11], 1, v[0:1]
	v_add_u32_e32 v0, v172, v4
	v_or_b32_e32 v174, 0x2400, v5
	v_lshlrev_b64 v[14:15], 1, v[0:1]
	v_add_u32_e32 v0, v173, v4
	v_or_b32_e32 v175, 0x2800, v5
	v_lshlrev_b64 v[144:145], 1, v[0:1]
	v_add_u32_e32 v0, v174, v4
	v_or_b32_e32 v176, 0x2c00, v5
	v_lshlrev_b64 v[148:149], 1, v[0:1]
	v_add_u32_e32 v0, v175, v4
	v_or_b32_e32 v177, 0x4000, v5
	v_lshlrev_b64 v[150:151], 1, v[0:1]
	v_add_u32_e32 v0, v176, v4
	v_lshlrev_b64 v[152:153], 1, v[0:1]
	v_add_u32_e32 v0, v177, v4
	v_lshlrev_b64 v[154:155], 1, v[0:1]
	v_lshl_add_u64 v[8:9], s[18:19], 0, v[2:3]
	v_lshl_add_u64 v[2:3], s[62:63], 0, v[2:3]
	v_lshl_add_u64 v[12:13], s[18:19], 0, v[10:11]
	v_lshl_add_u64 v[146:147], s[18:19], 0, v[144:145]
	v_lshl_add_u64 v[156:157], s[18:19], 0, v[154:155]
	v_or_b32_e32 v180, 0x4400, v5
	v_or_b32_e32 v181, 0x4800, v5
	v_or_b32_e32 v182, 0x4c00, v5
	v_or_b32_e32 v183, 0x6000, v5
	v_or_b32_e32 v189, 0x6400, v5
	v_or_b32_e32 v190, 0x6800, v5
	s_waitcnt vmcnt(35)
	v_lshlrev_b32_e32 v0, 16, v192
	v_mov_b32_e32 v233, v1
	v_add_u32_e32 v230,32,v4
	v_add_u32_e32 v232,v171,v230
	v_lshlrev_b64 v[234:235],1,v[232:233]
	v_lshl_add_u64 v[236:237],s[18:19],0,v[234:235]
	global_load_ushort v192, v[236:237], off
	s_waitcnt vmcnt(35)
	v_lshlrev_b32_e32 v158, 16, v193
	v_mov_b32_e32 v233, v1
	v_add_u32_e32 v230,32,v4
	v_add_u32_e32 v232,v173,v230
	v_lshlrev_b64 v[234:235],1,v[232:233]
	v_lshl_add_u64 v[236:237],s[18:19],0,v[234:235]
	global_load_ushort v193, v[236:237], off
	v_fmac_f32_e32 v0, v128, v158
	v_cvt_pk_bf16_f32 v0, v0, s0
	global_store_short v[6:7], v0, off
	v_add_u32_e32 v0, v180, v4
	v_lshlrev_b64 v[158:159], 1, v[0:1]
	v_add_u32_e32 v0, v181, v4
	v_lshlrev_b64 v[160:161], 1, v[0:1]
	v_add_u32_e32 v0, v182, v4
	v_lshlrev_b64 v[162:163], 1, v[0:1]
	v_add_u32_e32 v0, v183, v4
	v_lshlrev_b64 v[164:165], 1, v[0:1]
	v_lshl_add_u64 v[6:7], s[18:19], 0, v[14:15]
	v_lshl_add_u64 v[2:3], s[62:63], 0, v[10:11]
	v_lshl_add_u64 v[10:11], s[18:19], 0, v[150:151]
	v_lshl_add_u64 v[166:167], s[18:19], 0, v[164:165]
	s_waitcnt vmcnt(36)
	v_lshlrev_b32_e32 v0, 16, v194
	v_mov_b32_e32 v233, v1
	v_add_u32_e32 v230,32,v4
	v_add_u32_e32 v232,v177,v230
	v_lshlrev_b64 v[234:235],1,v[232:233]
	v_lshl_add_u64 v[236:237],s[18:19],0,v[234:235]
	global_load_ushort v194, v[236:237], off
	s_waitcnt vmcnt(33)
	v_lshlrev_b32_e32 v128, 16, v198
	v_mov_b32_e32 v233, v1
	v_add_u32_e32 v230,32,v4
	v_add_u32_e32 v232,v170,v230
	v_lshlrev_b64 v[234:235],1,v[232:233]
	v_lshl_add_u64 v[236:237],s[62:63],0,v[234:235]
	global_load_ushort v198, v[236:237], off
	v_fmac_f32_e32 v0, v129, v128
	v_cvt_pk_bf16_f32 v0, v0, s0
	global_store_short v[8:9], v0, off
	v_lshlrev_b32_e32 v128, 16, v195
	v_mov_b32_e32 v233, v1
	v_add_u32_e32 v230,32,v4
	v_add_u32_e32 v232,v172,v230
	v_lshlrev_b64 v[234:235],1,v[232:233]
	v_lshl_add_u64 v[236:237],s[18:19],0,v[234:235]
	global_load_ushort v195, v[236:237], off
	v_lshl_add_u64 v[8:9], s[18:19], 0, v[148:149]
	v_lshl_add_u64 v[2:3], s[62:63], 0, v[14:15]
	v_lshl_add_u64 v[14:15], s[18:19], 0, v[160:161]
	s_waitcnt vmcnt(32)
	v_lshlrev_b32_e32 v0, 16, v203
	v_mov_b32_e32 v233, v1
	v_add_u32_e32 v230,32,v4
	v_add_u32_e32 v232,v175,v230
	v_lshlrev_b64 v[234:235],1,v[232:233]
	v_lshl_add_u64 v[236:237],s[18:19],0,v[234:235]
	global_load_ushort v203, v[236:237], off
	v_fmac_f32_e32 v128, v130, v0
	v_cvt_pk_bf16_f32 v0, v128, s0
	global_store_short v[12:13], v0, off
	v_add_u32_e32 v0, v189, v4
	v_lshlrev_b64 v[128:129], 1, v[0:1]
	v_add_u32_e32 v0, v190, v4
	v_lshl_add_u64 v[2:3], s[62:63], 0, v[144:145]
	v_lshlrev_b64 v[144:145], 1, v[0:1]
	v_lshlrev_b32_e32 v0, 16, v199
	v_mov_b32_e32 v233, v1
	v_add_u32_e32 v230,32,v4
	v_add_u32_e32 v232,v183,v230
	v_lshlrev_b64 v[234:235],1,v[232:233]
	v_lshl_add_u64 v[236:237],s[18:19],0,v[234:235]
	global_load_ushort v199, v[236:237], off
	v_lshl_add_u64 v[12:13], s[18:19], 0, v[152:153]
	v_lshl_add_u64 v[168:169], s[18:19], 0, v[144:145]
	s_waitcnt vmcnt(32)
	v_lshlrev_b32_e32 v130, 16, v206
	v_mov_b32_e32 v233, v1
	v_add_u32_e32 v230,32,v4
	v_add_u32_e32 v232,v171,v230
	v_lshlrev_b64 v[234:235],1,v[232:233]
	v_lshl_add_u64 v[236:237],s[62:63],0,v[234:235]
	global_load_ushort v206, v[236:237], off
	v_fmac_f32_e32 v0, v131, v130
	v_cvt_pk_bf16_f32 v0, v0, s0
	global_store_short v[6:7], v0, off
	v_lshlrev_b32_e32 v130, 16, v196
	v_mov_b32_e32 v233, v1
	v_add_u32_e32 v230,32,v4
	v_add_u32_e32 v232,v174,v230
	v_lshlrev_b64 v[234:235],1,v[232:233]
	v_lshl_add_u64 v[236:237],s[18:19],0,v[234:235]
	global_load_ushort v196, v[236:237], off
	v_lshl_add_u64 v[2:3], s[62:63], 0, v[148:149]
	v_lshl_add_u64 v[6:7], s[18:19], 0, v[158:159]
	v_or_b32_e32 v178, 0x6c00, v5
	s_waitcnt vmcnt(32)
	v_lshlrev_b32_e32 v0, 16, v210
	v_mov_b32_e32 v233, v1
	v_add_u32_e32 v230,32,v4
	v_add_u32_e32 v232,v181,v230
	v_lshlrev_b64 v[234:235],1,v[232:233]
	v_lshl_add_u64 v[236:237],s[18:19],0,v[234:235]
	global_load_ushort v210, v[236:237], off
	v_fmac_f32_e32 v130, v132, v0
	v_cvt_pk_bf16_f32 v0, v130, s0
	global_store_short v[146:147], v0, off
	v_lshlrev_b32_e32 v132, 16, v204
	v_mov_b32_e32 v233, v1
	v_add_u32_e32 v230,32,v4
	v_add_u32_e32 v232,v172,v230
	v_lshlrev_b64 v[234:235],1,v[232:233]
	v_lshl_add_u64 v[236:237],s[62:63],0,v[234:235]
	global_load_ushort v204, v[236:237], off
	v_lshl_add_u64 v[2:3], s[62:63], 0, v[150:151]
	v_lshl_add_u64 v[130:131], s[18:19], 0, v[162:163]
	s_waitcnt vmcnt(33)
	v_lshlrev_b32_e32 v0, 16, v212
	v_mov_b32_e32 v233, v1
	v_add_u32_e32 v230,32,v4
	v_add_u32_e32 v232,v176,v230
	v_lshlrev_b64 v[234:235],1,v[232:233]
	v_lshl_add_u64 v[236:237],s[18:19],0,v[234:235]
	global_load_ushort v212, v[236:237], off
	v_fmac_f32_e32 v132, v133, v0
	v_cvt_pk_bf16_f32 v0, v132, s0
	global_store_short v[8:9], v0, off
	v_lshl_add_u64 v[8:9], s[18:19], 0, v[128:129]
	v_lshlrev_b32_e32 v132, 16, v201
	v_mov_b32_e32 v233, v1
	v_add_u32_e32 v230,32,v4
	v_add_u32_e32 v232,v190,v230
	v_lshlrev_b64 v[234:235],1,v[232:233]
	v_lshl_add_u64 v[236:237],s[18:19],0,v[234:235]
	global_load_ushort v201, v[236:237], off
	v_lshl_add_u64 v[2:3], s[62:63], 0, v[152:153]
	s_waitcnt vmcnt(34)
	v_lshlrev_b32_e32 v0, 16, v214
	v_mov_b32_e32 v233, v1
	v_add_u32_e32 v230,32,v4
	v_add_u32_e32 v232,v173,v230
	v_lshlrev_b64 v[234:235],1,v[232:233]
	v_lshl_add_u64 v[236:237],s[62:63],0,v[234:235]
	global_load_ushort v214, v[236:237], off
	v_fmac_f32_e32 v132, v134, v0
	v_cvt_pk_bf16_f32 v0, v132, s0
	global_store_short v[10:11], v0, off
	v_add_u32_e32 v0, v178, v4
	v_lshlrev_b64 v[132:133], 1, v[0:1]
	v_lshlrev_b32_e32 v0, 16, v207
	v_mov_b32_e32 v233, v1
	v_add_u32_e32 v230,32,v4
	v_add_u32_e32 v232,v180,v230
	v_lshlrev_b64 v[234:235],1,v[232:233]
	v_lshl_add_u64 v[236:237],s[18:19],0,v[234:235]
	global_load_ushort v207, v[236:237], off
	v_lshl_add_u64 v[10:11], s[62:63], 0, v[154:155]
	v_lshl_add_u64 v[2:3], s[18:19], 0, v[132:133]
	s_waitcnt vmcnt(35)
	v_lshlrev_b32_e32 v134, 16, v216
	v_mov_b32_e32 v233, v1
	v_add_u32_e32 v230,32,v4
	v_add_u32_e32 v232,v174,v230
	v_lshlrev_b64 v[234:235],1,v[232:233]
	v_lshl_add_u64 v[236:237],s[62:63],0,v[234:235]
	global_load_ushort v216, v[236:237], off
	v_fmac_f32_e32 v0, v135, v134
	v_cvt_pk_bf16_f32 v0, v0, s0
	global_store_short v[12:13], v0, off
	v_lshlrev_b32_e32 v12, 16, v197
	v_mov_b32_e32 v233, v1
	v_add_u32_e32 v230,32,v4
	v_add_u32_e32 v232,v182,v230
	v_lshlrev_b64 v[234:235],1,v[232:233]
	v_lshl_add_u64 v[236:237],s[18:19],0,v[234:235]
	global_load_ushort v197, v[236:237], off
	v_lshl_add_u64 v[10:11], s[62:63], 0, v[158:159]
	s_waitcnt vmcnt(36)
	v_lshlrev_b32_e32 v0, 16, v218
	v_mov_b32_e32 v233, v1
	v_add_u32_e32 v230,32,v4
	v_add_u32_e32 v232,v175,v230
	v_lshlrev_b64 v[234:235],1,v[232:233]
	v_lshl_add_u64 v[236:237],s[62:63],0,v[234:235]
	global_load_ushort v218, v[236:237], off
	v_fmac_f32_e32 v12, v136, v0
	v_cvt_pk_bf16_f32 v0, v12, s0
	global_store_short v[156:157], v0, off
	v_lshlrev_b32_e32 v12, 16, v211
	v_mov_b32_e32 v233, v1
	v_add_u32_e32 v230,32,v4
	v_add_u32_e32 v232,v189,v230
	v_lshlrev_b64 v[234:235],1,v[232:233]
	v_lshl_add_u64 v[236:237],s[18:19],0,v[234:235]
	global_load_ushort v211, v[236:237], off
	v_lshl_add_u64 v[10:11], s[62:63], 0, v[160:161]
	s_waitcnt vmcnt(38)
	v_lshlrev_b32_e32 v0, 16, v219
	v_mov_b32_e32 v233, v1
	v_add_u32_e32 v230,32,v4
	v_add_u32_e32 v232,v176,v230
	v_lshlrev_b64 v[234:235],1,v[232:233]
	v_lshl_add_u64 v[236:237],s[62:63],0,v[234:235]
	global_load_ushort v219, v[236:237], off
	v_fmac_f32_e32 v12, v137, v0
	v_cvt_pk_bf16_f32 v0, v12, s0
	global_store_short v[6:7], v0, off
	v_lshlrev_b32_e32 v10, 16, v205
	v_mov_b32_e32 v233, v1
	v_add_u32_e32 v230,32,v4
	v_add_u32_e32 v232,v177,v230
	v_lshlrev_b64 v[234:235],1,v[232:233]
	v_lshl_add_u64 v[236:237],s[62:63],0,v[234:235]
	global_load_ushort v205, v[236:237], off
	v_lshl_add_u64 v[6:7], s[62:63], 0, v[162:163]
	s_waitcnt vmcnt(40)
	v_lshlrev_b32_e32 v0, 16, v220
	v_mov_b32_e32 v233, v1
	v_add_u32_e32 v230,32,v4
	v_add_u32_e32 v232,v180,v230
	v_lshlrev_b64 v[234:235],1,v[232:233]
	v_lshl_add_u64 v[236:237],s[62:63],0,v[234:235]
	global_load_ushort v220, v[236:237], off
	v_fmac_f32_e32 v10, v138, v0
	v_cvt_pk_bf16_f32 v0, v10, s0
	global_store_short v[14:15], v0, off
	v_lshlrev_b32_e32 v10, 16, v213
	v_mov_b32_e32 v233, v1
	v_add_u32_e32 v230,32,v4
	v_add_u32_e32 v232,v181,v230
	v_lshlrev_b64 v[234:235],1,v[232:233]
	v_lshl_add_u64 v[236:237],s[62:63],0,v[234:235]
	global_load_ushort v213, v[236:237], off
	v_lshl_add_u64 v[6:7], s[62:63], 0, v[164:165]
	s_waitcnt vmcnt(42)
	v_lshlrev_b32_e32 v0, 16, v221
	v_mov_b32_e32 v233, v1
	v_add_u32_e32 v230,32,v4
	v_add_u32_e32 v232,v182,v230
	v_lshlrev_b64 v[234:235],1,v[232:233]
	v_lshl_add_u64 v[236:237],s[62:63],0,v[234:235]
	global_load_ushort v221, v[236:237], off
	v_fmac_f32_e32 v10, v139, v0
	v_cvt_pk_bf16_f32 v0, v10, s0
	global_store_short v[130:131], v0, off
	v_lshlrev_b32_e32 v10, 16, v202
	v_mov_b32_e32 v233, v1
	v_add_u32_e32 v230,32,v4
	v_add_u32_e32 v232,v183,v230
	v_lshlrev_b64 v[234:235],1,v[232:233]
	v_lshl_add_u64 v[236:237],s[62:63],0,v[234:235]
	global_load_ushort v202, v[236:237], off
	v_lshl_add_u64 v[6:7], s[62:63], 0, v[128:129]
	s_waitcnt vmcnt(44)
	v_lshlrev_b32_e32 v0, 16, v222
	v_mov_b32_e32 v233, v1
	v_add_u32_e32 v230,32,v4
	v_add_u32_e32 v232,v189,v230
	v_lshlrev_b64 v[234:235],1,v[232:233]
	v_lshl_add_u64 v[236:237],s[62:63],0,v[234:235]
	global_load_ushort v222, v[236:237], off
	v_fmac_f32_e32 v10, v140, v0
	v_cvt_pk_bf16_f32 v0, v10, s0
	global_store_short v[166:167], v0, off
	v_lshlrev_b32_e32 v10, 16, v215
	v_mov_b32_e32 v233, v1
	v_add_u32_e32 v230,32,v4
	v_add_u32_e32 v232,v190,v230
	v_lshlrev_b64 v[234:235],1,v[232:233]
	v_lshl_add_u64 v[236:237],s[62:63],0,v[234:235]
	global_load_ushort v215, v[236:237], off
	v_lshl_add_u64 v[6:7], s[62:63], 0, v[144:145]
	s_waitcnt vmcnt(46)
	v_lshlrev_b32_e32 v0, 16, v223
	v_mov_b32_e32 v233, v1
	v_add_u32_e32 v230,32,v4
	v_add_u32_e32 v232,v178,v230
	v_lshlrev_b64 v[234:235],1,v[232:233]
	v_lshl_add_u64 v[236:237],s[62:63],0,v[234:235]
	global_load_ushort v223, v[236:237], off
	v_fmac_f32_e32 v10, v141, v0
	v_cvt_pk_bf16_f32 v0, v10, s0
	global_store_short v[8:9], v0, off
	v_lshlrev_b32_e32 v8, 16, v209
	v_mov_b32_e32 v233, v1
	v_or_b32_e32 v231,0x8000,v5
	v_add_u32_e32 v232,v231,v4
	v_lshlrev_b64 v[234:235],1,v[232:233]
	v_lshl_add_u64 v[236:237],s[18:19],0,v[234:235]
	global_load_ushort v209, v[236:237], off
	v_lshl_add_u64 v[6:7], s[62:63], 0, v[132:133]
	s_waitcnt vmcnt(48)
	v_lshlrev_b32_e32 v0, 16, v224
	v_mov_b32_e32 v233, v1
	v_or_b32_e32 v231,0x8000,v5
	v_add_u32_e32 v232,v231,v4
	v_lshlrev_b64 v[234:235],1,v[232:233]
	v_lshl_add_u64 v[234:235],s[62:63],0,v[234:235]
	global_load_ushort v224, v[234:235], off
	v_fmac_f32_e32 v8, v142, v0
	v_cvt_pk_bf16_f32 v0, v8, s0
	global_store_short v[168:169], v0, off
	v_add_u32_e32 v6, 32, v4
	v_add_u32_e32 v0, v5, v6
	v_lshlrev_b64 v[8:9], 1, v[0:1]
	v_add_u32_e32 v0, v170, v6
	v_lshlrev_b64 v[12:13], 1, v[0:1]
	v_add_u32_e32 v0, v171, v6
	v_lshlrev_b64 v[14:15], 1, v[0:1]
	v_add_u32_e32 v0, v172, v6
	v_lshlrev_b64 v[128:129], 1, v[0:1]
	v_add_u32_e32 v0, v173, v6
	v_lshlrev_b64 v[130:131], 1, v[0:1]
	v_add_u32_e32 v0, v174, v6
	v_lshlrev_b64 v[132:133], 1, v[0:1]
	v_add_u32_e32 v0, v175, v6
	v_lshlrev_b64 v[134:135], 1, v[0:1]
	v_add_u32_e32 v0, v176, v6
	v_lshlrev_b64 v[136:137], 1, v[0:1]
	v_add_u32_e32 v0, v177, v6
	v_lshlrev_b64 v[138:139], 1, v[0:1]
	v_add_u32_e32 v0, v180, v6
	v_lshlrev_b64 v[140:141], 1, v[0:1]
	v_add_u32_e32 v0, v181, v6
	v_lshlrev_b64 v[144:145], 1, v[0:1]
	v_add_u32_e32 v0, v182, v6
	v_lshlrev_b64 v[146:147], 1, v[0:1]
	v_add_u32_e32 v0, v183, v6
	v_lshlrev_b64 v[148:149], 1, v[0:1]
	v_add_u32_e32 v0, v189, v6
	v_lshlrev_b64 v[150:151], 1, v[0:1]
	v_add_u32_e32 v0, v190, v6
	v_lshlrev_b64 v[152:153], 1, v[0:1]
	v_add_u32_e32 v0, v178, v6
	v_lshlrev_b64 v[154:155], 1, v[0:1]
	v_lshlrev_b32_e32 v0, 16, v217
	v_mov_b32_e32 v233, v1
	v_or_b32_e32 v230,0x8400,v5
	v_add_u32_e32 v232,v230,v4
	v_lshlrev_b64 v[234:235],1,v[232:233]
	v_lshl_add_u64 v[236:237],s[18:19],0,v[234:235]
	global_load_ushort v217, v[236:237], off
	v_lshl_add_u64 v[10:11], s[18:19], 0, v[8:9]
	v_lshl_add_u64 v[156:157], s[18:19], 0, v[154:155]
	v_lshl_add_u64 v[8:9], s[62:63], 0, v[8:9]
	v_lshl_add_u64 v[158:159], s[18:19], 0, v[138:139]
	v_lshl_add_u64 v[160:161], s[18:19], 0, v[148:149]
	s_waitcnt vmcnt(50)
	v_lshlrev_b32_e32 v7, 16, v225
	v_mov_b32_e32 v233, v1
	v_or_b32_e32 v231,0x8800,v5
	v_add_u32_e32 v232,v231,v4
	v_lshlrev_b64 v[234:235],1,v[232:233]
	v_lshl_add_u64 v[236:237],s[18:19],0,v[234:235]
	global_load_ushort v225, v[236:237], off
	v_fmac_f32_e32 v0, v143, v7
	v_cvt_pk_bf16_f32 v0, v0, s0
	global_store_short v[2:3], v0, off
	s_nop 0
	v_lshl_add_u64 v[2:3], s[18:19], 0, v[12:13]
	v_lshl_add_u64 v[8:9], s[62:63], 0, v[12:13]
	v_lshl_add_u64 v[12:13], s[18:19], 0, v[14:15]
	v_lshl_add_u64 v[142:143], s[18:19], 0, v[130:131]
	s_waitcnt vmcnt(50)
	v_lshlrev_b32_e32 v0, 16, v227
	v_mov_b32_e32 v233, v1
	v_or_b32_e32 v231,0xa000,v5
	v_add_u32_e32 v232,v231,v4
	v_lshlrev_b64 v[234:235],1,v[232:233]
	v_lshl_add_u64 v[236:237],s[18:19],0,v[234:235]
	global_load_ushort v227, v[236:237], off
	s_waitcnt vmcnt(50)
	v_lshlrev_b32_e32 v7, 16, v228
	v_mov_b32_e32 v233, v1
	v_or_b32_e32 v231,0xc000,v5
	v_add_u32_e32 v232,v231,v4
	v_lshlrev_b64 v[234:235],1,v[232:233]
	v_lshl_add_u64 v[236:237],s[18:19],0,v[234:235]
	global_load_ushort v228, v[236:237], off
	v_fmac_f32_e32 v0, v112, v7
	v_cvt_pk_bf16_f32 v0, v0, s0
	global_store_short v[10:11], v0, off
	s_waitcnt vmcnt(51)
	v_lshlrev_b32_e32 v7, 16, v229
	v_mov_b32_e32 v233, v1
	v_or_b32_e32 v230,0x8400,v5
	v_add_u32_e32 v232,v230,v4
	v_lshlrev_b64 v[234:235],1,v[232:233]
	v_lshl_add_u64 v[234:235],s[62:63],0,v[234:235]
	global_load_ushort v229, v[234:235], off
	v_lshl_add_u64 v[10:11], s[18:19], 0, v[128:129]
	v_lshl_add_u64 v[8:9], s[62:63], 0, v[14:15]
	v_lshl_add_u64 v[14:15], s[18:19], 0, v[134:135]
	s_waitcnt vmcnt(47)
	v_lshlrev_b32_e32 v0, 16, v198
	v_mov_b32_e32 v233, v1
	v_or_b32_e32 v230,0x8c00,v5
	v_add_u32_e32 v232,v230,v4
	v_lshlrev_b64 v[234:235],1,v[232:233]
	v_lshl_add_u64 v[236:237],s[18:19],0,v[234:235]
	global_load_ushort v198, v[236:237], off
	v_fmac_f32_e32 v7, v113, v0
	v_cvt_pk_bf16_f32 v0, v7, s0
	global_store_short v[2:3], v0, off
	v_lshlrev_b32_e32 v7, 16, v192
	v_mov_b32_e32 v233, v1
	v_or_b32_e32 v231,0xa800,v5
	v_add_u32_e32 v232,v231,v4
	v_lshlrev_b64 v[234:235],1,v[232:233]
	v_lshl_add_u64 v[236:237],s[18:19],0,v[234:235]
	global_load_ushort v192, v[236:237], off
	v_lshl_add_u64 v[8:9], s[18:19], 0, v[132:133]
	v_lshl_add_u64 v[2:3], s[62:63], 0, v[128:129]
	v_lshl_add_u64 v[112:113], s[18:19], 0, v[144:145]
	v_lshl_add_u64 v[128:129], s[18:19], 0, v[152:153]
	s_waitcnt vmcnt(44)
	v_lshlrev_b32_e32 v0, 16, v206
	v_mov_b32_e32 v233, v1
	v_or_b32_e32 v231,0xe000,v5
	v_add_u32_e32 v232,v231,v4
	v_lshlrev_b64 v[234:235],1,v[232:233]
	v_lshl_add_u64 v[236:237],s[18:19],0,v[234:235]
	global_load_ushort v206, v[236:237], off
	v_fmac_f32_e32 v7, v114, v0
	v_cvt_pk_bf16_f32 v0, v7, s0
	global_store_short v[12:13], v0, off
	v_lshlrev_b32_e32 v7, 16, v195
	v_mov_b32_e32 v233, v1
	v_or_b32_e32 v231,0x8800,v5
	v_add_u32_e32 v232,v231,v4
	v_lshlrev_b64 v[234:235],1,v[232:233]
	v_lshl_add_u64 v[236:237],s[62:63],0,v[234:235]
	global_load_ushort v195, v[236:237], off
	v_lshl_add_u64 v[12:13], s[18:19], 0, v[136:137]
	v_lshl_add_u64 v[2:3], s[62:63], 0, v[130:131]
	s_waitcnt vmcnt(42)
	v_lshlrev_b32_e32 v0, 16, v204
	v_mov_b32_e32 v233, v1
	v_or_b32_e32 v230,0xa400,v5
	v_add_u32_e32 v232,v230,v4
	v_lshlrev_b64 v[234:235],1,v[232:233]
	v_lshl_add_u64 v[236:237],s[18:19],0,v[234:235]
	global_load_ushort v204, v[236:237], off
	v_fmac_f32_e32 v7, v115, v0
	v_cvt_pk_bf16_f32 v0, v7, s0
	global_store_short v[10:11], v0, off
	v_lshlrev_b32_e32 v7, 16, v193
	v_mov_b32_e32 v233, v1
	v_or_b32_e32 v231,0xc800,v5
	v_add_u32_e32 v232,v231,v4
	v_lshlrev_b64 v[234:235],1,v[232:233]
	v_lshl_add_u64 v[236:237],s[18:19],0,v[234:235]
	global_load_ushort v193, v[236:237], off
	v_lshl_add_u64 v[2:3], s[62:63], 0, v[132:133]
	v_lshl_add_u64 v[10:11], s[18:19], 0, v[140:141]
	v_lshl_add_u64 v[114:115], s[18:19], 0, v[146:147]
	s_waitcnt vmcnt(41)
	v_lshlrev_b32_e32 v0, 16, v214
	v_mov_b32_e32 v233, v1
	v_or_b32_e32 v230,0x8c00,v5
	v_add_u32_e32 v232,v230,v4
	v_lshlrev_b64 v[234:235],1,v[232:233]
	v_lshl_add_u64 v[236:237],s[62:63],0,v[234:235]
	global_load_ushort v214, v[236:237], off
	v_fmac_f32_e32 v7, v116, v0
	v_cvt_pk_bf16_f32 v0, v7, s0
	global_store_short v[142:143], v0, off
	v_lshlrev_b32_e32 v7, 16, v196
	v_mov_b32_e32 v233, v1
	v_or_b32_e32 v230,0xac00,v5
	v_add_u32_e32 v232,v230,v4
	v_lshlrev_b64 v[234:235],1,v[232:233]
	v_lshl_add_u64 v[236:237],s[18:19],0,v[234:235]
	global_load_ushort v196, v[236:237], off
	v_lshl_add_u64 v[2:3], s[62:63], 0, v[134:135]
	s_waitcnt vmcnt(41)
	v_lshlrev_b32_e32 v0, 16, v216
	v_mov_b32_e32 v233, v1
	v_or_b32_e32 v230,0xe800,v5
	v_add_u32_e32 v232,v230,v4
	v_lshlrev_b64 v[234:235],1,v[232:233]
	v_lshl_add_u64 v[236:237],s[18:19],0,v[234:235]
	global_load_ushort v216, v[236:237], off
	v_fmac_f32_e32 v7, v117, v0
	v_cvt_pk_bf16_f32 v0, v7, s0
	global_store_short v[8:9], v0, off
	v_lshl_add_u64 v[8:9], s[18:19], 0, v[150:151]
	v_lshlrev_b32_e32 v7, 16, v203
	v_mov_b32_e32 v233, v1
	v_or_b32_e32 v231,0xa000,v5
	v_add_u32_e32 v232,v231,v4
	v_lshlrev_b64 v[234:235],1,v[232:233]
	v_lshl_add_u64 v[236:237],s[62:63],0,v[234:235]
	global_load_ushort v203, v[236:237], off
	v_lshl_add_u64 v[2:3], s[62:63], 0, v[136:137]
	s_waitcnt vmcnt(41)
	v_lshlrev_b32_e32 v0, 16, v218
	v_mov_b32_e32 v233, v1
	v_or_b32_e32 v230,0xc400,v5
	v_add_u32_e32 v232,v230,v4
	v_lshlrev_b64 v[234:235],1,v[232:233]
	v_lshl_add_u64 v[236:237],s[18:19],0,v[234:235]
	global_load_ushort v218, v[236:237], off
	v_fmac_f32_e32 v7, v118, v0
	v_cvt_pk_bf16_f32 v0, v7, s0
	global_store_short v[14:15], v0, off
	v_lshlrev_b32_e32 v7, 16, v212
	v_mov_b32_e32 v233, v1
	v_or_b32_e32 v230,0xa400,v5
	v_add_u32_e32 v232,v230,v4
	v_lshlrev_b64 v[234:235],1,v[232:233]
	v_lshl_add_u64 v[236:237],s[62:63],0,v[234:235]
	global_load_ushort v212, v[236:237], off
	v_lshl_add_u64 v[2:3], s[62:63], 0, v[138:139]
	s_waitcnt vmcnt(41)
	v_lshlrev_b32_e32 v0, 16, v219
	v_mov_b32_e32 v233, v1
	v_or_b32_e32 v230,0xcc00,v5
	v_add_u32_e32 v232,v230,v4
	v_lshlrev_b64 v[234:235],1,v[232:233]
	v_lshl_add_u64 v[236:237],s[18:19],0,v[234:235]
	global_load_ushort v219, v[236:237], off
	v_fmac_f32_e32 v7, v119, v0
	v_cvt_pk_bf16_f32 v0, v7, s0
	global_store_short v[12:13], v0, off
	v_lshlrev_b32_e32 v7, 16, v194
	v_mov_b32_e32 v233, v1
	v_or_b32_e32 v231,0xa800,v5
	v_add_u32_e32 v232,v231,v4
	v_lshlrev_b64 v[234:235],1,v[232:233]
	v_lshl_add_u64 v[236:237],s[62:63],0,v[234:235]
	global_load_ushort v194, v[236:237], off
	v_lshl_add_u64 v[2:3], s[62:63], 0, v[140:141]
	s_waitcnt vmcnt(42)
	v_lshlrev_b32_e32 v0, 16, v205
	v_mov_b32_e32 v233, v1
	v_or_b32_e32 v231,0xe400,v5
	v_add_u32_e32 v232,v231,v4
	v_lshlrev_b64 v[234:235],1,v[232:233]
	v_lshl_add_u64 v[236:237],s[18:19],0,v[234:235]
	global_load_ushort v205, v[236:237], off
	v_fmac_f32_e32 v7, v120, v0
	v_cvt_pk_bf16_f32 v0, v7, s0
	global_store_short v[158:159], v0, off
	v_lshlrev_b32_e32 v7, 16, v207
	v_mov_b32_e32 v233, v1
	v_or_b32_e32 v230,0xac00,v5
	v_add_u32_e32 v232,v230,v4
	v_lshlrev_b64 v[234:235],1,v[232:233]
	v_lshl_add_u64 v[236:237],s[62:63],0,v[234:235]
	global_load_ushort v207, v[236:237], off
	v_lshl_add_u64 v[2:3], s[62:63], 0, v[144:145]
	s_waitcnt vmcnt(44)
	v_lshlrev_b32_e32 v0, 16, v220
	v_mov_b32_e32 v233, v1
	v_or_b32_e32 v230,0xec00,v5
	v_add_u32_e32 v232,v230,v4
	v_lshlrev_b64 v[234:235],1,v[232:233]
	v_lshl_add_u64 v[236:237],s[18:19],0,v[234:235]
	global_load_ushort v220, v[236:237], off
	v_fmac_f32_e32 v7, v121, v0
	v_cvt_pk_bf16_f32 v0, v7, s0
	global_store_short v[10:11], v0, off
	v_lshlrev_b32_e32 v7, 16, v210
	v_mov_b32_e32 v233, v1
	v_or_b32_e32 v231,0xc000,v5
	v_add_u32_e32 v232,v231,v4
	v_lshlrev_b64 v[234:235],1,v[232:233]
	v_lshl_add_u64 v[236:237],s[62:63],0,v[234:235]
	global_load_ushort v210, v[236:237], off
	v_lshl_add_u64 v[2:3], s[62:63], 0, v[146:147]
	s_waitcnt vmcnt(45)
	v_lshlrev_b32_e32 v0, 16, v213
	v_mov_b32_e32 v233, v1
	v_or_b32_e32 v230,0xc400,v5
	v_add_u32_e32 v232,v230,v4
	v_lshlrev_b64 v[234:235],1,v[232:233]
	v_lshl_add_u64 v[236:237],s[62:63],0,v[234:235]
	global_load_ushort v213, v[236:237], off
	v_fmac_f32_e32 v7, v122, v0
	v_cvt_pk_bf16_f32 v0, v7, s0
	global_store_short v[112:113], v0, off
	v_lshlrev_b32_e32 v7, 16, v197
	v_mov_b32_e32 v233, v1
	v_or_b32_e32 v231,0xc800,v5
	v_add_u32_e32 v232,v231,v4
	v_lshlrev_b64 v[234:235],1,v[232:233]
	v_lshl_add_u64 v[236:237],s[62:63],0,v[234:235]
	global_load_ushort v197, v[236:237], off
	v_lshl_add_u64 v[2:3], s[62:63], 0, v[148:149]
	s_waitcnt vmcnt(47)
	v_lshlrev_b32_e32 v0, 16, v221
	v_mov_b32_e32 v233, v1
	v_or_b32_e32 v230,0xcc00,v5
	v_add_u32_e32 v232,v230,v4
	v_lshlrev_b64 v[234:235],1,v[232:233]
	v_lshl_add_u64 v[236:237],s[62:63],0,v[234:235]
	global_load_ushort v221, v[236:237], off
	v_fmac_f32_e32 v7, v123, v0
	v_cvt_pk_bf16_f32 v0, v7, s0
	global_store_short v[114:115], v0, off
	v_lshlrev_b32_e32 v7, 16, v199
	v_mov_b32_e32 v233, v1
	v_or_b32_e32 v231,0xe000,v5
	v_add_u32_e32 v232,v231,v4
	v_lshlrev_b64 v[234:235],1,v[232:233]
	v_lshl_add_u64 v[236:237],s[62:63],0,v[234:235]
	global_load_ushort v199, v[236:237], off
	v_lshl_add_u64 v[2:3], s[62:63], 0, v[150:151]
	s_waitcnt vmcnt(48)
	v_lshlrev_b32_e32 v0, 16, v202
	v_mov_b32_e32 v233, v1
	v_or_b32_e32 v231,0xe400,v5
	v_add_u32_e32 v232,v231,v4
	v_lshlrev_b64 v[234:235],1,v[232:233]
	v_lshl_add_u64 v[236:237],s[62:63],0,v[234:235]
	global_load_ushort v202, v[236:237], off
	v_fmac_f32_e32 v7, v124, v0
	v_cvt_pk_bf16_f32 v0, v7, s0
	global_store_short v[160:161], v0, off
	v_lshlrev_b32_e32 v7, 16, v211
	v_mov_b32_e32 v233, v1
	v_or_b32_e32 v230,0xe800,v5
	v_add_u32_e32 v232,v230,v4
	v_lshlrev_b64 v[234:235],1,v[232:233]
	v_lshl_add_u64 v[236:237],s[62:63],0,v[234:235]
	global_load_ushort v211, v[236:237], off
	v_lshl_add_u64 v[2:3], s[62:63], 0, v[152:153]
	s_waitcnt vmcnt(50)
	v_lshlrev_b32_e32 v0, 16, v222
	v_mov_b32_e32 v233, v1
	v_or_b32_e32 v230,0xec00,v5
	v_add_u32_e32 v232,v230,v4
	v_lshlrev_b64 v[234:235],1,v[232:233]
	v_lshl_add_u64 v[236:237],s[62:63],0,v[234:235]
	global_load_ushort v222, v[236:237], off
	v_fmac_f32_e32 v7, v125, v0
	v_cvt_pk_bf16_f32 v0, v7, s0
	global_store_short v[8:9], v0, off
	v_lshlrev_b32_e32 v2, 16, v201
	v_mov_b32_e32 v233, v1
	v_or_b32_e32 v230,0xec00,v5
	v_add_u32_e32 v232,v230,v6
	v_lshlrev_b64 v[230:231],1,v[232:233]
	v_lshl_add_u64 v[234:235],s[18:19],0,v[230:231]
	global_load_ushort v201, v[234:235], off
	s_waitcnt vmcnt(51)
	v_lshlrev_b32_e32 v0, 16, v215
	v_mov_b32_e32 v233, v1
	v_or_b32_e32 v231,0x8000,v5
	v_add_u32_e32 v232,v231,v6
	v_lshlrev_b64 v[234:235],1,v[232:233]
	v_lshl_add_u64 v[236:237],s[18:19],0,v[234:235]
	global_load_ushort v215, v[236:237], off
	v_fmac_f32_e32 v2, v126, v0
	v_cvt_pk_bf16_f32 v0, v2, s0
	global_store_short v[128:129], v0, off
	v_lshl_add_u64 v[2:3], s[62:63], 0, v[154:155]
	v_lshlrev_b32_e32 v2, 16, v226
	v_mov_b32_e32 v233, v1
	v_or_b32_e32 v231,0x8000,v5
	v_add_u32_e32 v232,v231,v6
	v_lshlrev_b64 v[234:235],1,v[232:233]
	v_lshl_add_u64 v[234:235],s[62:63],0,v[234:235]
	global_load_ushort v226, v[234:235], off
	s_waitcnt vmcnt(53)
	v_lshlrev_b32_e32 v0, 16, v223
	v_mov_b32_e32 v233, v1
	v_or_b32_e32 v230,0x8400,v5
	v_add_u32_e32 v232,v230,v6
	v_lshlrev_b64 v[234:235],1,v[232:233]
	v_lshl_add_u64 v[236:237],s[18:19],0,v[234:235]
	global_load_ushort v223, v[236:237], off
	v_fmac_f32_e32 v2, v127, v0
	v_cvt_pk_bf16_f32 v0, v2, s0
	global_store_short v[156:157], v0, off
	v_or_b32_e32 v7, 0x8000, v5
	v_add_u32_e32 v0, v7, v4
	v_lshlrev_b64 v[2:3], 1, v[0:1]
	v_lshl_add_u64 v[8:9], s[18:19], 0, v[2:3]
	v_lshl_add_u64 v[2:3], s[62:63], 0, v[2:3]
	v_or_b32_e32 v140, 0x8400, v5
	v_or_b32_e32 v141, 0x8800, v5
	v_add_u32_e32 v0, v140, v4
	v_or_b32_e32 v142, 0x8c00, v5
	v_lshlrev_b64 v[2:3], 1, v[0:1]
	v_add_u32_e32 v0, v141, v4
	v_or_b32_e32 v143, 0xa000, v5
	v_lshlrev_b64 v[12:13], 1, v[0:1]
	v_add_u32_e32 v0, v142, v4
	v_or_b32_e32 v144, 0xa400, v5
	v_lshlrev_b64 v[112:113], 1, v[0:1]
	v_add_u32_e32 v0, v143, v4
	v_or_b32_e32 v145, 0xa800, v5
	v_lshlrev_b64 v[114:115], 1, v[0:1]
	v_add_u32_e32 v0, v144, v4
	v_or_b32_e32 v146, 0xac00, v5
	v_lshlrev_b64 v[118:119], 1, v[0:1]
	v_add_u32_e32 v0, v145, v4
	v_or_b32_e32 v147, 0xc000, v5
	v_lshlrev_b64 v[120:121], 1, v[0:1]
	v_add_u32_e32 v0, v146, v4
	v_lshlrev_b64 v[122:123], 1, v[0:1]
	v_add_u32_e32 v0, v147, v4
	v_lshlrev_b64 v[124:125], 1, v[0:1]
	v_lshl_add_u64 v[10:11], s[18:19], 0, v[2:3]
	v_lshl_add_u64 v[2:3], s[62:63], 0, v[2:3]
	v_lshl_add_u64 v[14:15], s[18:19], 0, v[12:13]
	v_lshl_add_u64 v[116:117], s[18:19], 0, v[114:115]
	v_lshl_add_u64 v[126:127], s[18:19], 0, v[124:125]
	v_or_b32_e32 v150, 0xc400, v5
	v_or_b32_e32 v151, 0xc800, v5
	v_or_b32_e32 v152, 0xcc00, v5
	v_or_b32_e32 v153, 0xe000, v5
	v_or_b32_e32 v159, 0xe400, v5
	v_or_b32_e32 v160, 0xe800, v5
	s_waitcnt vmcnt(53)
	v_lshlrev_b32_e32 v0, 16, v209
	v_mov_b32_e32 v231, v1
	v_add_u32_e32 v230,v141,v6
	v_lshlrev_b64 v[232:233],1,v[230:231]
	v_lshl_add_u64 v[234:235],s[18:19],0,v[232:233]
	global_load_ushort v209, v[234:235], off
	s_waitcnt vmcnt(53)
	v_lshlrev_b32_e32 v128, 16, v224
	v_mov_b32_e32 v231, v1
	v_add_u32_e32 v230,v143,v6
	v_lshlrev_b64 v[232:233],1,v[230:231]
	v_lshl_add_u64 v[234:235],s[18:19],0,v[232:233]
	global_load_ushort v224, v[234:235], off
	v_fmac_f32_e32 v0, v96, v128
	v_cvt_pk_bf16_f32 v0, v0, s0
	global_store_short v[8:9], v0, off
	v_add_u32_e32 v0, v150, v4
	v_lshlrev_b64 v[128:129], 1, v[0:1]
	v_add_u32_e32 v0, v151, v4
	v_lshlrev_b64 v[130:131], 1, v[0:1]
	v_add_u32_e32 v0, v152, v4
	v_lshlrev_b64 v[132:133], 1, v[0:1]
	v_add_u32_e32 v0, v153, v4
	v_lshlrev_b64 v[134:135], 1, v[0:1]
	v_lshl_add_u64 v[8:9], s[18:19], 0, v[112:113]
	v_lshl_add_u64 v[2:3], s[62:63], 0, v[12:13]
	v_lshl_add_u64 v[12:13], s[18:19], 0, v[120:121]
	v_lshl_add_u64 v[136:137], s[18:19], 0, v[134:135]
	s_waitcnt vmcnt(53)
	v_lshlrev_b32_e32 v0, 16, v217
	v_mov_b32_e32 v231, v1
	v_add_u32_e32 v230,v147,v6
	v_lshlrev_b64 v[232:233],1,v[230:231]
	v_lshl_add_u64 v[234:235],s[18:19],0,v[232:233]
	global_load_ushort v217, v[234:235], off
	s_waitcnt vmcnt(48)
	v_lshlrev_b32_e32 v96, 16, v229
	v_mov_b32_e32 v231, v1
	v_add_u32_e32 v230,v140,v6
	v_lshlrev_b64 v[232:233],1,v[230:231]
	v_lshl_add_u64 v[234:235],s[62:63],0,v[232:233]
	global_load_ushort v229, v[234:235], off
	v_fmac_f32_e32 v0, v97, v96
	v_cvt_pk_bf16_f32 v0, v0, s0
	global_store_short v[10:11], v0, off
	v_lshl_add_u64 v[2:3], s[62:63], 0, v[112:113]
	v_lshlrev_b32_e32 v112, 16, v225
	v_mov_b32_e32 v231, v1
	v_add_u32_e32 v230,v142,v6
	v_lshlrev_b64 v[232:233],1,v[230:231]
	v_lshl_add_u64 v[234:235],s[18:19],0,v[232:233]
	global_load_ushort v225, v[234:235], off
	v_lshl_add_u64 v[10:11], s[18:19], 0, v[118:119]
	v_lshl_add_u64 v[96:97], s[18:19], 0, v[130:131]
	s_waitcnt vmcnt(45)
	v_lshlrev_b32_e32 v0, 16, v195
	v_mov_b32_e32 v231, v1
	v_add_u32_e32 v230,v145,v6
	v_lshlrev_b64 v[232:233],1,v[230:231]
	v_lshl_add_u64 v[234:235],s[18:19],0,v[232:233]
	global_load_ushort v195, v[234:235], off
	v_fmac_f32_e32 v112, v98, v0
	v_cvt_pk_bf16_f32 v0, v112, s0
	global_store_short v[14:15], v0, off
	v_add_u32_e32 v0, v159, v4
	v_lshlrev_b64 v[112:113], 1, v[0:1]
	v_add_u32_e32 v0, v160, v4
	v_lshl_add_u64 v[2:3], s[62:63], 0, v[114:115]
	v_lshlrev_b64 v[114:115], 1, v[0:1]
	v_lshlrev_b32_e32 v0, 16, v198
	v_mov_b32_e32 v231, v1
	v_add_u32_e32 v230,v153,v6
	v_lshlrev_b64 v[232:233],1,v[230:231]
	v_lshl_add_u64 v[234:235],s[18:19],0,v[232:233]
	global_load_ushort v198, v[234:235], off
	v_lshl_add_u64 v[14:15], s[18:19], 0, v[122:123]
	v_lshl_add_u64 v[138:139], s[18:19], 0, v[114:115]
	s_waitcnt vmcnt(44)
	v_lshlrev_b32_e32 v98, 16, v214
	v_mov_b32_e32 v231, v1
	v_add_u32_e32 v230,v141,v6
	v_lshlrev_b64 v[232:233],1,v[230:231]
	v_lshl_add_u64 v[234:235],s[62:63],0,v[232:233]
	global_load_ushort v214, v[234:235], off
	v_fmac_f32_e32 v0, v99, v98
	v_cvt_pk_bf16_f32 v0, v0, s0
	global_store_short v[8:9], v0, off
	v_lshlrev_b32_e32 v98, 16, v227
	v_mov_b32_e32 v231, v1
	v_add_u32_e32 v230,v144,v6
	v_lshlrev_b64 v[232:233],1,v[230:231]
	v_lshl_add_u64 v[234:235],s[18:19],0,v[232:233]
	global_load_ushort v227, v[234:235], off
	v_lshl_add_u64 v[2:3], s[62:63], 0, v[118:119]
	v_lshl_add_u64 v[8:9], s[18:19], 0, v[128:129]
	s_waitcnt vmcnt(42)
	v_lshlrev_b32_e32 v0, 16, v203
	v_mov_b32_e32 v231, v1
	v_add_u32_e32 v230,v151,v6
	v_lshlrev_b64 v[232:233],1,v[230:231]
	v_lshl_add_u64 v[234:235],s[18:19],0,v[232:233]
	global_load_ushort v203, v[234:235], off
	v_fmac_f32_e32 v98, v100, v0
	v_cvt_pk_bf16_f32 v0, v98, s0
	global_store_short v[116:117], v0, off
	v_lshlrev_b32_e32 v100, 16, v204
	v_mov_b32_e32 v231, v1
	v_add_u32_e32 v230,v142,v6
	v_lshlrev_b64 v[232:233],1,v[230:231]
	v_lshl_add_u64 v[234:235],s[62:63],0,v[232:233]
	global_load_ushort v204, v[234:235], off
	v_lshl_add_u64 v[2:3], s[62:63], 0, v[120:121]
	v_lshl_add_u64 v[98:99], s[18:19], 0, v[132:133]
	s_waitcnt vmcnt(42)
	v_lshlrev_b32_e32 v0, 16, v212
	v_mov_b32_e32 v231, v1
	v_add_u32_e32 v230,v146,v6
	v_lshlrev_b64 v[232:233],1,v[230:231]
	v_lshl_add_u64 v[234:235],s[18:19],0,v[232:233]
	global_load_ushort v212, v[234:235], off
	v_fmac_f32_e32 v100, v101, v0
	v_cvt_pk_bf16_f32 v0, v100, s0
	global_store_short v[10:11], v0, off
	v_lshl_add_u64 v[10:11], s[18:19], 0, v[112:113]
	v_lshlrev_b32_e32 v100, 16, v192
	v_mov_b32_e32 v231, v1
	v_add_u32_e32 v230,v160,v6
	v_lshlrev_b64 v[232:233],1,v[230:231]
	v_lshl_add_u64 v[234:235],s[18:19],0,v[232:233]
	global_load_ushort v192, v[234:235], off
	v_lshl_add_u64 v[2:3], s[62:63], 0, v[122:123]
	v_or_b32_e32 v122, 0xec00, v5
	s_waitcnt vmcnt(42)
	v_lshlrev_b32_e32 v0, 16, v194
	v_mov_b32_e32 v231, v1
	v_add_u32_e32 v230,v143,v6
	v_lshlrev_b64 v[232:233],1,v[230:231]
	v_lshl_add_u64 v[234:235],s[62:63],0,v[232:233]
	global_load_ushort v194, v[234:235], off
	v_fmac_f32_e32 v100, v102, v0
	v_cvt_pk_bf16_f32 v0, v100, s0
	global_store_short v[12:13], v0, off
	v_add_u32_e32 v0, v122, v4
	v_lshlrev_b64 v[100:101], 1, v[0:1]
	v_lshlrev_b32_e32 v0, 16, v196
	v_mov_b32_e32 v231, v1
	v_add_u32_e32 v230,v150,v6
	v_lshlrev_b64 v[232:233],1,v[230:231]
	v_lshl_add_u64 v[234:235],s[18:19],0,v[232:233]
	global_load_ushort v196, v[234:235], off
	v_lshl_add_u64 v[12:13], s[62:63], 0, v[124:125]
	v_lshl_add_u64 v[2:3], s[18:19], 0, v[100:101]
	s_waitcnt vmcnt(42)
	v_lshlrev_b32_e32 v102, 16, v207
	v_mov_b32_e32 v231, v1
	v_add_u32_e32 v230,v144,v6
	v_lshlrev_b64 v[232:233],1,v[230:231]
	v_lshl_add_u64 v[234:235],s[62:63],0,v[232:233]
	global_load_ushort v207, v[234:235], off
	v_fmac_f32_e32 v0, v103, v102
	v_cvt_pk_bf16_f32 v0, v0, s0
	global_store_short v[14:15], v0, off
	v_lshlrev_b32_e32 v14, 16, v228
	v_mov_b32_e32 v231, v1
	v_add_u32_e32 v230,v152,v6
	v_lshlrev_b64 v[232:233],1,v[230:231]
	v_lshl_add_u64 v[234:235],s[18:19],0,v[232:233]
	global_load_ushort v228, v[234:235], off
	v_lshl_add_u64 v[12:13], s[62:63], 0, v[128:129]
	s_waitcnt vmcnt(42)
	v_lshlrev_b32_e32 v0, 16, v210
	v_mov_b32_e32 v231, v1
	v_add_u32_e32 v230,v145,v6
	v_lshlrev_b64 v[232:233],1,v[230:231]
	v_lshl_add_u64 v[234:235],s[62:63],0,v[232:233]
	global_load_ushort v210, v[234:235], off
	v_fmac_f32_e32 v14, v104, v0
	v_cvt_pk_bf16_f32 v0, v14, s0
	global_store_short v[126:127], v0, off
	v_lshlrev_b32_e32 v14, 16, v218
	v_mov_b32_e32 v231, v1
	v_add_u32_e32 v230,v159,v6
	v_lshlrev_b64 v[232:233],1,v[230:231]
	v_lshl_add_u64 v[234:235],s[18:19],0,v[232:233]
	global_load_ushort v218, v[234:235], off
	v_lshl_add_u64 v[12:13], s[62:63], 0, v[130:131]
	s_waitcnt vmcnt(44)
	v_lshlrev_b32_e32 v0, 16, v213
	v_mov_b32_e32 v231, v1
	v_add_u32_e32 v230,v146,v6
	v_lshlrev_b64 v[232:233],1,v[230:231]
	v_lshl_add_u64 v[234:235],s[62:63],0,v[232:233]
	global_load_ushort v213, v[234:235], off
	v_fmac_f32_e32 v14, v105, v0
	v_cvt_pk_bf16_f32 v0, v14, s0
	global_store_short v[8:9], v0, off
	v_lshlrev_b32_e32 v12, 16, v193
	v_mov_b32_e32 v231, v1
	v_add_u32_e32 v230,v147,v6
	v_lshlrev_b64 v[232:233],1,v[230:231]
	v_lshl_add_u64 v[234:235],s[62:63],0,v[232:233]
	global_load_ushort v193, v[234:235], off
	v_lshl_add_u64 v[8:9], s[62:63], 0, v[132:133]
	s_waitcnt vmcnt(45)
	v_lshlrev_b32_e32 v0, 16, v197
	v_mov_b32_e32 v231, v1
	v_add_u32_e32 v230,v150,v6
	v_lshlrev_b64 v[232:233],1,v[230:231]
	v_lshl_add_u64 v[234:235],s[62:63],0,v[232:233]
	global_load_ushort v197, v[234:235], off
	v_fmac_f32_e32 v12, v106, v0
	v_cvt_pk_bf16_f32 v0, v12, s0
	global_store_short v[96:97], v0, off
	v_lshlrev_b32_e32 v12, 16, v219
	v_mov_b32_e32 v231, v1
	v_add_u32_e32 v230,v151,v6
	v_lshlrev_b64 v[232:233],1,v[230:231]
	v_lshl_add_u64 v[234:235],s[62:63],0,v[232:233]
	global_load_ushort v219, v[234:235], off
	v_lshl_add_u64 v[8:9], s[62:63], 0, v[134:135]
	s_waitcnt vmcnt(47)
	v_lshlrev_b32_e32 v0, 16, v221
	v_mov_b32_e32 v231, v1
	v_add_u32_e32 v230,v152,v6
	v_lshlrev_b64 v[232:233],1,v[230:231]
	v_lshl_add_u64 v[234:235],s[62:63],0,v[232:233]
	global_load_ushort v221, v[234:235], off
	v_fmac_f32_e32 v12, v107, v0
	v_cvt_pk_bf16_f32 v0, v12, s0
	global_store_short v[98:99], v0, off
	v_lshlrev_b32_e32 v12, 16, v206
	v_mov_b32_e32 v231, v1
	v_add_u32_e32 v230,v153,v6
	v_lshlrev_b64 v[232:233],1,v[230:231]
	v_lshl_add_u64 v[234:235],s[62:63],0,v[232:233]
	global_load_ushort v206, v[234:235], off
	v_lshl_add_u64 v[8:9], s[62:63], 0, v[112:113]
	s_waitcnt vmcnt(48)
	v_lshlrev_b32_e32 v0, 16, v199
	v_mov_b32_e32 v231, v1
	v_add_u32_e32 v230,v159,v6
	v_lshlrev_b64 v[232:233],1,v[230:231]
	v_lshl_add_u64 v[234:235],s[62:63],0,v[232:233]
	global_load_ushort v199, v[234:235], off
	v_fmac_f32_e32 v12, v108, v0
	v_cvt_pk_bf16_f32 v0, v12, s0
	global_store_short v[136:137], v0, off
	v_lshlrev_b32_e32 v12, 16, v205
	v_mov_b32_e32 v231, v1
	v_add_u32_e32 v230,v160,v6
	v_lshlrev_b64 v[232:233],1,v[230:231]
	v_lshl_add_u64 v[234:235],s[62:63],0,v[232:233]
	global_load_ushort v205, v[234:235], off
	v_lshl_add_u64 v[8:9], s[62:63], 0, v[114:115]
	s_waitcnt vmcnt(50)
	v_lshlrev_b32_e32 v0, 16, v202
	v_mov_b32_e32 v231, v1
	v_add_u32_e32 v230,v122,v6
	v_lshlrev_b64 v[232:233],1,v[230:231]
	v_lshl_add_u64 v[234:235],s[62:63],0,v[232:233]
	global_load_ushort v202, v[234:235], off
	v_fmac_f32_e32 v12, v109, v0
	v_cvt_pk_bf16_f32 v0, v12, s0
	global_store_short v[10:11], v0, off
	v_lshlrev_b32_e32 v10, 16, v216
	v_mov_b32_e32 v233, v1
	v_or_b32_e32 v231,0x10000,v5
	v_add_u32_e32 v232,v231,v4
	v_lshlrev_b64 v[234:235],1,v[232:233]
	v_lshl_add_u64 v[236:237],s[18:19],0,v[234:235]
	global_load_ushort v216, v[236:237], off
	v_lshl_add_u64 v[8:9], s[62:63], 0, v[100:101]
	s_waitcnt vmcnt(51)
	v_lshlrev_b32_e32 v0, 16, v211
	v_mov_b32_e32 v233, v1
	v_or_b32_e32 v231,0x10000,v5
	v_add_u32_e32 v232,v231,v4
	v_lshlrev_b64 v[234:235],1,v[232:233]
	v_lshl_add_u64 v[234:235],s[62:63],0,v[234:235]
	global_load_ushort v211, v[234:235], off
	v_fmac_f32_e32 v10, v110, v0
	v_cvt_pk_bf16_f32 v0, v10, s0
	global_store_short v[138:139], v0, off
	v_add_u32_e32 v0, v7, v6
	v_lshlrev_b64 v[8:9], 1, v[0:1]
	v_add_u32_e32 v0, v140, v6
	v_lshlrev_b64 v[12:13], 1, v[0:1]
	v_add_u32_e32 v0, v141, v6
	v_lshlrev_b64 v[14:15], 1, v[0:1]
	v_add_u32_e32 v0, v142, v6
	v_lshlrev_b64 v[96:97], 1, v[0:1]
	v_add_u32_e32 v0, v143, v6
	v_lshlrev_b64 v[98:99], 1, v[0:1]
	v_add_u32_e32 v0, v144, v6
	v_lshlrev_b64 v[100:101], 1, v[0:1]
	v_add_u32_e32 v0, v145, v6
	v_lshlrev_b64 v[102:103], 1, v[0:1]
	v_add_u32_e32 v0, v146, v6
	v_lshlrev_b64 v[104:105], 1, v[0:1]
	v_add_u32_e32 v0, v147, v6
	v_lshlrev_b64 v[106:107], 1, v[0:1]
	v_add_u32_e32 v0, v150, v6
	v_lshlrev_b64 v[108:109], 1, v[0:1]
	v_add_u32_e32 v0, v151, v6
	v_lshlrev_b64 v[112:113], 1, v[0:1]
	v_add_u32_e32 v0, v152, v6
	v_lshlrev_b64 v[114:115], 1, v[0:1]
	v_add_u32_e32 v0, v153, v6
	v_lshlrev_b64 v[116:117], 1, v[0:1]
	v_add_u32_e32 v0, v159, v6
	v_lshlrev_b64 v[118:119], 1, v[0:1]
	v_add_u32_e32 v0, v160, v6
	v_lshlrev_b64 v[120:121], 1, v[0:1]
	v_add_u32_e32 v0, v122, v6
	v_lshlrev_b64 v[122:123], 1, v[0:1]
	v_lshlrev_b32_e32 v0, 16, v220
	v_mov_b32_e32 v233, v1
	v_or_b32_e32 v230,0x10400,v5
	v_add_u32_e32 v232,v230,v4
	v_lshlrev_b64 v[234:235],1,v[232:233]
	v_lshl_add_u64 v[236:237],s[18:19],0,v[234:235]
	global_load_ushort v220, v[236:237], off
	v_lshl_add_u64 v[10:11], s[18:19], 0, v[8:9]
	v_lshl_add_u64 v[124:125], s[18:19], 0, v[122:123]
	v_lshl_add_u64 v[8:9], s[62:63], 0, v[8:9]
	v_lshl_add_u64 v[126:127], s[18:19], 0, v[106:107]
	s_waitcnt vmcnt(53)
	v_lshlrev_b32_e32 v110, 16, v222
	v_mov_b32_e32 v233, v1
	v_or_b32_e32 v231,0x10800,v5
	v_add_u32_e32 v232,v231,v4
	v_lshlrev_b64 v[234:235],1,v[232:233]
	v_lshl_add_u64 v[236:237],s[18:19],0,v[234:235]
	global_load_ushort v222, v[236:237], off
	v_fmac_f32_e32 v0, v111, v110
	v_cvt_pk_bf16_f32 v0, v0, s0
	global_store_short v[2:3], v0, off
	s_nop 0
	v_lshl_add_u64 v[2:3], s[18:19], 0, v[12:13]
	v_lshl_add_u64 v[8:9], s[62:63], 0, v[12:13]
	v_lshl_add_u64 v[12:13], s[18:19], 0, v[14:15]
	v_lshl_add_u64 v[110:111], s[18:19], 0, v[98:99]
	s_waitcnt vmcnt(52)
	v_lshlrev_b32_e32 v0, 16, v215
	v_mov_b32_e32 v233, v1
	v_or_b32_e32 v231,0x12000,v5
	v_add_u32_e32 v232,v231,v4
	v_lshlrev_b64 v[234:235],1,v[232:233]
	v_lshl_add_u64 v[236:237],s[18:19],0,v[234:235]
	global_load_ushort v215, v[236:237], off
	s_waitcnt vmcnt(51)
	v_lshlrev_b32_e32 v128, 16, v226
	v_mov_b32_e32 v233, v1
	v_or_b32_e32 v231,0x14000,v5
	v_add_u32_e32 v232,v231,v4
	v_lshlrev_b64 v[234:235],1,v[232:233]
	v_lshl_add_u64 v[236:237],s[18:19],0,v[234:235]
	global_load_ushort v226, v[236:237], off
	v_fmac_f32_e32 v0, v80, v128
	v_cvt_pk_bf16_f32 v0, v0, s0
	global_store_short v[10:11], v0, off
	s_waitcnt vmcnt(52)
	v_lshlrev_b32_e32 v80, 16, v223
	v_mov_b32_e32 v233, v1
	v_or_b32_e32 v230,0x10400,v5
	v_add_u32_e32 v232,v230,v4
	v_lshlrev_b64 v[234:235],1,v[232:233]
	v_lshl_add_u64 v[234:235],s[62:63],0,v[234:235]
	global_load_ushort v223, v[234:235], off
	v_lshl_add_u64 v[10:11], s[18:19], 0, v[96:97]
	v_lshl_add_u64 v[8:9], s[62:63], 0, v[14:15]
	v_lshl_add_u64 v[14:15], s[18:19], 0, v[102:103]
	v_lshl_add_u64 v[128:129], s[18:19], 0, v[116:117]
	s_waitcnt vmcnt(47)
	v_lshlrev_b32_e32 v0, 16, v229
	v_mov_b32_e32 v233, v1
	v_or_b32_e32 v230,0x10c00,v5
	v_add_u32_e32 v232,v230,v4
	v_lshlrev_b64 v[234:235],1,v[232:233]
	v_lshl_add_u64 v[236:237],s[18:19],0,v[234:235]
	global_load_ushort v229, v[236:237], off
	v_fmac_f32_e32 v80, v81, v0
	v_cvt_pk_bf16_f32 v0, v80, s0
	global_store_short v[2:3], v0, off
	v_lshl_add_u64 v[2:3], s[62:63], 0, v[96:97]
	v_lshlrev_b32_e32 v96, 16, v209
	v_mov_b32_e32 v233, v1
	v_or_b32_e32 v231,0x12800,v5
	v_add_u32_e32 v232,v231,v4
	v_lshlrev_b64 v[234:235],1,v[232:233]
	v_lshl_add_u64 v[236:237],s[18:19],0,v[234:235]
	global_load_ushort v209, v[236:237], off
	v_lshl_add_u64 v[8:9], s[18:19], 0, v[100:101]
	v_lshl_add_u64 v[80:81], s[18:19], 0, v[112:113]
	s_waitcnt vmcnt(44)
	v_lshlrev_b32_e32 v0, 16, v214
	v_mov_b32_e32 v233, v1
	v_or_b32_e32 v231,0x16000,v5
	v_add_u32_e32 v232,v231,v4
	v_lshlrev_b64 v[234:235],1,v[232:233]
	v_lshl_add_u64 v[236:237],s[18:19],0,v[234:235]
	global_load_ushort v214, v[236:237], off
	v_fmac_f32_e32 v96, v82, v0
	v_cvt_pk_bf16_f32 v0, v96, s0
	global_store_short v[12:13], v0, off
	v_lshlrev_b32_e32 v82, 16, v225
	v_mov_b32_e32 v233, v1
	v_or_b32_e32 v231,0x10800,v5
	v_add_u32_e32 v232,v231,v4
	v_lshlrev_b64 v[234:235],1,v[232:233]
	v_lshl_add_u64 v[236:237],s[62:63],0,v[234:235]
	global_load_ushort v225, v[236:237], off
	v_lshl_add_u64 v[12:13], s[18:19], 0, v[104:105]
	v_lshl_add_u64 v[2:3], s[62:63], 0, v[98:99]
	v_lshl_add_u64 v[96:97], s[18:19], 0, v[120:121]
	s_waitcnt vmcnt(42)
	v_lshlrev_b32_e32 v0, 16, v204
	v_mov_b32_e32 v233, v1
	v_or_b32_e32 v230,0x12400,v5
	v_add_u32_e32 v232,v230,v4
	v_lshlrev_b64 v[234:235],1,v[232:233]
	v_lshl_add_u64 v[236:237],s[18:19],0,v[234:235]
	global_load_ushort v204, v[236:237], off
	v_fmac_f32_e32 v82, v83, v0
	v_cvt_pk_bf16_f32 v0, v82, s0
	global_store_short v[10:11], v0, off
	v_lshlrev_b32_e32 v82, 16, v224
	v_mov_b32_e32 v233, v1
	v_or_b32_e32 v231,0x14800,v5
	v_add_u32_e32 v232,v231,v4
	v_lshlrev_b64 v[234:235],1,v[232:233]
	v_lshl_add_u64 v[236:237],s[18:19],0,v[234:235]
	global_load_ushort v224, v[236:237], off
	v_lshl_add_u64 v[2:3], s[62:63], 0, v[100:101]
	v_lshl_add_u64 v[10:11], s[18:19], 0, v[108:109]
	s_waitcnt vmcnt(41)
	v_lshlrev_b32_e32 v0, 16, v194
	v_mov_b32_e32 v233, v1
	v_or_b32_e32 v230,0x10c00,v5
	v_add_u32_e32 v232,v230,v4
	v_lshlrev_b64 v[234:235],1,v[232:233]
	v_lshl_add_u64 v[236:237],s[62:63],0,v[234:235]
	global_load_ushort v194, v[236:237], off
	v_fmac_f32_e32 v82, v84, v0
	v_cvt_pk_bf16_f32 v0, v82, s0
	global_store_short v[110:111], v0, off
	v_lshlrev_b32_e32 v84, 16, v227
	v_mov_b32_e32 v233, v1
	v_or_b32_e32 v230,0x12c00,v5
	v_add_u32_e32 v232,v230,v4
	v_lshlrev_b64 v[234:235],1,v[232:233]
	v_lshl_add_u64 v[236:237],s[18:19],0,v[234:235]
	global_load_ushort v227, v[236:237], off
	v_lshl_add_u64 v[2:3], s[62:63], 0, v[102:103]
	v_lshl_add_u64 v[82:83], s[18:19], 0, v[114:115]
	s_waitcnt vmcnt(41)
	v_lshlrev_b32_e32 v0, 16, v207
	v_mov_b32_e32 v233, v1
	v_or_b32_e32 v230,0x16800,v5
	v_add_u32_e32 v232,v230,v4
	v_lshlrev_b64 v[234:235],1,v[232:233]
	v_lshl_add_u64 v[236:237],s[18:19],0,v[234:235]
	global_load_ushort v207, v[236:237], off
	v_fmac_f32_e32 v84, v85, v0
	v_cvt_pk_bf16_f32 v0, v84, s0
	global_store_short v[8:9], v0, off
	v_lshl_add_u64 v[8:9], s[18:19], 0, v[118:119]
	v_lshlrev_b32_e32 v84, 16, v195
	v_mov_b32_e32 v233, v1
	v_or_b32_e32 v231,0x12000,v5
	v_add_u32_e32 v232,v231,v4
	v_lshlrev_b64 v[234:235],1,v[232:233]
	v_lshl_add_u64 v[236:237],s[62:63],0,v[234:235]
	global_load_ushort v195, v[236:237], off
	v_lshl_add_u64 v[2:3], s[62:63], 0, v[104:105]
	s_waitcnt vmcnt(41)
	v_lshlrev_b32_e32 v0, 16, v210
	v_mov_b32_e32 v233, v1
	v_or_b32_e32 v230,0x14400,v5
	v_add_u32_e32 v232,v230,v4
	v_lshlrev_b64 v[234:235],1,v[232:233]
	v_lshl_add_u64 v[236:237],s[18:19],0,v[234:235]
	global_load_ushort v210, v[236:237], off
	v_fmac_f32_e32 v84, v86, v0
	v_cvt_pk_bf16_f32 v0, v84, s0
	global_store_short v[14:15], v0, off
	v_lshlrev_b32_e32 v14, 16, v212
	v_mov_b32_e32 v233, v1
	v_or_b32_e32 v230,0x12400,v5
	v_add_u32_e32 v232,v230,v4
	v_lshlrev_b64 v[234:235],1,v[232:233]
	v_lshl_add_u64 v[236:237],s[62:63],0,v[234:235]
	global_load_ushort v212, v[236:237], off
	v_lshl_add_u64 v[2:3], s[62:63], 0, v[106:107]
	s_waitcnt vmcnt(41)
	v_lshlrev_b32_e32 v0, 16, v213
	v_mov_b32_e32 v233, v1
	v_or_b32_e32 v230,0x14c00,v5
	v_add_u32_e32 v232,v230,v4
	v_lshlrev_b64 v[234:235],1,v[232:233]
	v_lshl_add_u64 v[236:237],s[18:19],0,v[234:235]
	global_load_ushort v213, v[236:237], off
	v_fmac_f32_e32 v14, v87, v0
	v_cvt_pk_bf16_f32 v0, v14, s0
	global_store_short v[12:13], v0, off
	v_lshlrev_b32_e32 v12, 16, v217
	v_mov_b32_e32 v233, v1
	v_or_b32_e32 v231,0x12800,v5
	v_add_u32_e32 v232,v231,v4
	v_lshlrev_b64 v[234:235],1,v[232:233]
	v_lshl_add_u64 v[236:237],s[62:63],0,v[234:235]
	global_load_ushort v217, v[236:237], off
	v_lshl_add_u64 v[2:3], s[62:63], 0, v[108:109]
	s_waitcnt vmcnt(42)
	v_lshlrev_b32_e32 v0, 16, v193
	v_mov_b32_e32 v233, v1
	v_or_b32_e32 v231,0x16400,v5
	v_add_u32_e32 v232,v231,v4
	v_lshlrev_b64 v[234:235],1,v[232:233]
	v_lshl_add_u64 v[236:237],s[18:19],0,v[234:235]
	global_load_ushort v193, v[236:237], off
	v_fmac_f32_e32 v12, v88, v0
	v_cvt_pk_bf16_f32 v0, v12, s0
	global_store_short v[126:127], v0, off
	v_lshlrev_b32_e32 v12, 16, v196
	v_mov_b32_e32 v233, v1
	v_or_b32_e32 v230,0x12c00,v5
	v_add_u32_e32 v232,v230,v4
	v_lshlrev_b64 v[234:235],1,v[232:233]
	v_lshl_add_u64 v[236:237],s[62:63],0,v[234:235]
	global_load_ushort v196, v[236:237], off
	v_lshl_add_u64 v[2:3], s[62:63], 0, v[112:113]
	s_waitcnt vmcnt(44)
	v_lshlrev_b32_e32 v0, 16, v197
	v_mov_b32_e32 v233, v1
	v_or_b32_e32 v230,0x16c00,v5
	v_add_u32_e32 v232,v230,v4
	v_lshlrev_b64 v[234:235],1,v[232:233]
	v_lshl_add_u64 v[236:237],s[18:19],0,v[234:235]
	global_load_ushort v197, v[236:237], off
	v_fmac_f32_e32 v12, v89, v0
	v_cvt_pk_bf16_f32 v0, v12, s0
	global_store_short v[10:11], v0, off
	v_lshlrev_b32_e32 v10, 16, v203
	v_mov_b32_e32 v233, v1
	v_or_b32_e32 v231,0x14000,v5
	v_add_u32_e32 v232,v231,v4
	v_lshlrev_b64 v[234:235],1,v[232:233]
	v_lshl_add_u64 v[236:237],s[62:63],0,v[234:235]
	global_load_ushort v203, v[236:237], off
	v_lshl_add_u64 v[2:3], s[62:63], 0, v[114:115]
	s_waitcnt vmcnt(45)
	v_lshlrev_b32_e32 v0, 16, v219
	v_mov_b32_e32 v233, v1
	v_or_b32_e32 v230,0x14400,v5
	v_add_u32_e32 v232,v230,v4
	v_lshlrev_b64 v[234:235],1,v[232:233]
	v_lshl_add_u64 v[236:237],s[62:63],0,v[234:235]
	global_load_ushort v219, v[236:237], off
	v_fmac_f32_e32 v10, v90, v0
	v_cvt_pk_bf16_f32 v0, v10, s0
	global_store_short v[80:81], v0, off
	v_lshlrev_b32_e32 v10, 16, v228
	v_mov_b32_e32 v233, v1
	v_or_b32_e32 v231,0x14800,v5
	v_add_u32_e32 v232,v231,v4
	v_lshlrev_b64 v[234:235],1,v[232:233]
	v_lshl_add_u64 v[236:237],s[62:63],0,v[234:235]
	global_load_ushort v228, v[236:237], off
	v_lshl_add_u64 v[2:3], s[62:63], 0, v[116:117]
	s_waitcnt vmcnt(47)
	v_lshlrev_b32_e32 v0, 16, v221
	v_mov_b32_e32 v233, v1
	v_or_b32_e32 v230,0x14c00,v5
	v_add_u32_e32 v232,v230,v4
	v_lshlrev_b64 v[234:235],1,v[232:233]
	v_lshl_add_u64 v[236:237],s[62:63],0,v[234:235]
	global_load_ushort v221, v[236:237], off
	v_fmac_f32_e32 v10, v91, v0
	v_cvt_pk_bf16_f32 v0, v10, s0
	global_store_short v[82:83], v0, off
	v_lshlrev_b32_e32 v10, 16, v198
	v_mov_b32_e32 v233, v1
	v_or_b32_e32 v231,0x16000,v5
	v_add_u32_e32 v232,v231,v4
	v_lshlrev_b64 v[234:235],1,v[232:233]
	v_lshl_add_u64 v[236:237],s[62:63],0,v[234:235]
	global_load_ushort v198, v[236:237], off
	v_lshl_add_u64 v[2:3], s[62:63], 0, v[118:119]
	s_waitcnt vmcnt(48)
	v_lshlrev_b32_e32 v0, 16, v206
	v_mov_b32_e32 v233, v1
	v_or_b32_e32 v231,0x16400,v5
	v_add_u32_e32 v232,v231,v4
	v_lshlrev_b64 v[234:235],1,v[232:233]
	v_lshl_add_u64 v[236:237],s[62:63],0,v[234:235]
	global_load_ushort v206, v[236:237], off
	v_fmac_f32_e32 v10, v92, v0
	v_cvt_pk_bf16_f32 v0, v10, s0
	global_store_short v[128:129], v0, off
	v_lshlrev_b32_e32 v10, 16, v218
	v_mov_b32_e32 v233, v1
	v_or_b32_e32 v230,0x16800,v5
	v_add_u32_e32 v232,v230,v4
	v_lshlrev_b64 v[234:235],1,v[232:233]
	v_lshl_add_u64 v[236:237],s[62:63],0,v[234:235]
	global_load_ushort v218, v[236:237], off
	v_lshl_add_u64 v[2:3], s[62:63], 0, v[120:121]
	s_waitcnt vmcnt(50)
	v_lshlrev_b32_e32 v0, 16, v199
	v_mov_b32_e32 v233, v1
	v_or_b32_e32 v230,0x16c00,v5
	v_add_u32_e32 v232,v230,v4
	v_lshlrev_b64 v[234:235],1,v[232:233]
	v_lshl_add_u64 v[236:237],s[62:63],0,v[234:235]
	global_load_ushort v199, v[236:237], off
	v_fmac_f32_e32 v10, v93, v0
	v_cvt_pk_bf16_f32 v0, v10, s0
	global_store_short v[8:9], v0, off
	v_lshlrev_b32_e32 v2, 16, v192
	v_mov_b32_e32 v233, v1
	v_or_b32_e32 v230,0x16c00,v5
	v_add_u32_e32 v232,v230,v6
	v_lshlrev_b64 v[230:231],1,v[232:233]
	v_lshl_add_u64 v[234:235],s[18:19],0,v[230:231]
	global_load_ushort v192, v[234:235], off
	s_waitcnt vmcnt(51)
	v_lshlrev_b32_e32 v0, 16, v205
	v_mov_b32_e32 v233, v1
	v_or_b32_e32 v231,0x10000,v5
	v_add_u32_e32 v232,v231,v6
	v_lshlrev_b64 v[234:235],1,v[232:233]
	v_lshl_add_u64 v[236:237],s[18:19],0,v[234:235]
	global_load_ushort v205, v[236:237], off
	v_fmac_f32_e32 v2, v94, v0
	v_cvt_pk_bf16_f32 v0, v2, s0
	global_store_short v[96:97], v0, off
	v_lshl_add_u64 v[2:3], s[62:63], 0, v[122:123]
	v_lshlrev_b32_e32 v2, 16, v201
	v_mov_b32_e32 v233, v1
	v_or_b32_e32 v231,0x10000,v5
	v_add_u32_e32 v232,v231,v6
	v_lshlrev_b64 v[234:235],1,v[232:233]
	v_lshl_add_u64 v[234:235],s[62:63],0,v[234:235]
	global_load_ushort v201, v[234:235], off
	s_waitcnt vmcnt(53)
	v_lshlrev_b32_e32 v0, 16, v202
	v_mov_b32_e32 v233, v1
	v_or_b32_e32 v230,0x10400,v5
	v_add_u32_e32 v232,v230,v6
	v_lshlrev_b64 v[234:235],1,v[232:233]
	v_lshl_add_u64 v[236:237],s[18:19],0,v[234:235]
	global_load_ushort v202, v[236:237], off
	v_fmac_f32_e32 v2, v95, v0
	v_cvt_pk_bf16_f32 v0, v2, s0
	global_store_short v[124:125], v0, off
	v_or_b32_e32 v7, 0x10000, v5
	v_add_u32_e32 v0, v7, v4
	v_lshlrev_b64 v[2:3], 1, v[0:1]
	v_lshl_add_u64 v[8:9], s[18:19], 0, v[2:3]
	v_lshl_add_u64 v[2:3], s[62:63], 0, v[2:3]
	v_or_b32_e32 v108, 0x10400, v5
	v_or_b32_e32 v109, 0x10800, v5
	v_add_u32_e32 v0, v108, v4
	v_or_b32_e32 v110, 0x10c00, v5
	v_lshlrev_b64 v[2:3], 1, v[0:1]
	v_add_u32_e32 v0, v109, v4
	v_or_b32_e32 v111, 0x12000, v5
	v_lshlrev_b64 v[12:13], 1, v[0:1]
	v_add_u32_e32 v0, v110, v4
	v_or_b32_e32 v112, 0x12400, v5
	v_lshlrev_b64 v[80:81], 1, v[0:1]
	v_add_u32_e32 v0, v111, v4
	v_or_b32_e32 v113, 0x12800, v5
	v_lshlrev_b64 v[82:83], 1, v[0:1]
	v_add_u32_e32 v0, v112, v4
	v_or_b32_e32 v114, 0x12c00, v5
	v_lshlrev_b64 v[86:87], 1, v[0:1]
	v_add_u32_e32 v0, v113, v4
	v_or_b32_e32 v115, 0x14000, v5
	v_lshlrev_b64 v[88:89], 1, v[0:1]
	v_add_u32_e32 v0, v114, v4
	v_lshlrev_b64 v[90:91], 1, v[0:1]
	v_add_u32_e32 v0, v115, v4
	v_lshlrev_b64 v[92:93], 1, v[0:1]
	v_lshl_add_u64 v[10:11], s[18:19], 0, v[2:3]
	v_lshl_add_u64 v[2:3], s[62:63], 0, v[2:3]
	v_lshl_add_u64 v[14:15], s[18:19], 0, v[12:13]
	v_lshl_add_u64 v[84:85], s[18:19], 0, v[82:83]
	v_lshl_add_u64 v[94:95], s[18:19], 0, v[92:93]
	v_or_b32_e32 v118, 0x14400, v5
	v_or_b32_e32 v119, 0x14800, v5
	v_or_b32_e32 v120, 0x14c00, v5
	v_or_b32_e32 v121, 0x16000, v5
	v_or_b32_e32 v127, 0x16400, v5
	v_or_b32_e32 v128, 0x16800, v5
	s_waitcnt vmcnt(53)
	v_lshlrev_b32_e32 v0, 16, v216
	v_mov_b32_e32 v231, v1
	v_add_u32_e32 v230,v109,v6
	v_lshlrev_b64 v[232:233],1,v[230:231]
	v_lshl_add_u64 v[234:235],s[18:19],0,v[232:233]
	global_load_ushort v216, v[234:235], off
	s_waitcnt vmcnt(53)
	v_lshlrev_b32_e32 v96, 16, v211
	v_mov_b32_e32 v231, v1
	v_add_u32_e32 v230,v111,v6
	v_lshlrev_b64 v[232:233],1,v[230:231]
	v_lshl_add_u64 v[234:235],s[18:19],0,v[232:233]
	global_load_ushort v211, v[234:235], off
	v_fmac_f32_e32 v0, v64, v96
	v_cvt_pk_bf16_f32 v0, v0, s0
	global_store_short v[8:9], v0, off
	v_add_u32_e32 v0, v118, v4
	v_lshlrev_b64 v[96:97], 1, v[0:1]
	v_add_u32_e32 v0, v119, v4
	v_lshlrev_b64 v[98:99], 1, v[0:1]
	v_add_u32_e32 v0, v120, v4
	v_lshlrev_b64 v[100:101], 1, v[0:1]
	v_add_u32_e32 v0, v121, v4
	v_lshlrev_b64 v[102:103], 1, v[0:1]
	v_lshl_add_u64 v[8:9], s[18:19], 0, v[80:81]
	v_lshl_add_u64 v[2:3], s[62:63], 0, v[12:13]
	v_lshl_add_u64 v[12:13], s[18:19], 0, v[88:89]
	v_lshl_add_u64 v[104:105], s[18:19], 0, v[102:103]
	s_waitcnt vmcnt(53)
	v_lshlrev_b32_e32 v0, 16, v220
	v_mov_b32_e32 v231, v1
	v_add_u32_e32 v230,v115,v6
	v_lshlrev_b64 v[232:233],1,v[230:231]
	v_lshl_add_u64 v[234:235],s[18:19],0,v[232:233]
	global_load_ushort v220, v[234:235], off
	s_waitcnt vmcnt(48)
	v_lshlrev_b32_e32 v64, 16, v223
	v_mov_b32_e32 v231, v1
	v_add_u32_e32 v230,v108,v6
	v_lshlrev_b64 v[232:233],1,v[230:231]
	v_lshl_add_u64 v[234:235],s[62:63],0,v[232:233]
	global_load_ushort v223, v[234:235], off
	v_fmac_f32_e32 v0, v65, v64
	v_cvt_pk_bf16_f32 v0, v0, s0
	global_store_short v[10:11], v0, off
	v_lshl_add_u64 v[2:3], s[62:63], 0, v[80:81]
	v_lshlrev_b32_e32 v80, 16, v222
	v_mov_b32_e32 v231, v1
	v_add_u32_e32 v230,v110,v6
	v_lshlrev_b64 v[232:233],1,v[230:231]
	v_lshl_add_u64 v[234:235],s[18:19],0,v[232:233]
	global_load_ushort v222, v[234:235], off
	v_lshl_add_u64 v[10:11], s[18:19], 0, v[86:87]
	v_lshl_add_u64 v[64:65], s[18:19], 0, v[98:99]
	s_waitcnt vmcnt(45)
	v_lshlrev_b32_e32 v0, 16, v225
	v_mov_b32_e32 v231, v1
	v_add_u32_e32 v230,v113,v6
	v_lshlrev_b64 v[232:233],1,v[230:231]
	v_lshl_add_u64 v[234:235],s[18:19],0,v[232:233]
	global_load_ushort v225, v[234:235], off
	v_fmac_f32_e32 v80, v66, v0
	v_cvt_pk_bf16_f32 v0, v80, s0
	global_store_short v[14:15], v0, off
	v_add_u32_e32 v0, v127, v4
	v_lshlrev_b64 v[80:81], 1, v[0:1]
	v_add_u32_e32 v0, v128, v4
	v_lshl_add_u64 v[2:3], s[62:63], 0, v[82:83]
	v_lshlrev_b64 v[82:83], 1, v[0:1]
	v_lshlrev_b32_e32 v0, 16, v229
	v_mov_b32_e32 v231, v1
	v_add_u32_e32 v230,v121,v6
	v_lshlrev_b64 v[232:233],1,v[230:231]
	v_lshl_add_u64 v[234:235],s[18:19],0,v[232:233]
	global_load_ushort v229, v[234:235], off
	v_lshl_add_u64 v[14:15], s[18:19], 0, v[90:91]
	v_lshl_add_u64 v[106:107], s[18:19], 0, v[82:83]
	s_waitcnt vmcnt(44)
	v_lshlrev_b32_e32 v66, 16, v194
	v_mov_b32_e32 v231, v1
	v_add_u32_e32 v230,v109,v6
	v_lshlrev_b64 v[232:233],1,v[230:231]
	v_lshl_add_u64 v[234:235],s[62:63],0,v[232:233]
	global_load_ushort v194, v[234:235], off
	v_fmac_f32_e32 v0, v67, v66
	v_cvt_pk_bf16_f32 v0, v0, s0
	global_store_short v[8:9], v0, off
	v_lshlrev_b32_e32 v66, 16, v215
	v_mov_b32_e32 v231, v1
	v_add_u32_e32 v230,v112,v6
	v_lshlrev_b64 v[232:233],1,v[230:231]
	v_lshl_add_u64 v[234:235],s[18:19],0,v[232:233]
	global_load_ushort v215, v[234:235], off
	v_lshl_add_u64 v[2:3], s[62:63], 0, v[86:87]
	v_lshl_add_u64 v[8:9], s[18:19], 0, v[96:97]
	s_waitcnt vmcnt(42)
	v_lshlrev_b32_e32 v0, 16, v195
	v_mov_b32_e32 v231, v1
	v_add_u32_e32 v230,v119,v6
	v_lshlrev_b64 v[232:233],1,v[230:231]
	v_lshl_add_u64 v[234:235],s[18:19],0,v[232:233]
	global_load_ushort v195, v[234:235], off
	v_fmac_f32_e32 v66, v68, v0
	v_cvt_pk_bf16_f32 v0, v66, s0
	global_store_short v[84:85], v0, off
	v_lshlrev_b32_e32 v68, 16, v204
	v_mov_b32_e32 v231, v1
	v_add_u32_e32 v230,v110,v6
	v_lshlrev_b64 v[232:233],1,v[230:231]
	v_lshl_add_u64 v[234:235],s[62:63],0,v[232:233]
	global_load_ushort v204, v[234:235], off
	v_lshl_add_u64 v[2:3], s[62:63], 0, v[88:89]
	v_lshl_add_u64 v[66:67], s[18:19], 0, v[100:101]
	s_waitcnt vmcnt(42)
	v_lshlrev_b32_e32 v0, 16, v212
	v_mov_b32_e32 v231, v1
	v_add_u32_e32 v230,v114,v6
	v_lshlrev_b64 v[232:233],1,v[230:231]
	v_lshl_add_u64 v[234:235],s[18:19],0,v[232:233]
	global_load_ushort v212, v[234:235], off
	v_fmac_f32_e32 v68, v69, v0
	v_cvt_pk_bf16_f32 v0, v68, s0
	global_store_short v[10:11], v0, off
	v_lshl_add_u64 v[10:11], s[18:19], 0, v[80:81]
	v_lshlrev_b32_e32 v68, 16, v209
	v_mov_b32_e32 v231, v1
	v_add_u32_e32 v230,v128,v6
	v_lshlrev_b64 v[232:233],1,v[230:231]
	v_lshl_add_u64 v[234:235],s[18:19],0,v[232:233]
	global_load_ushort v209, v[234:235], off
	v_lshl_add_u64 v[2:3], s[62:63], 0, v[90:91]
	v_or_b32_e32 v90, 0x16c00, v5
	s_waitcnt vmcnt(42)
	v_lshlrev_b32_e32 v0, 16, v217
	v_mov_b32_e32 v231, v1
	v_add_u32_e32 v230,v111,v6
	v_lshlrev_b64 v[232:233],1,v[230:231]
	v_lshl_add_u64 v[234:235],s[62:63],0,v[232:233]
	global_load_ushort v217, v[234:235], off
	v_fmac_f32_e32 v68, v70, v0
	v_cvt_pk_bf16_f32 v0, v68, s0
	global_store_short v[12:13], v0, off
	v_add_u32_e32 v0, v90, v4
	v_lshlrev_b64 v[68:69], 1, v[0:1]
	v_lshlrev_b32_e32 v0, 16, v227
	v_mov_b32_e32 v231, v1
	v_add_u32_e32 v230,v118,v6
	v_lshlrev_b64 v[232:233],1,v[230:231]
	v_lshl_add_u64 v[234:235],s[18:19],0,v[232:233]
	global_load_ushort v227, v[234:235], off
	v_lshl_add_u64 v[12:13], s[62:63], 0, v[92:93]
	v_lshl_add_u64 v[2:3], s[18:19], 0, v[68:69]
	s_waitcnt vmcnt(42)
	v_lshlrev_b32_e32 v70, 16, v196
	v_mov_b32_e32 v231, v1
	v_add_u32_e32 v230,v112,v6
	v_lshlrev_b64 v[232:233],1,v[230:231]
	v_lshl_add_u64 v[234:235],s[62:63],0,v[232:233]
	global_load_ushort v196, v[234:235], off
	v_fmac_f32_e32 v0, v71, v70
	v_cvt_pk_bf16_f32 v0, v0, s0
	global_store_short v[14:15], v0, off
	v_lshlrev_b32_e32 v14, 16, v226
	v_mov_b32_e32 v231, v1
	v_add_u32_e32 v230,v120,v6
	v_lshlrev_b64 v[232:233],1,v[230:231]
	v_lshl_add_u64 v[234:235],s[18:19],0,v[232:233]
	global_load_ushort v226, v[234:235], off
	v_lshl_add_u64 v[12:13], s[62:63], 0, v[96:97]
	s_waitcnt vmcnt(42)
	v_lshlrev_b32_e32 v0, 16, v203
	v_mov_b32_e32 v231, v1
	v_add_u32_e32 v230,v113,v6
	v_lshlrev_b64 v[232:233],1,v[230:231]
	v_lshl_add_u64 v[234:235],s[62:63],0,v[232:233]
	global_load_ushort v203, v[234:235], off
	v_fmac_f32_e32 v14, v72, v0
	v_cvt_pk_bf16_f32 v0, v14, s0
	global_store_short v[94:95], v0, off
	v_lshlrev_b32_e32 v14, 16, v210
	v_mov_b32_e32 v231, v1
	v_add_u32_e32 v230,v127,v6
	v_lshlrev_b64 v[232:233],1,v[230:231]
	v_lshl_add_u64 v[234:235],s[18:19],0,v[232:233]
	global_load_ushort v210, v[234:235], off
	v_lshl_add_u64 v[12:13], s[62:63], 0, v[98:99]
	s_waitcnt vmcnt(44)
	v_lshlrev_b32_e32 v0, 16, v219
	v_mov_b32_e32 v231, v1
	v_add_u32_e32 v230,v114,v6
	v_lshlrev_b64 v[232:233],1,v[230:231]
	v_lshl_add_u64 v[234:235],s[62:63],0,v[232:233]
	global_load_ushort v219, v[234:235], off
	v_fmac_f32_e32 v14, v73, v0
	v_cvt_pk_bf16_f32 v0, v14, s0
	global_store_short v[8:9], v0, off
	v_lshlrev_b32_e32 v12, 16, v224
	v_mov_b32_e32 v231, v1
	v_add_u32_e32 v230,v115,v6
	v_lshlrev_b64 v[232:233],1,v[230:231]
	v_lshl_add_u64 v[234:235],s[62:63],0,v[232:233]
	global_load_ushort v224, v[234:235], off
	v_lshl_add_u64 v[8:9], s[62:63], 0, v[100:101]
	s_waitcnt vmcnt(45)
	v_lshlrev_b32_e32 v0, 16, v228
	v_mov_b32_e32 v231, v1
	v_add_u32_e32 v230,v118,v6
	v_lshlrev_b64 v[232:233],1,v[230:231]
	v_lshl_add_u64 v[234:235],s[62:63],0,v[232:233]
	global_load_ushort v228, v[234:235], off
	v_fmac_f32_e32 v12, v74, v0
	v_cvt_pk_bf16_f32 v0, v12, s0
	global_store_short v[64:65], v0, off
	v_lshlrev_b32_e32 v12, 16, v213
	v_mov_b32_e32 v231, v1
	v_add_u32_e32 v230,v119,v6
	v_lshlrev_b64 v[232:233],1,v[230:231]
	v_lshl_add_u64 v[234:235],s[62:63],0,v[232:233]
	global_load_ushort v213, v[234:235], off
	v_lshl_add_u64 v[8:9], s[62:63], 0, v[102:103]
	s_waitcnt vmcnt(47)
	v_lshlrev_b32_e32 v0, 16, v221
	v_mov_b32_e32 v231, v1
	v_add_u32_e32 v230,v120,v6
	v_lshlrev_b64 v[232:233],1,v[230:231]
	v_lshl_add_u64 v[234:235],s[62:63],0,v[232:233]
	global_load_ushort v221, v[234:235], off
	v_fmac_f32_e32 v12, v75, v0
	v_cvt_pk_bf16_f32 v0, v12, s0
	global_store_short v[66:67], v0, off
	v_lshlrev_b32_e32 v12, 16, v214
	v_mov_b32_e32 v231, v1
	v_add_u32_e32 v230,v121,v6
	v_lshlrev_b64 v[232:233],1,v[230:231]
	v_lshl_add_u64 v[234:235],s[62:63],0,v[232:233]
	global_load_ushort v214, v[234:235], off
	v_lshl_add_u64 v[8:9], s[62:63], 0, v[80:81]
	s_waitcnt vmcnt(48)
	v_lshlrev_b32_e32 v0, 16, v198
	v_mov_b32_e32 v231, v1
	v_add_u32_e32 v230,v127,v6
	v_lshlrev_b64 v[232:233],1,v[230:231]
	v_lshl_add_u64 v[234:235],s[62:63],0,v[232:233]
	global_load_ushort v198, v[234:235], off
	v_fmac_f32_e32 v12, v76, v0
	v_cvt_pk_bf16_f32 v0, v12, s0
	global_store_short v[104:105], v0, off
	v_lshlrev_b32_e32 v12, 16, v193
	v_mov_b32_e32 v231, v1
	v_add_u32_e32 v230,v128,v6
	v_lshlrev_b64 v[232:233],1,v[230:231]
	v_lshl_add_u64 v[234:235],s[62:63],0,v[232:233]
	global_load_ushort v193, v[234:235], off
	v_lshl_add_u64 v[8:9], s[62:63], 0, v[82:83]
	s_waitcnt vmcnt(50)
	v_lshlrev_b32_e32 v0, 16, v206
	v_mov_b32_e32 v231, v1
	v_add_u32_e32 v230,v90,v6
	v_lshlrev_b64 v[232:233],1,v[230:231]
	v_lshl_add_u64 v[234:235],s[62:63],0,v[232:233]
	global_load_ushort v206, v[234:235], off
	v_fmac_f32_e32 v12, v77, v0
	v_cvt_pk_bf16_f32 v0, v12, s0
	global_store_short v[10:11], v0, off
	v_lshlrev_b32_e32 v10, 16, v207
	v_mov_b32_e32 v233, v1
	v_or_b32_e32 v231,0x18000,v5
	v_add_u32_e32 v232,v231,v4
	v_lshlrev_b64 v[234:235],1,v[232:233]
	v_lshl_add_u64 v[236:237],s[18:19],0,v[234:235]
	global_load_ushort v207, v[236:237], off
	v_lshl_add_u64 v[8:9], s[62:63], 0, v[68:69]
	s_waitcnt vmcnt(51)
	v_lshlrev_b32_e32 v0, 16, v218
	v_mov_b32_e32 v233, v1
	v_or_b32_e32 v231,0x18000,v5
	v_add_u32_e32 v232,v231,v4
	v_lshlrev_b64 v[234:235],1,v[232:233]
	v_lshl_add_u64 v[234:235],s[62:63],0,v[234:235]
	global_load_ushort v218, v[234:235], off
	v_fmac_f32_e32 v10, v78, v0
	v_cvt_pk_bf16_f32 v0, v10, s0
	global_store_short v[106:107], v0, off
	v_add_u32_e32 v0, v7, v6
	v_lshlrev_b64 v[8:9], 1, v[0:1]
	v_add_u32_e32 v0, v108, v6
	v_lshlrev_b64 v[12:13], 1, v[0:1]
	v_add_u32_e32 v0, v109, v6
	v_lshlrev_b64 v[14:15], 1, v[0:1]
	v_add_u32_e32 v0, v110, v6
	v_lshlrev_b64 v[64:65], 1, v[0:1]
	v_add_u32_e32 v0, v111, v6
	v_lshlrev_b64 v[66:67], 1, v[0:1]
	v_add_u32_e32 v0, v112, v6
	v_lshlrev_b64 v[68:69], 1, v[0:1]
	v_add_u32_e32 v0, v113, v6
	v_lshlrev_b64 v[70:71], 1, v[0:1]
	v_add_u32_e32 v0, v114, v6
	v_lshlrev_b64 v[72:73], 1, v[0:1]
	v_add_u32_e32 v0, v115, v6
	v_lshlrev_b64 v[74:75], 1, v[0:1]
	v_add_u32_e32 v0, v118, v6
	v_lshlrev_b64 v[76:77], 1, v[0:1]
	v_add_u32_e32 v0, v119, v6
	v_lshlrev_b64 v[80:81], 1, v[0:1]
	v_add_u32_e32 v0, v120, v6
	v_lshlrev_b64 v[82:83], 1, v[0:1]
	v_add_u32_e32 v0, v121, v6
	v_lshlrev_b64 v[84:85], 1, v[0:1]
	v_add_u32_e32 v0, v127, v6
	v_lshlrev_b64 v[86:87], 1, v[0:1]
	v_add_u32_e32 v0, v128, v6
	v_lshlrev_b64 v[88:89], 1, v[0:1]
	v_add_u32_e32 v0, v90, v6
	v_lshlrev_b64 v[90:91], 1, v[0:1]
	v_lshlrev_b32_e32 v0, 16, v197
	v_mov_b32_e32 v233, v1
	v_or_b32_e32 v230,0x18400,v5
	v_add_u32_e32 v232,v230,v4
	v_lshlrev_b64 v[234:235],1,v[232:233]
	v_lshl_add_u64 v[236:237],s[18:19],0,v[234:235]
	global_load_ushort v197, v[236:237], off
	v_lshl_add_u64 v[10:11], s[18:19], 0, v[8:9]
	v_lshl_add_u64 v[92:93], s[18:19], 0, v[90:91]
	v_lshl_add_u64 v[8:9], s[62:63], 0, v[8:9]
	v_lshl_add_u64 v[94:95], s[18:19], 0, v[74:75]
	s_waitcnt vmcnt(53)
	v_lshlrev_b32_e32 v78, 16, v199
	v_mov_b32_e32 v233, v1
	v_or_b32_e32 v231,0x18800,v5
	v_add_u32_e32 v232,v231,v4
	v_lshlrev_b64 v[234:235],1,v[232:233]
	v_lshl_add_u64 v[236:237],s[18:19],0,v[234:235]
	global_load_ushort v199, v[236:237], off
	v_fmac_f32_e32 v0, v79, v78
	v_cvt_pk_bf16_f32 v0, v0, s0
	global_store_short v[2:3], v0, off
	s_nop 0
	v_lshl_add_u64 v[2:3], s[18:19], 0, v[12:13]
	v_lshl_add_u64 v[8:9], s[62:63], 0, v[12:13]
	v_lshl_add_u64 v[12:13], s[18:19], 0, v[14:15]
	v_lshl_add_u64 v[78:79], s[18:19], 0, v[66:67]
	s_waitcnt vmcnt(52)
	v_lshlrev_b32_e32 v0, 16, v205
	v_mov_b32_e32 v233, v1
	v_or_b32_e32 v231,0x1a000,v5
	v_add_u32_e32 v232,v231,v4
	v_lshlrev_b64 v[234:235],1,v[232:233]
	v_lshl_add_u64 v[236:237],s[18:19],0,v[234:235]
	global_load_ushort v205, v[236:237], off
	s_waitcnt vmcnt(51)
	v_lshlrev_b32_e32 v96, 16, v201
	v_mov_b32_e32 v233, v1
	v_or_b32_e32 v231,0x1c000,v5
	v_add_u32_e32 v232,v231,v4
	v_lshlrev_b64 v[234:235],1,v[232:233]
	v_lshl_add_u64 v[236:237],s[18:19],0,v[234:235]
	global_load_ushort v201, v[236:237], off
	v_fmac_f32_e32 v0, v48, v96
	v_cvt_pk_bf16_f32 v0, v0, s0
	global_store_short v[10:11], v0, off
	s_waitcnt vmcnt(52)
	v_lshlrev_b32_e32 v48, 16, v202
	v_mov_b32_e32 v233, v1
	v_or_b32_e32 v230,0x18400,v5
	v_add_u32_e32 v232,v230,v4
	v_lshlrev_b64 v[234:235],1,v[232:233]
	v_lshl_add_u64 v[234:235],s[62:63],0,v[234:235]
	global_load_ushort v202, v[234:235], off
	v_lshl_add_u64 v[10:11], s[18:19], 0, v[64:65]
	v_lshl_add_u64 v[8:9], s[62:63], 0, v[14:15]
	v_lshl_add_u64 v[14:15], s[18:19], 0, v[70:71]
	v_lshl_add_u64 v[96:97], s[18:19], 0, v[84:85]
	s_waitcnt vmcnt(47)
	v_lshlrev_b32_e32 v0, 16, v223
	v_mov_b32_e32 v233, v1
	v_or_b32_e32 v230,0x18c00,v5
	v_add_u32_e32 v232,v230,v4
	v_lshlrev_b64 v[234:235],1,v[232:233]
	v_lshl_add_u64 v[236:237],s[18:19],0,v[234:235]
	global_load_ushort v223, v[236:237], off
	v_fmac_f32_e32 v48, v49, v0
	v_cvt_pk_bf16_f32 v0, v48, s0
	global_store_short v[2:3], v0, off
	v_lshl_add_u64 v[2:3], s[62:63], 0, v[64:65]
	v_lshlrev_b32_e32 v64, 16, v216
	v_mov_b32_e32 v233, v1
	v_or_b32_e32 v231,0x1a800,v5
	v_add_u32_e32 v232,v231,v4
	v_lshlrev_b64 v[234:235],1,v[232:233]
	v_lshl_add_u64 v[236:237],s[18:19],0,v[234:235]
	global_load_ushort v216, v[236:237], off
	v_lshl_add_u64 v[8:9], s[18:19], 0, v[68:69]
	v_lshl_add_u64 v[48:49], s[18:19], 0, v[80:81]
	s_waitcnt vmcnt(44)
	v_lshlrev_b32_e32 v0, 16, v194
	v_mov_b32_e32 v233, v1
	v_or_b32_e32 v231,0x1e000,v5
	v_add_u32_e32 v232,v231,v4
	v_lshlrev_b64 v[234:235],1,v[232:233]
	v_lshl_add_u64 v[236:237],s[18:19],0,v[234:235]
	global_load_ushort v194, v[236:237], off
	v_fmac_f32_e32 v64, v50, v0
	v_cvt_pk_bf16_f32 v0, v64, s0
	global_store_short v[12:13], v0, off
	v_lshlrev_b32_e32 v50, 16, v222
	v_mov_b32_e32 v233, v1
	v_or_b32_e32 v231,0x18800,v5
	v_add_u32_e32 v232,v231,v4
	v_lshlrev_b64 v[234:235],1,v[232:233]
	v_lshl_add_u64 v[236:237],s[62:63],0,v[234:235]
	global_load_ushort v222, v[236:237], off
	v_lshl_add_u64 v[12:13], s[18:19], 0, v[72:73]
	v_lshl_add_u64 v[2:3], s[62:63], 0, v[66:67]
	v_lshl_add_u64 v[64:65], s[18:19], 0, v[88:89]
	s_waitcnt vmcnt(42)
	v_lshlrev_b32_e32 v0, 16, v204
	v_mov_b32_e32 v233, v1
	v_or_b32_e32 v230,0x1a400,v5
	v_add_u32_e32 v232,v230,v4
	v_lshlrev_b64 v[234:235],1,v[232:233]
	v_lshl_add_u64 v[236:237],s[18:19],0,v[234:235]
	global_load_ushort v204, v[236:237], off
	v_fmac_f32_e32 v50, v51, v0
	v_cvt_pk_bf16_f32 v0, v50, s0
	global_store_short v[10:11], v0, off
	v_lshlrev_b32_e32 v50, 16, v211
	v_mov_b32_e32 v233, v1
	v_or_b32_e32 v231,0x1c800,v5
	v_add_u32_e32 v232,v231,v4
	v_lshlrev_b64 v[234:235],1,v[232:233]
	v_lshl_add_u64 v[236:237],s[18:19],0,v[234:235]
	global_load_ushort v211, v[236:237], off
	v_lshl_add_u64 v[2:3], s[62:63], 0, v[68:69]
	v_lshl_add_u64 v[10:11], s[18:19], 0, v[76:77]
	s_waitcnt vmcnt(41)
	v_lshlrev_b32_e32 v0, 16, v217
	v_mov_b32_e32 v233, v1
	v_or_b32_e32 v230,0x18c00,v5
	v_add_u32_e32 v232,v230,v4
	v_lshlrev_b64 v[234:235],1,v[232:233]
	v_lshl_add_u64 v[236:237],s[62:63],0,v[234:235]
	global_load_ushort v217, v[236:237], off
	v_fmac_f32_e32 v50, v52, v0
	v_cvt_pk_bf16_f32 v0, v50, s0
	global_store_short v[78:79], v0, off
	v_lshlrev_b32_e32 v52, 16, v215
	v_mov_b32_e32 v233, v1
	v_or_b32_e32 v230,0x1ac00,v5
	v_add_u32_e32 v232,v230,v4
	v_lshlrev_b64 v[234:235],1,v[232:233]
	v_lshl_add_u64 v[236:237],s[18:19],0,v[234:235]
	global_load_ushort v215, v[236:237], off
	v_lshl_add_u64 v[2:3], s[62:63], 0, v[70:71]
	v_lshl_add_u64 v[50:51], s[18:19], 0, v[82:83]
	s_waitcnt vmcnt(41)
	v_lshlrev_b32_e32 v0, 16, v196
	v_mov_b32_e32 v233, v1
	v_or_b32_e32 v230,0x1e800,v5
	v_add_u32_e32 v232,v230,v4
	v_lshlrev_b64 v[234:235],1,v[232:233]
	v_lshl_add_u64 v[236:237],s[18:19],0,v[234:235]
	global_load_ushort v196, v[236:237], off
	v_fmac_f32_e32 v52, v53, v0
	v_cvt_pk_bf16_f32 v0, v52, s0
	global_store_short v[8:9], v0, off
	v_lshl_add_u64 v[8:9], s[18:19], 0, v[86:87]
	v_lshlrev_b32_e32 v52, 16, v225
	v_mov_b32_e32 v233, v1
	v_or_b32_e32 v231,0x1a000,v5
	v_add_u32_e32 v232,v231,v4
	v_lshlrev_b64 v[234:235],1,v[232:233]
	v_lshl_add_u64 v[236:237],s[62:63],0,v[234:235]
	global_load_ushort v225, v[236:237], off
	v_lshl_add_u64 v[2:3], s[62:63], 0, v[72:73]
	s_waitcnt vmcnt(41)
	v_lshlrev_b32_e32 v0, 16, v203
	v_mov_b32_e32 v233, v1
	v_or_b32_e32 v230,0x1c400,v5
	v_add_u32_e32 v232,v230,v4
	v_lshlrev_b64 v[234:235],1,v[232:233]
	v_lshl_add_u64 v[236:237],s[18:19],0,v[234:235]
	global_load_ushort v203, v[236:237], off
	v_fmac_f32_e32 v52, v54, v0
	v_cvt_pk_bf16_f32 v0, v52, s0
	global_store_short v[14:15], v0, off
	v_lshlrev_b32_e32 v14, 16, v212
	v_mov_b32_e32 v233, v1
	v_or_b32_e32 v230,0x1a400,v5
	v_add_u32_e32 v232,v230,v4
	v_lshlrev_b64 v[234:235],1,v[232:233]
	v_lshl_add_u64 v[236:237],s[62:63],0,v[234:235]
	global_load_ushort v212, v[236:237], off
	v_lshl_add_u64 v[2:3], s[62:63], 0, v[74:75]
	s_waitcnt vmcnt(41)
	v_lshlrev_b32_e32 v0, 16, v219
	v_mov_b32_e32 v233, v1
	v_or_b32_e32 v230,0x1cc00,v5
	v_add_u32_e32 v232,v230,v4
	v_lshlrev_b64 v[234:235],1,v[232:233]
	v_lshl_add_u64 v[236:237],s[18:19],0,v[234:235]
	global_load_ushort v219, v[236:237], off
	v_fmac_f32_e32 v14, v55, v0
	v_cvt_pk_bf16_f32 v0, v14, s0
	global_store_short v[12:13], v0, off
	v_lshlrev_b32_e32 v12, 16, v220
	v_mov_b32_e32 v233, v1
	v_or_b32_e32 v231,0x1a800,v5
	v_add_u32_e32 v232,v231,v4
	v_lshlrev_b64 v[234:235],1,v[232:233]
	v_lshl_add_u64 v[236:237],s[62:63],0,v[234:235]
	global_load_ushort v220, v[236:237], off
	v_lshl_add_u64 v[2:3], s[62:63], 0, v[76:77]
	s_waitcnt vmcnt(42)
	v_lshlrev_b32_e32 v0, 16, v224
	v_mov_b32_e32 v233, v1
	v_or_b32_e32 v231,0x1e400,v5
	v_add_u32_e32 v232,v231,v4
	v_lshlrev_b64 v[234:235],1,v[232:233]
	v_lshl_add_u64 v[236:237],s[18:19],0,v[234:235]
	global_load_ushort v224, v[236:237], off
	v_fmac_f32_e32 v12, v56, v0
	v_cvt_pk_bf16_f32 v0, v12, s0
	global_store_short v[94:95], v0, off
	v_lshlrev_b32_e32 v12, 16, v227
	v_mov_b32_e32 v233, v1
	v_or_b32_e32 v230,0x1ac00,v5
	v_add_u32_e32 v232,v230,v4
	v_lshlrev_b64 v[234:235],1,v[232:233]
	v_lshl_add_u64 v[236:237],s[62:63],0,v[234:235]
	global_load_ushort v227, v[236:237], off
	v_lshl_add_u64 v[2:3], s[62:63], 0, v[80:81]
	s_waitcnt vmcnt(44)
	v_lshlrev_b32_e32 v0, 16, v228
	v_mov_b32_e32 v233, v1
	v_or_b32_e32 v230,0x1ec00,v5
	v_add_u32_e32 v232,v230,v4
	v_lshlrev_b64 v[234:235],1,v[232:233]
	v_lshl_add_u64 v[236:237],s[18:19],0,v[234:235]
	global_load_ushort v228, v[236:237], off
	v_fmac_f32_e32 v12, v57, v0
	v_cvt_pk_bf16_f32 v0, v12, s0
	global_store_short v[10:11], v0, off
	v_lshlrev_b32_e32 v10, 16, v195
	v_mov_b32_e32 v233, v1
	v_or_b32_e32 v231,0x1c000,v5
	v_add_u32_e32 v232,v231,v4
	v_lshlrev_b64 v[234:235],1,v[232:233]
	v_lshl_add_u64 v[236:237],s[62:63],0,v[234:235]
	global_load_ushort v195, v[236:237], off
	v_lshl_add_u64 v[2:3], s[62:63], 0, v[82:83]
	s_waitcnt vmcnt(45)
	v_lshlrev_b32_e32 v0, 16, v213
	v_mov_b32_e32 v233, v1
	v_or_b32_e32 v230,0x1c400,v5
	v_add_u32_e32 v232,v230,v4
	v_lshlrev_b64 v[234:235],1,v[232:233]
	v_lshl_add_u64 v[236:237],s[62:63],0,v[234:235]
	global_load_ushort v213, v[236:237], off
	v_fmac_f32_e32 v10, v58, v0
	v_cvt_pk_bf16_f32 v0, v10, s0
	global_store_short v[48:49], v0, off
	v_lshlrev_b32_e32 v10, 16, v226
	v_mov_b32_e32 v233, v1
	v_or_b32_e32 v231,0x1c800,v5
	v_add_u32_e32 v232,v231,v4
	v_lshlrev_b64 v[234:235],1,v[232:233]
	v_lshl_add_u64 v[236:237],s[62:63],0,v[234:235]
	global_load_ushort v226, v[236:237], off
	v_lshl_add_u64 v[2:3], s[62:63], 0, v[84:85]
	s_waitcnt vmcnt(47)
	v_lshlrev_b32_e32 v0, 16, v221
	v_mov_b32_e32 v233, v1
	v_or_b32_e32 v230,0x1cc00,v5
	v_add_u32_e32 v232,v230,v4
	v_lshlrev_b64 v[234:235],1,v[232:233]
	v_lshl_add_u64 v[236:237],s[62:63],0,v[234:235]
	global_load_ushort v221, v[236:237], off
	v_fmac_f32_e32 v10, v59, v0
	v_cvt_pk_bf16_f32 v0, v10, s0
	global_store_short v[50:51], v0, off
	v_lshlrev_b32_e32 v10, 16, v229
	v_mov_b32_e32 v233, v1
	v_or_b32_e32 v231,0x1e000,v5
	v_add_u32_e32 v232,v231,v4
	v_lshlrev_b64 v[234:235],1,v[232:233]
	v_lshl_add_u64 v[236:237],s[62:63],0,v[234:235]
	global_load_ushort v229, v[236:237], off
	v_lshl_add_u64 v[2:3], s[62:63], 0, v[86:87]
	s_waitcnt vmcnt(48)
	v_lshlrev_b32_e32 v0, 16, v214
	v_mov_b32_e32 v233, v1
	v_or_b32_e32 v231,0x1e400,v5
	v_add_u32_e32 v232,v231,v4
	v_lshlrev_b64 v[234:235],1,v[232:233]
	v_lshl_add_u64 v[236:237],s[62:63],0,v[234:235]
	global_load_ushort v214, v[236:237], off
	v_fmac_f32_e32 v10, v60, v0
	v_cvt_pk_bf16_f32 v0, v10, s0
	global_store_short v[96:97], v0, off
	v_lshlrev_b32_e32 v10, 16, v210
	v_mov_b32_e32 v233, v1
	v_or_b32_e32 v230,0x1e800,v5
	v_add_u32_e32 v232,v230,v4
	v_lshlrev_b64 v[234:235],1,v[232:233]
	v_lshl_add_u64 v[236:237],s[62:63],0,v[234:235]
	global_load_ushort v210, v[236:237], off
	v_lshl_add_u64 v[2:3], s[62:63], 0, v[88:89]
	s_waitcnt vmcnt(50)
	v_lshlrev_b32_e32 v0, 16, v198
	v_mov_b32_e32 v233, v1
	v_or_b32_e32 v230,0x1ec00,v5
	v_add_u32_e32 v232,v230,v4
	v_lshlrev_b64 v[234:235],1,v[232:233]
	v_lshl_add_u64 v[234:235],s[62:63],0,v[234:235]
	global_load_ushort v198, v[234:235], off
	v_fmac_f32_e32 v10, v61, v0
	v_cvt_pk_bf16_f32 v0, v10, s0
	global_store_short v[8:9], v0, off
	v_lshlrev_b32_e32 v2, 16, v209
	v_mov_b32_e32 v233, v1
	v_or_b32_e32 v230,0x1ec00,v5
	v_add_u32_e32 v232,v230,v6
	v_lshlrev_b64 v[234:235],1,v[232:233]
	v_lshl_add_u64 v[230:231],s[18:19],0,v[234:235]
	global_load_ushort v209, v[230:231], off
	s_waitcnt vmcnt(51)
	v_lshlrev_b32_e32 v0, 16, v193
	v_mov_b32_e32 v233, v1
	v_or_b32_e32 v231,0x18000,v5
	v_add_u32_e32 v232,v231,v6
	v_lshlrev_b64 v[234:235],1,v[232:233]
	v_lshl_add_u64 v[236:237],s[18:19],0,v[234:235]
	global_load_ushort v193, v[236:237], off
	v_fmac_f32_e32 v2, v62, v0
	v_cvt_pk_bf16_f32 v0, v2, s0
	global_store_short v[64:65], v0, off
	v_lshl_add_u64 v[2:3], s[62:63], 0, v[90:91]
	v_lshlrev_b32_e32 v2, 16, v192
	v_mov_b32_e32 v233, v1
	v_or_b32_e32 v231,0x18000,v5
	v_add_u32_e32 v232,v231,v6
	v_lshlrev_b64 v[234:235],1,v[232:233]
	v_lshl_add_u64 v[234:235],s[62:63],0,v[234:235]
	global_load_ushort v192, v[234:235], off
	s_waitcnt vmcnt(53)
	v_lshlrev_b32_e32 v0, 16, v206
	v_mov_b32_e32 v233, v1
	v_or_b32_e32 v230,0x18400,v5
	v_add_u32_e32 v232,v230,v6
	v_lshlrev_b64 v[234:235],1,v[232:233]
	v_lshl_add_u64 v[236:237],s[18:19],0,v[234:235]
	global_load_ushort v206, v[236:237], off
	v_fmac_f32_e32 v2, v63, v0
	v_cvt_pk_bf16_f32 v0, v2, s0
	global_store_short v[92:93], v0, off
	v_or_b32_e32 v7, 0x18000, v5
	v_add_u32_e32 v0, v7, v4
	v_lshlrev_b64 v[2:3], 1, v[0:1]
	v_lshl_add_u64 v[8:9], s[18:19], 0, v[2:3]
	v_lshl_add_u64 v[2:3], s[62:63], 0, v[2:3]
	v_or_b32_e32 v76, 0x18400, v5
	v_or_b32_e32 v77, 0x18800, v5
	v_add_u32_e32 v0, v76, v4
	v_or_b32_e32 v78, 0x18c00, v5
	v_lshlrev_b64 v[2:3], 1, v[0:1]
	v_add_u32_e32 v0, v77, v4
	v_or_b32_e32 v79, 0x1a000, v5
	v_lshlrev_b64 v[12:13], 1, v[0:1]
	v_add_u32_e32 v0, v78, v4
	v_or_b32_e32 v80, 0x1a400, v5
	v_lshlrev_b64 v[48:49], 1, v[0:1]
	v_add_u32_e32 v0, v79, v4
	v_or_b32_e32 v81, 0x1a800, v5
	v_lshlrev_b64 v[50:51], 1, v[0:1]
	v_add_u32_e32 v0, v80, v4
	v_or_b32_e32 v82, 0x1ac00, v5
	v_lshlrev_b64 v[54:55], 1, v[0:1]
	v_add_u32_e32 v0, v81, v4
	v_or_b32_e32 v83, 0x1c000, v5
	v_lshlrev_b64 v[56:57], 1, v[0:1]
	v_add_u32_e32 v0, v82, v4
	v_lshlrev_b64 v[58:59], 1, v[0:1]
	v_add_u32_e32 v0, v83, v4
	v_lshlrev_b64 v[60:61], 1, v[0:1]
	v_lshl_add_u64 v[10:11], s[18:19], 0, v[2:3]
	v_lshl_add_u64 v[2:3], s[62:63], 0, v[2:3]
	v_lshl_add_u64 v[14:15], s[18:19], 0, v[12:13]
	v_lshl_add_u64 v[52:53], s[18:19], 0, v[50:51]
	v_lshl_add_u64 v[62:63], s[18:19], 0, v[60:61]
	v_or_b32_e32 v86, 0x1c400, v5
	v_or_b32_e32 v87, 0x1c800, v5
	v_or_b32_e32 v88, 0x1cc00, v5
	v_or_b32_e32 v89, 0x1e000, v5
	v_or_b32_e32 v95, 0x1e400, v5
	v_or_b32_e32 v96, 0x1e800, v5
	s_waitcnt vmcnt(53)
	v_lshlrev_b32_e32 v0, 16, v207
	v_mov_b32_e32 v231, v1
	v_add_u32_e32 v230,v77,v6
	v_lshlrev_b64 v[232:233],1,v[230:231]
	v_lshl_add_u64 v[234:235],s[18:19],0,v[232:233]
	global_load_ushort v207, v[234:235], off
	s_waitcnt vmcnt(53)
	v_lshlrev_b32_e32 v64, 16, v218
	v_mov_b32_e32 v231, v1
	v_add_u32_e32 v230,v79,v6
	v_lshlrev_b64 v[232:233],1,v[230:231]
	v_lshl_add_u64 v[234:235],s[18:19],0,v[232:233]
	global_load_ushort v218, v[234:235], off
	v_fmac_f32_e32 v0, v32, v64
	v_cvt_pk_bf16_f32 v0, v0, s0
	global_store_short v[8:9], v0, off
	v_add_u32_e32 v0, v86, v4
	v_lshlrev_b64 v[64:65], 1, v[0:1]
	v_add_u32_e32 v0, v87, v4
	v_lshlrev_b64 v[66:67], 1, v[0:1]
	v_add_u32_e32 v0, v88, v4
	v_lshlrev_b64 v[68:69], 1, v[0:1]
	v_add_u32_e32 v0, v89, v4
	v_lshlrev_b64 v[70:71], 1, v[0:1]
	v_lshl_add_u64 v[8:9], s[18:19], 0, v[48:49]
	v_lshl_add_u64 v[2:3], s[62:63], 0, v[12:13]
	v_lshl_add_u64 v[12:13], s[18:19], 0, v[56:57]
	v_lshl_add_u64 v[72:73], s[18:19], 0, v[70:71]
	s_waitcnt vmcnt(53)
	v_lshlrev_b32_e32 v0, 16, v197
	v_mov_b32_e32 v231, v1
	v_add_u32_e32 v230,v83,v6
	v_lshlrev_b64 v[232:233],1,v[230:231]
	v_lshl_add_u64 v[234:235],s[18:19],0,v[232:233]
	global_load_ushort v197, v[234:235], off
	s_waitcnt vmcnt(48)
	v_lshlrev_b32_e32 v32, 16, v202
	v_mov_b32_e32 v231, v1
	v_add_u32_e32 v230,v76,v6
	v_lshlrev_b64 v[232:233],1,v[230:231]
	v_lshl_add_u64 v[234:235],s[62:63],0,v[232:233]
	global_load_ushort v202, v[234:235], off
	v_fmac_f32_e32 v0, v33, v32
	v_cvt_pk_bf16_f32 v0, v0, s0
	global_store_short v[10:11], v0, off
	v_lshl_add_u64 v[2:3], s[62:63], 0, v[48:49]
	v_lshlrev_b32_e32 v48, 16, v199
	v_mov_b32_e32 v231, v1
	v_add_u32_e32 v230,v78,v6
	v_lshlrev_b64 v[232:233],1,v[230:231]
	v_lshl_add_u64 v[234:235],s[18:19],0,v[232:233]
	global_load_ushort v199, v[234:235], off
	v_lshl_add_u64 v[10:11], s[18:19], 0, v[54:55]
	v_lshl_add_u64 v[32:33], s[18:19], 0, v[66:67]
	s_waitcnt vmcnt(45)
	v_lshlrev_b32_e32 v0, 16, v222
	v_mov_b32_e32 v231, v1
	v_add_u32_e32 v230,v81,v6
	v_lshlrev_b64 v[232:233],1,v[230:231]
	v_lshl_add_u64 v[234:235],s[18:19],0,v[232:233]
	global_load_ushort v222, v[234:235], off
	v_fmac_f32_e32 v48, v34, v0
	v_cvt_pk_bf16_f32 v0, v48, s0
	global_store_short v[14:15], v0, off
	v_add_u32_e32 v0, v95, v4
	v_lshlrev_b64 v[48:49], 1, v[0:1]
	v_add_u32_e32 v0, v96, v4
	v_lshl_add_u64 v[2:3], s[62:63], 0, v[50:51]
	v_lshlrev_b64 v[50:51], 1, v[0:1]
	v_lshlrev_b32_e32 v0, 16, v223
	v_mov_b32_e32 v231, v1
	v_add_u32_e32 v230,v89,v6
	v_lshlrev_b64 v[232:233],1,v[230:231]
	v_lshl_add_u64 v[234:235],s[18:19],0,v[232:233]
	global_load_ushort v223, v[234:235], off
	v_lshl_add_u64 v[14:15], s[18:19], 0, v[58:59]
	v_lshl_add_u64 v[74:75], s[18:19], 0, v[50:51]
	s_waitcnt vmcnt(44)
	v_lshlrev_b32_e32 v34, 16, v217
	v_mov_b32_e32 v231, v1
	v_add_u32_e32 v230,v77,v6
	v_lshlrev_b64 v[232:233],1,v[230:231]
	v_lshl_add_u64 v[234:235],s[62:63],0,v[232:233]
	global_load_ushort v217, v[234:235], off
	v_fmac_f32_e32 v0, v35, v34
	v_cvt_pk_bf16_f32 v0, v0, s0
	global_store_short v[8:9], v0, off
	v_lshlrev_b32_e32 v34, 16, v205
	v_mov_b32_e32 v231, v1
	v_add_u32_e32 v230,v80,v6
	v_lshlrev_b64 v[232:233],1,v[230:231]
	v_lshl_add_u64 v[234:235],s[18:19],0,v[232:233]
	global_load_ushort v205, v[234:235], off
	v_lshl_add_u64 v[2:3], s[62:63], 0, v[54:55]
	v_lshl_add_u64 v[8:9], s[18:19], 0, v[64:65]
	s_waitcnt vmcnt(42)
	v_lshlrev_b32_e32 v0, 16, v225
	v_mov_b32_e32 v231, v1
	v_add_u32_e32 v230,v87,v6
	v_lshlrev_b64 v[232:233],1,v[230:231]
	v_lshl_add_u64 v[234:235],s[18:19],0,v[232:233]
	global_load_ushort v225, v[234:235], off
	v_fmac_f32_e32 v34, v36, v0
	v_cvt_pk_bf16_f32 v0, v34, s0
	global_store_short v[52:53], v0, off
	v_lshlrev_b32_e32 v36, 16, v204
	v_mov_b32_e32 v231, v1
	v_add_u32_e32 v230,v78,v6
	v_lshlrev_b64 v[232:233],1,v[230:231]
	v_lshl_add_u64 v[234:235],s[62:63],0,v[232:233]
	global_load_ushort v204, v[234:235], off
	v_lshl_add_u64 v[2:3], s[62:63], 0, v[56:57]
	v_lshl_add_u64 v[34:35], s[18:19], 0, v[68:69]
	v_or_b32_e32 v56, 0x1ec00, v5
	s_waitcnt vmcnt(42)
	v_lshlrev_b32_e32 v0, 16, v212
	v_mov_b32_e32 v231, v1
	v_add_u32_e32 v230,v82,v6
	v_lshlrev_b64 v[232:233],1,v[230:231]
	v_lshl_add_u64 v[234:235],s[18:19],0,v[232:233]
	global_load_ushort v212, v[234:235], off
	v_fmac_f32_e32 v36, v37, v0
	v_cvt_pk_bf16_f32 v0, v36, s0
	global_store_short v[10:11], v0, off
	v_lshl_add_u64 v[10:11], s[18:19], 0, v[48:49]
	v_lshlrev_b32_e32 v36, 16, v216
	v_mov_b32_e32 v231, v1
	v_add_u32_e32 v230,v96,v6
	v_lshlrev_b64 v[232:233],1,v[230:231]
	v_lshl_add_u64 v[234:235],s[18:19],0,v[232:233]
	global_load_ushort v216, v[234:235], off
	v_lshl_add_u64 v[2:3], s[62:63], 0, v[58:59]
	s_waitcnt vmcnt(42)
	v_lshlrev_b32_e32 v0, 16, v220
	v_mov_b32_e32 v231, v1
	v_add_u32_e32 v230,v79,v6
	v_lshlrev_b64 v[232:233],1,v[230:231]
	v_lshl_add_u64 v[234:235],s[62:63],0,v[232:233]
	global_load_ushort v220, v[234:235], off
	v_fmac_f32_e32 v36, v38, v0
	v_cvt_pk_bf16_f32 v0, v36, s0
	global_store_short v[12:13], v0, off
	v_add_u32_e32 v0, v56, v4
	v_lshlrev_b64 v[4:5], 1, v[0:1]
	v_lshlrev_b32_e32 v0, 16, v215
	v_mov_b32_e32 v231, v1
	v_add_u32_e32 v230,v86,v6
	v_lshlrev_b64 v[232:233],1,v[230:231]
	v_lshl_add_u64 v[234:235],s[18:19],0,v[232:233]
	global_load_ushort v215, v[234:235], off
	v_lshl_add_u64 v[12:13], s[62:63], 0, v[60:61]
	v_lshl_add_u64 v[2:3], s[18:19], 0, v[4:5]
	v_lshl_add_u64 v[4:5], s[62:63], 0, v[4:5]
	s_waitcnt vmcnt(42)
	v_lshlrev_b32_e32 v36, 16, v227
	v_mov_b32_e32 v231, v1
	v_add_u32_e32 v230,v80,v6
	v_lshlrev_b64 v[232:233],1,v[230:231]
	v_lshl_add_u64 v[234:235],s[62:63],0,v[232:233]
	global_load_ushort v227, v[234:235], off
	v_fmac_f32_e32 v0, v39, v36
	v_cvt_pk_bf16_f32 v0, v0, s0
	global_store_short v[14:15], v0, off
	v_lshlrev_b32_e32 v14, 16, v201
	v_mov_b32_e32 v231, v1
	v_add_u32_e32 v230,v88,v6
	v_lshlrev_b64 v[232:233],1,v[230:231]
	v_lshl_add_u64 v[234:235],s[18:19],0,v[232:233]
	global_load_ushort v201, v[234:235], off
	v_lshl_add_u64 v[12:13], s[62:63], 0, v[64:65]
	s_waitcnt vmcnt(42)
	v_lshlrev_b32_e32 v0, 16, v195
	v_mov_b32_e32 v231, v1
	v_add_u32_e32 v230,v81,v6
	v_lshlrev_b64 v[232:233],1,v[230:231]
	v_lshl_add_u64 v[234:235],s[62:63],0,v[232:233]
	global_load_ushort v195, v[234:235], off
	v_fmac_f32_e32 v14, v40, v0
	v_cvt_pk_bf16_f32 v0, v14, s0
	global_store_short v[62:63], v0, off
	v_lshlrev_b32_e32 v14, 16, v203
	v_mov_b32_e32 v231, v1
	v_add_u32_e32 v230,v95,v6
	v_lshlrev_b64 v[232:233],1,v[230:231]
	v_lshl_add_u64 v[234:235],s[18:19],0,v[232:233]
	global_load_ushort v203, v[234:235], off
	v_lshl_add_u64 v[12:13], s[62:63], 0, v[66:67]
	s_waitcnt vmcnt(44)
	v_lshlrev_b32_e32 v0, 16, v213
	v_mov_b32_e32 v231, v1
	v_add_u32_e32 v230,v82,v6
	v_lshlrev_b64 v[232:233],1,v[230:231]
	v_lshl_add_u64 v[234:235],s[62:63],0,v[232:233]
	global_load_ushort v213, v[234:235], off
	v_fmac_f32_e32 v14, v41, v0
	v_cvt_pk_bf16_f32 v0, v14, s0
	global_store_short v[8:9], v0, off
	v_lshlrev_b32_e32 v12, 16, v211
	v_mov_b32_e32 v231, v1
	v_add_u32_e32 v230,v83,v6
	v_lshlrev_b64 v[232:233],1,v[230:231]
	v_lshl_add_u64 v[234:235],s[62:63],0,v[232:233]
	global_load_ushort v211, v[234:235], off
	v_lshl_add_u64 v[8:9], s[62:63], 0, v[68:69]
	s_waitcnt vmcnt(45)
	v_lshlrev_b32_e32 v0, 16, v226
	v_mov_b32_e32 v231, v1
	v_add_u32_e32 v230,v86,v6
	v_lshlrev_b64 v[232:233],1,v[230:231]
	v_lshl_add_u64 v[234:235],s[62:63],0,v[232:233]
	global_load_ushort v226, v[234:235], off
	v_fmac_f32_e32 v12, v42, v0
	v_cvt_pk_bf16_f32 v0, v12, s0
	global_store_short v[32:33], v0, off
	v_lshlrev_b32_e32 v12, 16, v219
	v_mov_b32_e32 v231, v1
	v_add_u32_e32 v230,v87,v6
	v_lshlrev_b64 v[232:233],1,v[230:231]
	v_lshl_add_u64 v[234:235],s[62:63],0,v[232:233]
	global_load_ushort v219, v[234:235], off
	v_lshl_add_u64 v[8:9], s[62:63], 0, v[70:71]
	s_waitcnt vmcnt(47)
	v_lshlrev_b32_e32 v0, 16, v221
	v_mov_b32_e32 v231, v1
	v_add_u32_e32 v230,v88,v6
	v_lshlrev_b64 v[232:233],1,v[230:231]
	v_lshl_add_u64 v[234:235],s[62:63],0,v[232:233]
	global_load_ushort v221, v[234:235], off
	v_fmac_f32_e32 v12, v43, v0
	v_cvt_pk_bf16_f32 v0, v12, s0
	global_store_short v[34:35], v0, off
	v_lshlrev_b32_e32 v12, 16, v194
	v_mov_b32_e32 v231, v1
	v_add_u32_e32 v230,v89,v6
	v_lshlrev_b64 v[232:233],1,v[230:231]
	v_lshl_add_u64 v[234:235],s[62:63],0,v[232:233]
	global_load_ushort v194, v[234:235], off
	v_lshl_add_u64 v[8:9], s[62:63], 0, v[48:49]
	s_waitcnt vmcnt(48)
	v_lshlrev_b32_e32 v0, 16, v229
	v_mov_b32_e32 v231, v1
	v_add_u32_e32 v230,v95,v6
	v_lshlrev_b64 v[232:233],1,v[230:231]
	v_lshl_add_u64 v[234:235],s[62:63],0,v[232:233]
	global_load_ushort v229, v[234:235], off
	v_fmac_f32_e32 v12, v44, v0
	v_cvt_pk_bf16_f32 v0, v12, s0
	global_store_short v[72:73], v0, off
	v_lshlrev_b32_e32 v12, 16, v224
	v_mov_b32_e32 v231, v1
	v_add_u32_e32 v230,v96,v6
	v_lshlrev_b64 v[232:233],1,v[230:231]
	v_lshl_add_u64 v[234:235],s[62:63],0,v[232:233]
	global_load_ushort v224, v[234:235], off
	v_lshl_add_u64 v[8:9], s[62:63], 0, v[50:51]
	s_waitcnt vmcnt(50)
	v_lshlrev_b32_e32 v0, 16, v214
	v_mov_b32_e32 v231, v1
	v_add_u32_e32 v230,v56,v6
	v_lshlrev_b64 v[232:233],1,v[230:231]
	v_lshl_add_u64 v[234:235],s[62:63],0,v[232:233]
	global_load_ushort v214, v[234:235], off
	v_fmac_f32_e32 v12, v45, v0
	v_cvt_pk_bf16_f32 v0, v12, s0
	global_store_short v[10:11], v0, off
	v_lshlrev_b32_e32 v8, 16, v196
	s_waitcnt vmcnt(50)
	v_lshlrev_b32_e32 v0, 16, v210
	v_fmac_f32_e32 v8, v46, v0
	v_cvt_pk_bf16_f32 v0, v8, s0
	global_store_short v[74:75], v0, off
	v_add_u32_e32 v0, v7, v6
	v_lshlrev_b64 v[4:5], 1, v[0:1]
	v_add_u32_e32 v0, v76, v6
	v_lshlrev_b64 v[10:11], 1, v[0:1]
	v_add_u32_e32 v0, v77, v6
	v_lshlrev_b64 v[12:13], 1, v[0:1]
	v_add_u32_e32 v0, v78, v6
	v_lshlrev_b64 v[14:15], 1, v[0:1]
	v_add_u32_e32 v0, v79, v6
	v_lshlrev_b64 v[32:33], 1, v[0:1]
	v_add_u32_e32 v0, v80, v6
	v_lshlrev_b64 v[34:35], 1, v[0:1]
	v_add_u32_e32 v0, v81, v6
	v_lshlrev_b64 v[36:37], 1, v[0:1]
	v_add_u32_e32 v0, v82, v6
	v_lshlrev_b64 v[38:39], 1, v[0:1]
	v_add_u32_e32 v0, v83, v6
	v_lshlrev_b64 v[40:41], 1, v[0:1]
	v_add_u32_e32 v0, v86, v6
	v_lshlrev_b64 v[42:43], 1, v[0:1]
	v_add_u32_e32 v0, v87, v6
	v_lshlrev_b64 v[44:45], 1, v[0:1]
	v_add_u32_e32 v0, v88, v6
	v_lshlrev_b64 v[48:49], 1, v[0:1]
	v_add_u32_e32 v0, v89, v6
	v_lshlrev_b64 v[50:51], 1, v[0:1]
	v_add_u32_e32 v0, v95, v6
	v_lshlrev_b64 v[52:53], 1, v[0:1]
	v_add_u32_e32 v0, v96, v6
	v_lshlrev_b64 v[54:55], 1, v[0:1]
	v_add_u32_e32 v0, v56, v6
	v_lshlrev_b64 v[6:7], 1, v[0:1]
	v_lshlrev_b32_e32 v0, 16, v228
	v_lshl_add_u64 v[8:9], s[18:19], 0, v[4:5]
	v_lshl_add_u64 v[56:57], s[18:19], 0, v[6:7]
	v_lshl_add_u64 v[4:5], s[62:63], 0, v[4:5]
	v_lshl_add_u64 v[58:59], s[18:19], 0, v[40:41]
	s_waitcnt vmcnt(50)
	v_lshlrev_b32_e32 v46, 16, v198
	v_fmac_f32_e32 v0, v47, v46
	v_cvt_pk_bf16_f32 v0, v0, s0
	global_store_short v[2:3], v0, off
	s_nop 0
	v_lshl_add_u64 v[2:3], s[18:19], 0, v[10:11]
	v_lshl_add_u64 v[4:5], s[62:63], 0, v[10:11]
	v_lshl_add_u64 v[10:11], s[18:19], 0, v[12:13]
	v_lshl_add_u64 v[46:47], s[18:19], 0, v[32:33]
	s_waitcnt vmcnt(48)
	v_lshlrev_b32_e32 v0, 16, v193
	s_waitcnt vmcnt(46)
	v_lshlrev_b32_e32 v60, 16, v192
	v_fmac_f32_e32 v0, v16, v60
	v_cvt_pk_bf16_f32 v0, v0, s0
	global_store_short v[8:9], v0, off
	s_waitcnt vmcnt(46)
	v_lshlrev_b32_e32 v16, 16, v206
	v_lshl_add_u64 v[8:9], s[18:19], 0, v[14:15]
	v_lshl_add_u64 v[4:5], s[62:63], 0, v[12:13]
	v_lshl_add_u64 v[12:13], s[18:19], 0, v[36:37]
	v_lshl_add_u64 v[60:61], s[18:19], 0, v[50:51]
	s_waitcnt vmcnt(40)
	v_lshlrev_b32_e32 v0, 16, v202
	v_fmac_f32_e32 v16, v17, v0
	v_cvt_pk_bf16_f32 v0, v16, s0
	global_store_short v[2:3], v0, off
	v_lshlrev_b32_e32 v16, 16, v207
	v_lshl_add_u64 v[4:5], s[18:19], 0, v[34:35]
	v_lshl_add_u64 v[2:3], s[62:63], 0, v[14:15]
	v_lshl_add_u64 v[14:15], s[18:19], 0, v[44:45]
	s_waitcnt vmcnt(35)
	v_lshlrev_b32_e32 v0, 16, v217
	v_fmac_f32_e32 v16, v18, v0
	v_cvt_pk_bf16_f32 v0, v16, s0
	global_store_short v[10:11], v0, off
	v_lshlrev_b32_e32 v18, 16, v199
	v_lshl_add_u64 v[10:11], s[18:19], 0, v[38:39]
	v_lshl_add_u64 v[2:3], s[62:63], 0, v[32:33]
	v_lshl_add_u64 v[16:17], s[18:19], 0, v[54:55]
	s_waitcnt vmcnt(31)
	v_lshlrev_b32_e32 v0, 16, v204
	v_fmac_f32_e32 v18, v19, v0
	v_cvt_pk_bf16_f32 v0, v18, s0
	global_store_short v[8:9], v0, off
	v_lshlrev_b32_e32 v18, 16, v218
	v_lshl_add_u64 v[2:3], s[62:63], 0, v[34:35]
	v_lshl_add_u64 v[8:9], s[18:19], 0, v[42:43]
	s_waitcnt vmcnt(28)
	v_lshlrev_b32_e32 v0, 16, v220
	v_fmac_f32_e32 v18, v20, v0
	v_cvt_pk_bf16_f32 v0, v18, s0
	global_store_short v[46:47], v0, off
	v_lshlrev_b32_e32 v20, 16, v205
	v_lshl_add_u64 v[2:3], s[62:63], 0, v[36:37]
	v_lshl_add_u64 v[18:19], s[18:19], 0, v[48:49]
	s_waitcnt vmcnt(26)
	v_lshlrev_b32_e32 v0, 16, v227
	v_fmac_f32_e32 v20, v21, v0
	v_cvt_pk_bf16_f32 v0, v20, s0
	global_store_short v[4:5], v0, off
	v_lshl_add_u64 v[4:5], s[18:19], 0, v[52:53]
	v_lshlrev_b32_e32 v20, 16, v222
	v_lshl_add_u64 v[2:3], s[62:63], 0, v[38:39]
	s_waitcnt vmcnt(24)
	v_lshlrev_b32_e32 v0, 16, v195
	v_fmac_f32_e32 v20, v22, v0
	v_cvt_pk_bf16_f32 v0, v20, s0
	global_store_short v[12:13], v0, off
	v_lshlrev_b32_e32 v12, 16, v212
	v_lshl_add_u64 v[2:3], s[62:63], 0, v[40:41]
	s_waitcnt vmcnt(22)
	v_lshlrev_b32_e32 v0, 16, v213
	v_fmac_f32_e32 v12, v23, v0
	v_cvt_pk_bf16_f32 v0, v12, s0
	global_store_short v[10:11], v0, off
	v_lshlrev_b32_e32 v10, 16, v197
	v_lshl_add_u64 v[2:3], s[62:63], 0, v[42:43]
	s_waitcnt vmcnt(21)
	v_lshlrev_b32_e32 v0, 16, v211
	v_fmac_f32_e32 v10, v24, v0
	v_cvt_pk_bf16_f32 v0, v10, s0
	global_store_short v[58:59], v0, off
	v_lshlrev_b32_e32 v10, 16, v215
	v_lshl_add_u64 v[2:3], s[62:63], 0, v[44:45]
	s_waitcnt vmcnt(21)
	v_lshlrev_b32_e32 v0, 16, v226
	v_fmac_f32_e32 v10, v25, v0
	v_cvt_pk_bf16_f32 v0, v10, s0
	global_store_short v[8:9], v0, off
	v_lshlrev_b32_e32 v8, 16, v225
	v_lshl_add_u64 v[2:3], s[62:63], 0, v[48:49]
	s_waitcnt vmcnt(20)
	v_lshlrev_b32_e32 v0, 16, v219
	v_fmac_f32_e32 v8, v26, v0
	v_cvt_pk_bf16_f32 v0, v8, s0
	global_store_short v[14:15], v0, off
	v_lshlrev_b32_e32 v8, 16, v201
	v_lshl_add_u64 v[2:3], s[62:63], 0, v[50:51]
	s_waitcnt vmcnt(20)
	v_lshlrev_b32_e32 v0, 16, v221
	v_fmac_f32_e32 v8, v27, v0
	v_cvt_pk_bf16_f32 v0, v8, s0
	global_store_short v[18:19], v0, off
	v_lshlrev_b32_e32 v8, 16, v223
	v_lshl_add_u64 v[2:3], s[62:63], 0, v[52:53]
	s_waitcnt vmcnt(19)
	v_lshlrev_b32_e32 v0, 16, v194
	v_fmac_f32_e32 v8, v28, v0
	v_cvt_pk_bf16_f32 v0, v8, s0
	global_store_short v[60:61], v0, off
	v_lshlrev_b32_e32 v8, 16, v203
	v_lshl_add_u64 v[2:3], s[62:63], 0, v[54:55]
	s_waitcnt vmcnt(19)
	v_lshlrev_b32_e32 v0, 16, v229
	v_fmac_f32_e32 v8, v29, v0
	v_cvt_pk_bf16_f32 v0, v8, s0
	global_store_short v[4:5], v0, off
	v_lshlrev_b32_e32 v2, 16, v216
	s_waitcnt vmcnt(18)
	v_lshlrev_b32_e32 v0, 16, v224
	v_fmac_f32_e32 v2, v30, v0
	v_cvt_pk_bf16_f32 v0, v2, s0
	global_store_short v[16:17], v0, off
	v_lshl_add_u64 v[2:3], s[62:63], 0, v[6:7]
	v_lshlrev_b32_e32 v2, 16, v209
	s_waitcnt vmcnt(18)
	v_lshlrev_b32_e32 v0, 16, v214
	v_fmac_f32_e32 v2, v31, v0
	v_cvt_pk_bf16_f32 v0, v2, s0
	global_store_short v[56:57], v0, off
	s_add_i32 s31, s31, s92
	s_cmpk_gt_i32 s31, 0x103
	s_cbranch_scc1 .LBB0_3413

.LBB0_3396:
	s_lshl_b64 s[14:15], s[0:1], 9
	s_lshl_b64 s[4:5], s[6:7], 9
	s_waitcnt vmcnt(0)
	v_mov_b32_e32 v0, v208
	v_mov_b32_e32 v2, v1
	v_lshrrev_b32_e32 v3, 1, v0
	v_and_b32_e32 v3, 0x3fff80, v3
	v_lshrrev_b32_e32 v4, 3, v0
	v_add_u32_e32 v3, s0, v3
	v_and_b32_e32 v0, 0xdf, v0
	v_and_or_b32 v3, v4, 4, v3
	v_or_b32_e32 v0, s6, v0
	v_add_u32_e32 v2, v0, v2
	v_lshlrev_b32_e32 v3, 10, v3
	v_add_u32_e32 v0, v3, v2
	v_or_b32_e32 v164, 0x400, v3
	v_lshl_add_u64 v[6:7], v[0:1], 1, s[18:19]
	v_add_u32_e32 v0, v164, v2
	v_or_b32_e32 v167, 0x800, v3
	v_lshl_add_u64 v[4:5], v[0:1], 1, s[18:19]
	v_add_u32_e32 v0, v167, v2
	v_or_b32_e32 v169, 0xc00, v3
	global_load_ushort v194, v[6:7], off
	global_load_ushort v195, v[4:5], off
	v_lshl_add_u64 v[230:231],v[0:1],1,s[18:19]
	global_load_ushort v196, v[230:231], off
	v_mov_b32_e32 v231, v1
	v_add_u32_e32 v230,v169,v2
	v_lshl_add_u64 v[232:233],v[230:231],1,s[18:19]
	global_load_ushort v197, v[232:233], off
	v_mov_b32_e32 v233, v1
	v_or_b32_e32 v231,0x2000,v3
	v_add_u32_e32 v232,v231,v2
	v_lshl_add_u64 v[234:235],v[232:233],1,s[18:19]
	global_load_ushort v198, v[234:235], off
	v_mov_b32_e32 v233, v1
	v_or_b32_e32 v231,0x2400,v3
	v_add_u32_e32 v232,v231,v2
	v_lshl_add_u64 v[234:235],v[232:233],1,s[18:19]
	global_load_ushort v199, v[234:235], off
	v_mov_b32_e32 v233, v1
	v_or_b32_e32 v231,0x2800,v3
	v_add_u32_e32 v232,v231,v2
	v_lshl_add_u64 v[234:235],v[232:233],1,s[18:19]
	global_load_ushort v201, v[234:235], off
	v_mov_b32_e32 v233, v1
	v_or_b32_e32 v231,0x2c00,v3
	v_add_u32_e32 v232,v231,v2
	v_lshl_add_u64 v[234:235],v[232:233],1,s[18:19]
	global_load_ushort v202, v[234:235], off
	v_mov_b32_e32 v233, v1
	v_or_b32_e32 v231,0x4000,v3
	v_add_u32_e32 v232,v231,v2
	v_lshl_add_u64 v[234:235],v[232:233],1,s[18:19]
	global_load_ushort v203, v[234:235], off
	v_mov_b32_e32 v233, v1
	v_or_b32_e32 v231,0x4400,v3
	v_add_u32_e32 v232,v231,v2
	v_lshl_add_u64 v[234:235],v[232:233],1,s[18:19]
	global_load_ushort v204, v[234:235], off
	v_mov_b32_e32 v233, v1
	v_or_b32_e32 v231,0x4800,v3
	v_add_u32_e32 v232,v231,v2
	v_lshl_add_u64 v[234:235],v[232:233],1,s[18:19]
	global_load_ushort v205, v[234:235], off
	v_mov_b32_e32 v233, v1
	v_or_b32_e32 v231,0x4c00,v3
	v_add_u32_e32 v232,v231,v2
	v_lshl_add_u64 v[234:235],v[232:233],1,s[18:19]
	global_load_ushort v206, v[234:235], off
	v_mov_b32_e32 v233, v1
	v_or_b32_e32 v231,0x6000,v3
	v_add_u32_e32 v232,v231,v2
	v_lshl_add_u64 v[234:235],v[232:233],1,s[18:19]
	global_load_ushort v207, v[234:235], off
	v_mov_b32_e32 v233, v1
	v_or_b32_e32 v231,0x6400,v3
	v_add_u32_e32 v232,v231,v2
	v_lshl_add_u64 v[234:235],v[232:233],1,s[18:19]
	global_load_ushort v209, v[234:235], off
	v_mov_b32_e32 v233, v1
	v_or_b32_e32 v231,0x6800,v3
	v_add_u32_e32 v232,v231,v2
	v_lshl_add_u64 v[234:235],v[232:233],1,s[18:19]
	global_load_ushort v210, v[234:235], off
	v_mov_b32_e32 v233, v1
	v_or_b32_e32 v231,0x6c00,v3
	v_add_u32_e32 v232,v231,v2
	v_lshl_add_u64 v[234:235],v[232:233],1,s[18:19]
	global_load_ushort v211, v[234:235], off
	v_mov_b32_e32 v233, v1
	v_add_u32_e32 v230,32,v2
	v_add_u32_e32 v232,v3,v230
	v_lshl_add_u64 v[234:235],v[232:233],1,s[18:19]
	global_load_ushort v212, v[234:235], off
	v_mov_b32_e32 v233, v1
	v_add_u32_e32 v230,32,v2
	v_add_u32_e32 v232,v167,v230
	v_lshl_add_u64 v[234:235],v[232:233],1,s[18:19]
	global_load_ushort v213, v[234:235], off
	v_mov_b32_e32 v233, v1
	v_add_u32_e32 v230,32,v2
	v_add_u32_e32 v232,v169,v230
	v_lshl_add_u64 v[234:235],v[232:233],1,s[18:19]
	global_load_ushort v214, v[234:235], off
	v_mov_b32_e32 v235, v1
	v_or_b32_e32 v231,0x2000,v3
	v_add_u32_e32 v232,32,v2
	v_add_u32_e32 v234,v231,v232
	v_lshl_add_u64 v[236:237],v[234:235],1,s[18:19]
	global_load_ushort v215, v[236:237], off
	v_mov_b32_e32 v235, v1
	v_or_b32_e32 v231,0x2400,v3
	v_add_u32_e32 v232,32,v2
	v_add_u32_e32 v234,v231,v232
	v_lshl_add_u64 v[236:237],v[234:235],1,s[18:19]
	global_load_ushort v216, v[236:237], off
	v_mov_b32_e32 v235, v1
	v_or_b32_e32 v231,0x2800,v3
	v_add_u32_e32 v232,32,v2
	v_add_u32_e32 v234,v231,v232
	v_lshl_add_u64 v[236:237],v[234:235],1,s[18:19]
	global_load_ushort v217, v[236:237], off
	v_mov_b32_e32 v235, v1
	v_or_b32_e32 v231,0x2c00,v3
	v_add_u32_e32 v232,32,v2
	v_add_u32_e32 v234,v231,v232
	v_lshl_add_u64 v[236:237],v[234:235],1,s[18:19]
	global_load_ushort v218, v[236:237], off
	v_mov_b32_e32 v233, v1
	v_add_u32_e32 v230,32,v2
	v_add_u32_e32 v232,v164,v230
	v_lshl_add_u64 v[234:235],v[232:233],1,s[18:19]
	global_load_ushort v219, v[234:235], off
	v_mov_b32_e32 v235, v1
	v_or_b32_e32 v231,0x4000,v3
	v_add_u32_e32 v232,32,v2
	v_add_u32_e32 v234,v231,v232
	v_lshl_add_u64 v[236:237],v[234:235],1,s[18:19]
	global_load_ushort v220, v[236:237], off
	v_mov_b32_e32 v235, v1
	v_or_b32_e32 v231,0x4400,v3
	v_add_u32_e32 v232,32,v2
	v_add_u32_e32 v234,v231,v232
	v_lshl_add_u64 v[236:237],v[234:235],1,s[18:19]
	global_load_ushort v221, v[236:237], off
	v_mov_b32_e32 v235, v1
	v_or_b32_e32 v231,0x4800,v3
	v_add_u32_e32 v232,32,v2
	v_add_u32_e32 v234,v231,v232
	v_lshl_add_u64 v[236:237],v[234:235],1,s[18:19]
	global_load_ushort v222, v[236:237], off
	v_mov_b32_e32 v235, v1
	v_or_b32_e32 v231,0x4c00,v3
	v_add_u32_e32 v232,32,v2
	v_add_u32_e32 v234,v231,v232
	v_lshl_add_u64 v[236:237],v[234:235],1,s[18:19]
	global_load_ushort v223, v[236:237], off
	v_mov_b32_e32 v235, v1
	v_or_b32_e32 v231,0x6000,v3
	v_add_u32_e32 v232,32,v2
	v_add_u32_e32 v234,v231,v232
	v_lshl_add_u64 v[236:237],v[234:235],1,s[18:19]
	global_load_ushort v224, v[236:237], off
	v_mov_b32_e32 v235, v1
	v_or_b32_e32 v231,0x6400,v3
	v_add_u32_e32 v232,32,v2
	v_add_u32_e32 v234,v231,v232
	v_lshl_add_u64 v[236:237],v[234:235],1,s[18:19]
	global_load_ushort v225, v[236:237], off
	v_mov_b32_e32 v235, v1
	v_or_b32_e32 v231,0x6800,v3
	v_add_u32_e32 v232,32,v2
	v_add_u32_e32 v234,v231,v232
	v_lshl_add_u64 v[236:237],v[234:235],1,s[18:19]
	global_load_ushort v226, v[236:237], off
	v_mov_b32_e32 v235, v1
	v_or_b32_e32 v231,0x6c00,v3
	v_add_u32_e32 v232,32,v2
	v_add_u32_e32 v234,v231,v232
	v_lshl_add_u64 v[236:237],v[234:235],1,s[18:19]
	global_load_ushort v227, v[236:237], off
	v_mov_b32_e32 v233, v1
	v_or_b32_e32 v231,0x8000,v3
	v_add_u32_e32 v232,v231,v2
	v_lshl_add_u64 v[234:235],v[232:233],1,s[18:19]
	global_load_ushort v228, v[234:235], off
	v_mov_b32_e32 v233, v1
	v_or_b32_e32 v230,0x8400,v3
	v_add_u32_e32 v232,v230,v2
	v_lshl_add_u64 v[234:235],v[232:233],1,s[18:19]
	global_load_ushort v229, v[234:235], off
	v_lshl_add_u64 v[8:9], v[0:1], 1, s[18:19]
	v_add_u32_e32 v0, v169, v2
	v_or_b32_e32 v171, 0x2000, v3
	v_lshl_add_u64 v[10:11], v[0:1], 1, s[18:19]
	v_add_u32_e32 v0, v171, v2
	v_or_b32_e32 v173, 0x2400, v3
	v_lshl_add_u64 v[12:13], v[0:1], 1, s[18:19]
	v_add_u32_e32 v0, v173, v2
	v_lshl_add_u64 v[14:15], v[0:1], 1, s[18:19]
	v_or_b32_e32 v175, 0x2800, v3
	v_add_u32_e32 v0, v175, v2
	v_lshl_add_u64 v[144:145], v[0:1], 1, s[18:19]
	v_or_b32_e32 v177, 0x2c00, v3
	v_add_u32_e32 v0, v177, v2
	v_lshl_add_u64 v[146:147], v[0:1], 1, s[18:19]
	v_or_b32_e32 v179, 0x4000, v3
	v_add_u32_e32 v0, v179, v2
	v_lshl_add_u64 v[148:149], v[0:1], 1, s[18:19]
	v_or_b32_e32 v181, 0x4400, v3
	v_add_u32_e32 v0, v181, v2
	v_lshl_add_u64 v[150:151], v[0:1], 1, s[18:19]
	v_or_b32_e32 v183, 0x4800, v3
	v_add_u32_e32 v0, v183, v2
	v_lshl_add_u64 v[152:153], v[0:1], 1, s[18:19]
	v_or_b32_e32 v185, 0x4c00, v3
	v_add_u32_e32 v0, v185, v2
	v_lshl_add_u64 v[154:155], v[0:1], 1, s[18:19]
	v_or_b32_e32 v187, 0x6000, v3
	v_add_u32_e32 v0, v187, v2
	v_lshl_add_u64 v[156:157], v[0:1], 1, s[18:19]
	v_or_b32_e32 v189, 0x6400, v3
	v_add_u32_e32 v0, v189, v2
	v_lshl_add_u64 v[158:159], v[0:1], 1, s[18:19]
	v_or_b32_e32 v191, 0x6800, v3
	v_add_u32_e32 v0, v191, v2
	v_or_b32_e32 v193, 0x6c00, v3
	v_lshl_add_u64 v[160:161], v[0:1], 1, s[18:19]
	v_add_u32_e32 v0, v193, v2
	v_lshl_add_u64 v[162:163], v[0:1], 1, s[18:19]
	s_waitcnt vmcnt(33)
	v_lshlrev_b32_e32 v165, 16, v194
	v_mov_b32_e32 v233, v1
	v_or_b32_e32 v231,0x8800,v3
	v_add_u32_e32 v232,v231,v2
	v_lshl_add_u64 v[234:235],v[232:233],1,s[18:19]
	global_load_ushort v194, v[234:235], off
	v_mul_f32_e32 v128, v128, v165
	s_waitcnt vmcnt(33)
	v_lshlrev_b32_e32 v165, 16, v195
	v_mov_b32_e32 v233, v1
	v_or_b32_e32 v231,0x8c00,v3
	v_add_u32_e32 v232,v231,v2
	v_lshl_add_u64 v[234:235],v[232:233],1,s[18:19]
	global_load_ushort v195, v[234:235], off
	v_mul_f32_e32 v129, v129, v165
	v_cvt_pk_bf16_f32 v129, v129, s0
	s_waitcnt vmcnt(33)
	v_lshlrev_b32_e32 v165, 16, v196
	v_mov_b32_e32 v233, v1
	v_or_b32_e32 v231,0xa000,v3
	v_add_u32_e32 v232,v231,v2
	v_lshl_add_u64 v[234:235],v[232:233],1,s[18:19]
	global_load_ushort v196, v[234:235], off
	v_mul_f32_e32 v130, v130, v165
	global_store_short v[4:5], v129, off
	v_cvt_pk_bf16_f32 v4, v130, s0
	s_waitcnt vmcnt(34)
	v_lshlrev_b32_e32 v165, 16, v197
	v_mov_b32_e32 v233, v1
	v_or_b32_e32 v231,0xa400,v3
	v_add_u32_e32 v232,v231,v2
	v_lshl_add_u64 v[234:235],v[232:233],1,s[18:19]
	global_load_ushort v197, v[234:235], off
	v_mul_f32_e32 v5, v131, v165
	global_store_short v[8:9], v4, off
	s_waitcnt vmcnt(35)
	v_lshlrev_b32_e32 v129, 16, v198
	v_mov_b32_e32 v233, v1
	v_or_b32_e32 v231,0xa800,v3
	v_add_u32_e32 v232,v231,v2
	v_lshl_add_u64 v[234:235],v[232:233],1,s[18:19]
	global_load_ushort v198, v[234:235], off
	v_cvt_pk_bf16_f32 v4, v5, s0
	v_mul_f32_e32 v5, v132, v129
	s_waitcnt vmcnt(35)
	v_lshlrev_b32_e32 v8, 16, v199
	v_mov_b32_e32 v233, v1
	v_or_b32_e32 v231,0xac00,v3
	v_add_u32_e32 v232,v231,v2
	v_lshl_add_u64 v[234:235],v[232:233],1,s[18:19]
	global_load_ushort v199, v[234:235], off
	global_store_short v[10:11], v4, off
	v_cvt_pk_bf16_f32 v4, v5, s0
	v_mul_f32_e32 v5, v133, v8
	global_store_short v[12:13], v4, off
	v_cvt_pk_bf16_f32 v4, v5, s0
	global_store_short v[14:15], v4, off
	s_waitcnt vmcnt(38)
	v_lshlrev_b32_e32 v4, 16, v201
	v_mov_b32_e32 v233, v1
	v_or_b32_e32 v231,0xc000,v3
	v_add_u32_e32 v232,v231,v2
	v_lshl_add_u64 v[234:235],v[232:233],1,s[18:19]
	global_load_ushort v201, v[234:235], off
	v_mul_f32_e32 v4, v134, v4
	v_cvt_pk_bf16_f32 v4, v4, s0
	global_store_short v[144:145], v4, off
	s_waitcnt vmcnt(39)
	v_lshlrev_b32_e32 v4, 16, v202
	v_mov_b32_e32 v233, v1
	v_or_b32_e32 v231,0xc400,v3
	v_add_u32_e32 v232,v231,v2
	v_lshl_add_u64 v[234:235],v[232:233],1,s[18:19]
	global_load_ushort v202, v[234:235], off
	v_mul_f32_e32 v4, v135, v4
	v_cvt_pk_bf16_f32 v4, v4, s0
	global_store_short v[146:147], v4, off
	s_waitcnt vmcnt(40)
	v_lshlrev_b32_e32 v4, 16, v203
	v_mov_b32_e32 v233, v1
	v_or_b32_e32 v231,0xc800,v3
	v_add_u32_e32 v232,v231,v2
	v_lshl_add_u64 v[234:235],v[232:233],1,s[18:19]
	global_load_ushort v203, v[234:235], off
	v_mul_f32_e32 v4, v136, v4
	v_cvt_pk_bf16_f32 v4, v4, s0
	global_store_short v[148:149], v4, off
	s_waitcnt vmcnt(41)
	v_lshlrev_b32_e32 v4, 16, v204
	v_mov_b32_e32 v233, v1
	v_or_b32_e32 v231,0xcc00,v3
	v_add_u32_e32 v232,v231,v2
	v_lshl_add_u64 v[234:235],v[232:233],1,s[18:19]
	global_load_ushort v204, v[234:235], off
	v_mul_f32_e32 v4, v137, v4
	v_cvt_pk_bf16_f32 v4, v4, s0
	global_store_short v[150:151], v4, off
	s_waitcnt vmcnt(42)
	v_lshlrev_b32_e32 v4, 16, v205
	v_mov_b32_e32 v233, v1
	v_or_b32_e32 v231,0xe000,v3
	v_add_u32_e32 v232,v231,v2
	v_lshl_add_u64 v[234:235],v[232:233],1,s[18:19]
	global_load_ushort v205, v[234:235], off
	v_mul_f32_e32 v4, v138, v4
	v_cvt_pk_bf16_f32 v4, v4, s0
	global_store_short v[152:153], v4, off
	s_waitcnt vmcnt(43)
	v_lshlrev_b32_e32 v4, 16, v206
	v_mov_b32_e32 v233, v1
	v_or_b32_e32 v231,0xe400,v3
	v_add_u32_e32 v232,v231,v2
	v_lshl_add_u64 v[234:235],v[232:233],1,s[18:19]
	global_load_ushort v206, v[234:235], off
	v_mul_f32_e32 v4, v139, v4
	v_cvt_pk_bf16_f32 v4, v4, s0
	global_store_short v[154:155], v4, off
	s_waitcnt vmcnt(44)
	v_lshlrev_b32_e32 v4, 16, v207
	v_mov_b32_e32 v233, v1
	v_or_b32_e32 v231,0xe800,v3
	v_add_u32_e32 v232,v231,v2
	v_lshl_add_u64 v[234:235],v[232:233],1,s[18:19]
	global_load_ushort v207, v[234:235], off
	v_mul_f32_e32 v4, v140, v4
	v_cvt_pk_bf16_f32 v4, v4, s0
	global_store_short v[156:157], v4, off
	s_waitcnt vmcnt(45)
	v_lshlrev_b32_e32 v4, 16, v209
	v_mov_b32_e32 v233, v1
	v_or_b32_e32 v231,0xec00,v3
	v_add_u32_e32 v232,v231,v2
	v_lshl_add_u64 v[234:235],v[232:233],1,s[18:19]
	global_load_ushort v209, v[234:235], off
	v_mul_f32_e32 v4, v141, v4
	v_cvt_pk_bf16_f32 v4, v4, s0
	global_store_short v[158:159], v4, off
	s_waitcnt vmcnt(46)
	v_lshlrev_b32_e32 v4, 16, v210
	v_mov_b32_e32 v233, v1
	v_add_u32_e32 v230,32,v2
	v_or_b32_e32 v231,0x8000,v3
	v_add_u32_e32 v232,v231,v230
	v_lshl_add_u64 v[234:235],v[232:233],1,s[18:19]
	global_load_ushort v210, v[234:235], off
	v_mul_f32_e32 v4, v142, v4
	s_waitcnt vmcnt(46)
	v_lshlrev_b32_e32 v0, 16, v211
	v_mov_b32_e32 v235, v1
	v_add_u32_e32 v230,32,v2
	v_or_b32_e32 v232,0x8400,v3
	v_add_u32_e32 v234,v232,v230
	v_lshl_add_u64 v[236:237],v[234:235],1,s[18:19]
	global_load_ushort v211, v[236:237], off
	v_cvt_pk_bf16_f32 v4, v4, s0
	v_mul_f32_e32 v0, v143, v0
	global_store_short v[160:161], v4, off
	v_cvt_pk_bf16_f32 v0, v0, s0
	v_add_u32_e32 v4, 32, v2
	global_store_short v[162:163], v0, off
	v_add_u32_e32 v0, v3, v4
	v_cvt_pk_bf16_f32 v128, v128, s0
	v_lshl_add_u64 v[8:9], v[0:1], 1, s[18:19]
	v_add_u32_e32 v0, v164, v4
	global_store_short v[6:7], v128, off
	v_lshl_add_u64 v[6:7], v[0:1], 1, s[18:19]
	v_add_u32_e32 v0, v167, v4
	v_lshl_add_u64 v[10:11], v[0:1], 1, s[18:19]
	v_add_u32_e32 v0, v169, v4
	v_lshl_add_u64 v[12:13], v[0:1], 1, s[18:19]
	v_add_u32_e32 v0, v171, v4
	v_lshl_add_u64 v[14:15], v[0:1], 1, s[18:19]
	v_add_u32_e32 v0, v173, v4
	v_lshl_add_u64 v[128:129], v[0:1], 1, s[18:19]
	v_add_u32_e32 v0, v175, v4
	v_lshl_add_u64 v[130:131], v[0:1], 1, s[18:19]
	v_add_u32_e32 v0, v177, v4
	v_lshl_add_u64 v[132:133], v[0:1], 1, s[18:19]
	v_add_u32_e32 v0, v179, v4
	v_lshl_add_u64 v[134:135], v[0:1], 1, s[18:19]
	v_add_u32_e32 v0, v181, v4
	v_lshl_add_u64 v[136:137], v[0:1], 1, s[18:19]
	v_add_u32_e32 v0, v183, v4
	v_lshl_add_u64 v[138:139], v[0:1], 1, s[18:19]
	v_add_u32_e32 v0, v185, v4
	v_lshl_add_u64 v[140:141], v[0:1], 1, s[18:19]
	v_add_u32_e32 v0, v187, v4
	v_lshl_add_u64 v[142:143], v[0:1], 1, s[18:19]
	v_add_u32_e32 v0, v189, v4
	v_lshl_add_u64 v[144:145], v[0:1], 1, s[18:19]
	v_add_u32_e32 v0, v191, v4
	v_lshl_add_u64 v[146:147], v[0:1], 1, s[18:19]
	v_add_u32_e32 v0, v193, v4
	v_lshl_add_u64 v[148:149], v[0:1], 1, s[18:19]
	s_waitcnt vmcnt(49)
	v_lshlrev_b32_e32 v5, 16, v212
	v_mov_b32_e32 v233, v1
	v_or_b32_e32 v231,0x8800,v3
	v_add_u32_e32 v232,v231,v4
	v_lshl_add_u64 v[234:235],v[232:233],1,s[18:19]
	global_load_ushort v212, v[234:235], off
	v_mul_f32_e32 v5, v112, v5
	v_cvt_pk_bf16_f32 v5, v5, s0
	global_store_short v[8:9], v5, off
	s_waitcnt vmcnt(44)
	v_lshlrev_b32_e32 v5, 16, v219
	v_mov_b32_e32 v233, v1
	v_or_b32_e32 v231,0x8c00,v3
	v_add_u32_e32 v232,v231,v4
	v_lshl_add_u64 v[234:235],v[232:233],1,s[18:19]
	global_load_ushort v219, v[234:235], off
	v_mul_f32_e32 v5, v113, v5
	v_cvt_pk_bf16_f32 v5, v5, s0
	global_store_short v[6:7], v5, off
	v_lshlrev_b32_e32 v5, 16, v213
	v_mov_b32_e32 v233, v1
	v_or_b32_e32 v231,0xa000,v3
	v_add_u32_e32 v232,v231,v4
	v_lshl_add_u64 v[234:235],v[232:233],1,s[18:19]
	global_load_ushort v213, v[234:235], off
	v_mul_f32_e32 v5, v114, v5
	v_cvt_pk_bf16_f32 v5, v5, s0
	global_store_short v[10:11], v5, off
	v_lshlrev_b32_e32 v5, 16, v214
	v_mov_b32_e32 v233, v1
	v_or_b32_e32 v231,0xa400,v3
	v_add_u32_e32 v232,v231,v4
	v_lshl_add_u64 v[234:235],v[232:233],1,s[18:19]
	global_load_ushort v214, v[234:235], off
	v_mul_f32_e32 v5, v115, v5
	v_cvt_pk_bf16_f32 v5, v5, s0
	global_store_short v[12:13], v5, off
	v_lshlrev_b32_e32 v5, 16, v215
	v_mov_b32_e32 v233, v1
	v_or_b32_e32 v231,0xa800,v3
	v_add_u32_e32 v232,v231,v4
	v_lshl_add_u64 v[234:235],v[232:233],1,s[18:19]
	global_load_ushort v215, v[234:235], off
	v_mul_f32_e32 v5, v116, v5
	v_cvt_pk_bf16_f32 v5, v5, s0
	global_store_short v[14:15], v5, off
	v_lshlrev_b32_e32 v5, 16, v216
	v_mov_b32_e32 v233, v1
	v_or_b32_e32 v231,0xac00,v3
	v_add_u32_e32 v232,v231,v4
	v_lshl_add_u64 v[234:235],v[232:233],1,s[18:19]
	global_load_ushort v216, v[234:235], off
	v_mul_f32_e32 v5, v117, v5
	v_cvt_pk_bf16_f32 v5, v5, s0
	global_store_short v[128:129], v5, off
	v_lshlrev_b32_e32 v5, 16, v217
	v_mov_b32_e32 v233, v1
	v_or_b32_e32 v231,0xc000,v3
	v_add_u32_e32 v232,v231,v4
	v_lshl_add_u64 v[234:235],v[232:233],1,s[18:19]
	global_load_ushort v217, v[234:235], off
	v_mul_f32_e32 v5, v118, v5
	v_cvt_pk_bf16_f32 v5, v5, s0
	global_store_short v[130:131], v5, off
	v_lshlrev_b32_e32 v5, 16, v218
	v_mov_b32_e32 v233, v1
	v_or_b32_e32 v231,0xc400,v3
	v_add_u32_e32 v232,v231,v4
	v_lshl_add_u64 v[234:235],v[232:233],1,s[18:19]
	global_load_ushort v218, v[234:235], off
	v_mul_f32_e32 v5, v119, v5
	v_cvt_pk_bf16_f32 v5, v5, s0
	global_store_short v[132:133], v5, off
	s_waitcnt vmcnt(57)
	v_lshlrev_b32_e32 v5, 16, v220
	v_mov_b32_e32 v233, v1
	v_or_b32_e32 v231,0xc800,v3
	v_add_u32_e32 v232,v231,v4
	v_lshl_add_u64 v[234:235],v[232:233],1,s[18:19]
	global_load_ushort v220, v[234:235], off
	v_mul_f32_e32 v5, v120, v5
	v_cvt_pk_bf16_f32 v5, v5, s0
	global_store_short v[134:135], v5, off
	s_waitcnt vmcnt(58)
	v_lshlrev_b32_e32 v5, 16, v221
	v_mov_b32_e32 v233, v1
	v_or_b32_e32 v231,0xcc00,v3
	v_add_u32_e32 v232,v231,v4
	v_lshl_add_u64 v[234:235],v[232:233],1,s[18:19]
	global_load_ushort v221, v[234:235], off
	v_mul_f32_e32 v5, v121, v5
	v_cvt_pk_bf16_f32 v5, v5, s0
	global_store_short v[136:137], v5, off
	s_waitcnt vmcnt(59)
	v_lshlrev_b32_e32 v5, 16, v222
	v_mov_b32_e32 v233, v1
	v_or_b32_e32 v231,0xe000,v3
	v_add_u32_e32 v232,v231,v4
	v_lshl_add_u64 v[234:235],v[232:233],1,s[18:19]
	global_load_ushort v222, v[234:235], off
	v_mul_f32_e32 v5, v122, v5
	v_cvt_pk_bf16_f32 v5, v5, s0
	global_store_short v[138:139], v5, off
	s_waitcnt vmcnt(60)
	v_lshlrev_b32_e32 v5, 16, v223
	v_mov_b32_e32 v233, v1
	v_or_b32_e32 v231,0xe400,v3
	v_add_u32_e32 v232,v231,v4
	v_lshl_add_u64 v[234:235],v[232:233],1,s[18:19]
	global_load_ushort v223, v[234:235], off
	v_mul_f32_e32 v5, v123, v5
	v_cvt_pk_bf16_f32 v5, v5, s0
	global_store_short v[140:141], v5, off
	s_waitcnt vmcnt(61)
	v_lshlrev_b32_e32 v5, 16, v224
	v_mov_b32_e32 v233, v1
	v_or_b32_e32 v231,0xe800,v3
	v_add_u32_e32 v232,v231,v4
	v_lshl_add_u64 v[234:235],v[232:233],1,s[18:19]
	global_load_ushort v224, v[234:235], off
	v_mul_f32_e32 v5, v124, v5
	v_cvt_pk_bf16_f32 v5, v5, s0
	s_waitcnt vmcnt(56)
	global_store_short v[142:143], v5, off
	v_lshlrev_b32_e32 v5, 16, v225
	v_mov_b32_e32 v233, v1
	v_or_b32_e32 v231,0xec00,v3
	v_add_u32_e32 v232,v231,v4
	v_lshl_add_u64 v[234:235],v[232:233],1,s[18:19]
	global_load_ushort v225, v[234:235], off
	v_mul_f32_e32 v5, v125, v5
	v_cvt_pk_bf16_f32 v5, v5, s0
	global_store_short v[144:145], v5, off
	v_lshlrev_b32_e32 v5, 16, v226
	v_mov_b32_e32 v233, v1
	v_or_b32_e32 v231,0x10000,v3
	v_add_u32_e32 v232,v231,v2
	v_lshl_add_u64 v[234:235],v[232:233],1,s[18:19]
	global_load_ushort v226, v[234:235], off
	v_lshlrev_b32_e32 v0, 16, v227
	v_mov_b32_e32 v233, v1
	v_or_b32_e32 v230,0x10400,v3
	v_add_u32_e32 v232,v230,v2
	v_lshl_add_u64 v[234:235],v[232:233],1,s[18:19]
	global_load_ushort v227, v[234:235], off
	v_mul_f32_e32 v5, v126, v5
	v_mul_f32_e32 v0, v127, v0
	v_cvt_pk_bf16_f32 v5, v5, s0
	v_cvt_pk_bf16_f32 v0, v0, s0
	global_store_short v[146:147], v5, off
	s_waitcnt vmcnt(56)
	global_store_short v[148:149], v0, off
	v_or_b32_e32 v5, 0x8000, v3
	v_add_u32_e32 v0, v5, v2
	v_or_b32_e32 v134, 0x8400, v3
	v_lshl_add_u64 v[6:7], v[0:1], 1, s[18:19]
	v_add_u32_e32 v0, v134, v2
	v_or_b32_e32 v137, 0x8800, v3
	v_lshl_add_u64 v[8:9], v[0:1], 1, s[18:19]
	v_add_u32_e32 v0, v137, v2
	v_or_b32_e32 v139, 0x8c00, v3
	v_lshl_add_u64 v[10:11], v[0:1], 1, s[18:19]
	v_add_u32_e32 v0, v139, v2
	v_or_b32_e32 v141, 0xa000, v3
	v_lshl_add_u64 v[12:13], v[0:1], 1, s[18:19]
	v_add_u32_e32 v0, v141, v2
	v_or_b32_e32 v143, 0xa400, v3
	v_lshl_add_u64 v[14:15], v[0:1], 1, s[18:19]
	v_add_u32_e32 v0, v143, v2
	v_or_b32_e32 v145, 0xa800, v3
	v_lshl_add_u64 v[112:113], v[0:1], 1, s[18:19]
	v_add_u32_e32 v0, v145, v2
	v_lshl_add_u64 v[114:115], v[0:1], 1, s[18:19]
	v_or_b32_e32 v147, 0xac00, v3
	v_add_u32_e32 v0, v147, v2
	v_lshl_add_u64 v[116:117], v[0:1], 1, s[18:19]
	v_or_b32_e32 v149, 0xc000, v3
	v_add_u32_e32 v0, v149, v2
	v_lshl_add_u64 v[118:119], v[0:1], 1, s[18:19]
	v_or_b32_e32 v151, 0xc400, v3
	v_add_u32_e32 v0, v151, v2
	v_lshl_add_u64 v[120:121], v[0:1], 1, s[18:19]
	v_or_b32_e32 v153, 0xc800, v3
	v_add_u32_e32 v0, v153, v2
	v_lshl_add_u64 v[122:123], v[0:1], 1, s[18:19]
	v_or_b32_e32 v155, 0xcc00, v3
	v_add_u32_e32 v0, v155, v2
	v_lshl_add_u64 v[124:125], v[0:1], 1, s[18:19]
	v_or_b32_e32 v157, 0xe000, v3
	v_add_u32_e32 v0, v157, v2
	v_lshl_add_u64 v[126:127], v[0:1], 1, s[18:19]
	v_or_b32_e32 v159, 0xe400, v3
	v_add_u32_e32 v0, v159, v2
	v_or_b32_e32 v161, 0xe800, v3
	v_lshl_add_u64 v[128:129], v[0:1], 1, s[18:19]
	v_add_u32_e32 v0, v161, v2
	v_or_b32_e32 v163, 0xec00, v3
	v_lshl_add_u64 v[130:131], v[0:1], 1, s[18:19]
	v_add_u32_e32 v0, v163, v2
	v_lshl_add_u64 v[132:133], v[0:1], 1, s[18:19]
	v_lshlrev_b32_e32 v135, 16, v228
	v_mov_b32_e32 v233, v1
	v_or_b32_e32 v231,0x10800,v3
	v_add_u32_e32 v232,v231,v2
	v_lshl_add_u64 v[234:235],v[232:233],1,s[18:19]
	global_load_ushort v228, v[234:235], off
	v_mul_f32_e32 v80, v80, v135
	v_lshlrev_b32_e32 v135, 16, v229
	v_mov_b32_e32 v233, v1
	v_or_b32_e32 v231,0x10c00,v3
	v_add_u32_e32 v232,v231,v2
	v_lshl_add_u64 v[234:235],v[232:233],1,s[18:19]
	global_load_ushort v229, v[234:235], off
	v_cvt_pk_bf16_f32 v80, v80, s0
	v_mul_f32_e32 v81, v81, v135
	v_lshlrev_b32_e32 v135, 16, v194
	v_mov_b32_e32 v233, v1
	v_or_b32_e32 v231,0x12000,v3
	v_add_u32_e32 v232,v231,v2
	v_lshl_add_u64 v[234:235],v[232:233],1,s[18:19]
	global_load_ushort v194, v[234:235], off
	global_store_short v[6:7], v80, off
	v_cvt_pk_bf16_f32 v6, v81, s0
	v_mul_f32_e32 v7, v82, v135
	v_lshlrev_b32_e32 v80, 16, v195
	v_mov_b32_e32 v233, v1
	v_or_b32_e32 v231,0x12400,v3
	v_add_u32_e32 v232,v231,v2
	v_lshl_add_u64 v[234:235],v[232:233],1,s[18:19]
	global_load_ushort v195, v[234:235], off
	s_waitcnt vmcnt(56)
	global_store_short v[8:9], v6, off
	v_cvt_pk_bf16_f32 v6, v7, s0
	v_mul_f32_e32 v7, v83, v80
	v_lshlrev_b32_e32 v8, 16, v196
	v_mov_b32_e32 v233, v1
	v_or_b32_e32 v231,0x12800,v3
	v_add_u32_e32 v232,v231,v2
	v_lshl_add_u64 v[234:235],v[232:233],1,s[18:19]
	global_load_ushort v196, v[234:235], off
	global_store_short v[10:11], v6, off
	v_cvt_pk_bf16_f32 v6, v7, s0
	v_mul_f32_e32 v7, v84, v8
	v_lshlrev_b32_e32 v8, 16, v197
	v_mov_b32_e32 v233, v1
	v_or_b32_e32 v231,0x12c00,v3
	v_add_u32_e32 v232,v231,v2
	v_lshl_add_u64 v[234:235],v[232:233],1,s[18:19]
	global_load_ushort v197, v[234:235], off
	global_store_short v[12:13], v6, off
	v_cvt_pk_bf16_f32 v6, v7, s0
	v_mul_f32_e32 v7, v85, v8
	v_lshlrev_b32_e32 v8, 16, v198
	v_mov_b32_e32 v233, v1
	v_or_b32_e32 v231,0x14000,v3
	v_add_u32_e32 v232,v231,v2
	v_lshl_add_u64 v[234:235],v[232:233],1,s[18:19]
	global_load_ushort v198, v[234:235], off
	s_waitcnt vmcnt(56)
	global_store_short v[14:15], v6, off
	v_cvt_pk_bf16_f32 v6, v7, s0
	v_mul_f32_e32 v7, v86, v8
	v_lshlrev_b32_e32 v8, 16, v199
	v_mov_b32_e32 v233, v1
	v_or_b32_e32 v231,0x14400,v3
	v_add_u32_e32 v232,v231,v2
	v_lshl_add_u64 v[234:235],v[232:233],1,s[18:19]
	global_load_ushort v199, v[234:235], off
	global_store_short v[112:113], v6, off
	v_cvt_pk_bf16_f32 v6, v7, s0
	global_store_short v[114:115], v6, off
	v_mul_f32_e32 v6, v87, v8
	v_cvt_pk_bf16_f32 v6, v6, s0
	global_store_short v[116:117], v6, off
	v_lshlrev_b32_e32 v6, 16, v201
	v_mov_b32_e32 v233, v1
	v_or_b32_e32 v231,0x14800,v3
	v_add_u32_e32 v232,v231,v2
	v_lshl_add_u64 v[234:235],v[232:233],1,s[18:19]
	global_load_ushort v201, v[234:235], off
	v_mul_f32_e32 v6, v88, v6
	v_cvt_pk_bf16_f32 v6, v6, s0
	s_waitcnt vmcnt(56)
	global_store_short v[118:119], v6, off
	v_lshlrev_b32_e32 v6, 16, v202
	v_mov_b32_e32 v233, v1
	v_or_b32_e32 v231,0x14c00,v3
	v_add_u32_e32 v232,v231,v2
	v_lshl_add_u64 v[234:235],v[232:233],1,s[18:19]
	global_load_ushort v202, v[234:235], off
	v_mul_f32_e32 v6, v89, v6
	v_cvt_pk_bf16_f32 v6, v6, s0
	global_store_short v[120:121], v6, off
	v_lshlrev_b32_e32 v6, 16, v203
	v_mov_b32_e32 v233, v1
	v_or_b32_e32 v231,0x16000,v3
	v_add_u32_e32 v232,v231,v2
	v_lshl_add_u64 v[234:235],v[232:233],1,s[18:19]
	global_load_ushort v203, v[234:235], off
	v_mul_f32_e32 v6, v90, v6
	v_cvt_pk_bf16_f32 v6, v6, s0
	global_store_short v[122:123], v6, off
	v_lshlrev_b32_e32 v6, 16, v204
	v_mov_b32_e32 v233, v1
	v_or_b32_e32 v231,0x16400,v3
	v_add_u32_e32 v232,v231,v2
	v_lshl_add_u64 v[234:235],v[232:233],1,s[18:19]
	global_load_ushort v204, v[234:235], off
	v_mul_f32_e32 v6, v91, v6
	v_cvt_pk_bf16_f32 v6, v6, s0
	s_waitcnt vmcnt(56)
	global_store_short v[124:125], v6, off
	v_lshlrev_b32_e32 v6, 16, v205
	v_mov_b32_e32 v233, v1
	v_or_b32_e32 v231,0x16800,v3
	v_add_u32_e32 v232,v231,v2
	v_lshl_add_u64 v[234:235],v[232:233],1,s[18:19]
	global_load_ushort v205, v[234:235], off
	v_mul_f32_e32 v6, v92, v6
	v_cvt_pk_bf16_f32 v6, v6, s0
	global_store_short v[126:127], v6, off
	v_lshlrev_b32_e32 v6, 16, v206
	v_mov_b32_e32 v233, v1
	v_or_b32_e32 v231,0x16c00,v3
	v_add_u32_e32 v232,v231,v2
	v_lshl_add_u64 v[234:235],v[232:233],1,s[18:19]
	global_load_ushort v206, v[234:235], off
	v_mul_f32_e32 v6, v93, v6
	v_cvt_pk_bf16_f32 v6, v6, s0
	v_lshlrev_b32_e32 v0, 16, v209
	v_mov_b32_e32 v233, v1
	v_or_b32_e32 v231,0x10000,v3
	v_add_u32_e32 v232,v231,v4
	v_lshl_add_u64 v[234:235],v[232:233],1,s[18:19]
	global_load_ushort v209, v[234:235], off
	global_store_short v[128:129], v6, off
	v_lshlrev_b32_e32 v6, 16, v207
	v_mov_b32_e32 v233, v1
	v_or_b32_e32 v230,0x10400,v3
	v_add_u32_e32 v232,v230,v4
	v_lshl_add_u64 v[234:235],v[232:233],1,s[18:19]
	s_waitcnt vmcnt(56)
	global_load_ushort v207, v[234:235], off
	v_mul_f32_e32 v0, v95, v0
	v_mul_f32_e32 v6, v94, v6
	v_cvt_pk_bf16_f32 v0, v0, s0
	v_cvt_pk_bf16_f32 v6, v6, s0
	global_store_short v[132:133], v0, off
	v_add_u32_e32 v0, v5, v4
	global_store_short v[130:131], v6, off
	v_lshl_add_u64 v[6:7], v[0:1], 1, s[18:19]
	v_add_u32_e32 v0, v134, v4
	v_lshl_add_u64 v[8:9], v[0:1], 1, s[18:19]
	v_add_u32_e32 v0, v137, v4
	v_lshl_add_u64 v[10:11], v[0:1], 1, s[18:19]
	v_add_u32_e32 v0, v139, v4
	v_lshl_add_u64 v[12:13], v[0:1], 1, s[18:19]
	v_add_u32_e32 v0, v141, v4
	v_lshl_add_u64 v[14:15], v[0:1], 1, s[18:19]
	v_add_u32_e32 v0, v143, v4
	v_lshl_add_u64 v[80:81], v[0:1], 1, s[18:19]
	v_add_u32_e32 v0, v145, v4
	v_lshl_add_u64 v[82:83], v[0:1], 1, s[18:19]
	v_add_u32_e32 v0, v147, v4
	v_lshl_add_u64 v[84:85], v[0:1], 1, s[18:19]
	v_add_u32_e32 v0, v149, v4
	v_lshl_add_u64 v[86:87], v[0:1], 1, s[18:19]
	v_add_u32_e32 v0, v151, v4
	v_lshl_add_u64 v[88:89], v[0:1], 1, s[18:19]
	v_add_u32_e32 v0, v153, v4
	v_lshl_add_u64 v[90:91], v[0:1], 1, s[18:19]
	v_add_u32_e32 v0, v155, v4
	v_lshl_add_u64 v[92:93], v[0:1], 1, s[18:19]
	v_add_u32_e32 v0, v157, v4
	v_lshl_add_u64 v[94:95], v[0:1], 1, s[18:19]
	v_add_u32_e32 v0, v159, v4
	v_lshl_add_u64 v[112:113], v[0:1], 1, s[18:19]
	v_add_u32_e32 v0, v161, v4
	v_lshl_add_u64 v[114:115], v[0:1], 1, s[18:19]
	v_add_u32_e32 v0, v163, v4
	v_lshl_add_u64 v[116:117], v[0:1], 1, s[18:19]
	v_lshlrev_b32_e32 v5, 16, v210
	v_mov_b32_e32 v233, v1
	v_or_b32_e32 v231,0x10800,v3
	v_add_u32_e32 v232,v231,v4
	v_lshl_add_u64 v[234:235],v[232:233],1,s[18:19]
	global_load_ushort v210, v[234:235], off
	v_lshlrev_b32_e32 v118, 16, v211
	v_mov_b32_e32 v233, v1
	v_or_b32_e32 v231,0x10c00,v3
	v_add_u32_e32 v232,v231,v4
	v_lshl_add_u64 v[234:235],v[232:233],1,s[18:19]
	global_load_ushort v211, v[234:235], off
	v_lshlrev_b32_e32 v119, 16, v212
	v_mov_b32_e32 v233, v1
	v_or_b32_e32 v231,0x12000,v3
	v_add_u32_e32 v232,v231,v4
	v_lshl_add_u64 v[234:235],v[232:233],1,s[18:19]
	global_load_ushort v212, v[234:235], off
	v_mul_f32_e32 v5, v48, v5
	v_mul_f32_e32 v48, v49, v118
	v_mul_f32_e32 v49, v50, v119
	v_cvt_pk_bf16_f32 v5, v5, s0
	v_cvt_pk_bf16_f32 v48, v48, s0
	s_waitcnt vmcnt(56)
	global_store_short v[6:7], v5, off
	global_store_short v[8:9], v48, off
	v_cvt_pk_bf16_f32 v5, v49, s0
	global_store_short v[10:11], v5, off
	v_lshlrev_b32_e32 v5, 16, v219
	v_mov_b32_e32 v233, v1
	v_or_b32_e32 v231,0x12400,v3
	v_add_u32_e32 v232,v231,v4
	v_lshl_add_u64 v[234:235],v[232:233],1,s[18:19]
	global_load_ushort v219, v[234:235], off
	v_mul_f32_e32 v5, v51, v5
	v_cvt_pk_bf16_f32 v5, v5, s0
	global_store_short v[12:13], v5, off
	v_lshlrev_b32_e32 v5, 16, v213
	v_mov_b32_e32 v233, v1
	v_or_b32_e32 v231,0x12800,v3
	v_add_u32_e32 v232,v231,v4
	v_lshl_add_u64 v[234:235],v[232:233],1,s[18:19]
	global_load_ushort v213, v[234:235], off
	v_mul_f32_e32 v5, v52, v5
	v_cvt_pk_bf16_f32 v5, v5, s0
	s_waitcnt vmcnt(56)
	global_store_short v[14:15], v5, off
	v_lshlrev_b32_e32 v5, 16, v214
	v_mov_b32_e32 v233, v1
	v_or_b32_e32 v231,0x12c00,v3
	v_add_u32_e32 v232,v231,v4
	v_lshl_add_u64 v[234:235],v[232:233],1,s[18:19]
	global_load_ushort v214, v[234:235], off
	v_mul_f32_e32 v5, v53, v5
	v_cvt_pk_bf16_f32 v5, v5, s0
	global_store_short v[80:81], v5, off
	v_lshlrev_b32_e32 v5, 16, v215
	v_mov_b32_e32 v233, v1
	v_or_b32_e32 v231,0x14000,v3
	v_add_u32_e32 v232,v231,v4
	v_lshl_add_u64 v[234:235],v[232:233],1,s[18:19]
	global_load_ushort v215, v[234:235], off
	v_mul_f32_e32 v5, v54, v5
	v_cvt_pk_bf16_f32 v5, v5, s0
	global_store_short v[82:83], v5, off
	v_lshlrev_b32_e32 v5, 16, v216
	v_mov_b32_e32 v233, v1
	v_or_b32_e32 v231,0x14400,v3
	v_add_u32_e32 v232,v231,v4
	v_lshl_add_u64 v[234:235],v[232:233],1,s[18:19]
	global_load_ushort v216, v[234:235], off
	v_mul_f32_e32 v5, v55, v5
	v_cvt_pk_bf16_f32 v5, v5, s0
	s_waitcnt vmcnt(56)
	global_store_short v[84:85], v5, off
	v_lshlrev_b32_e32 v5, 16, v217
	v_mov_b32_e32 v233, v1
	v_or_b32_e32 v231,0x14800,v3
	v_add_u32_e32 v232,v231,v4
	v_lshl_add_u64 v[234:235],v[232:233],1,s[18:19]
	global_load_ushort v217, v[234:235], off
	v_mul_f32_e32 v5, v56, v5
	v_cvt_pk_bf16_f32 v5, v5, s0
	global_store_short v[86:87], v5, off
	v_lshlrev_b32_e32 v5, 16, v218
	v_mov_b32_e32 v233, v1
	v_or_b32_e32 v231,0x14c00,v3
	v_add_u32_e32 v232,v231,v4
	v_lshl_add_u64 v[234:235],v[232:233],1,s[18:19]
	global_load_ushort v218, v[234:235], off
	v_mul_f32_e32 v5, v57, v5
	v_cvt_pk_bf16_f32 v5, v5, s0
	global_store_short v[88:89], v5, off
	v_lshlrev_b32_e32 v5, 16, v220
	v_mov_b32_e32 v233, v1
	v_or_b32_e32 v231,0x16000,v3
	v_add_u32_e32 v232,v231,v4
	v_lshl_add_u64 v[234:235],v[232:233],1,s[18:19]
	global_load_ushort v220, v[234:235], off
	v_mul_f32_e32 v5, v58, v5
	v_cvt_pk_bf16_f32 v5, v5, s0
	s_waitcnt vmcnt(56)
	global_store_short v[90:91], v5, off
	v_lshlrev_b32_e32 v5, 16, v221
	v_mov_b32_e32 v233, v1
	v_or_b32_e32 v231,0x16400,v3
	v_add_u32_e32 v232,v231,v4
	v_lshl_add_u64 v[234:235],v[232:233],1,s[18:19]
	global_load_ushort v221, v[234:235], off
	v_mul_f32_e32 v5, v59, v5
	v_cvt_pk_bf16_f32 v5, v5, s0
	global_store_short v[92:93], v5, off
	v_lshlrev_b32_e32 v5, 16, v222
	v_mov_b32_e32 v233, v1
	v_or_b32_e32 v231,0x16800,v3
	v_add_u32_e32 v232,v231,v4
	v_lshl_add_u64 v[234:235],v[232:233],1,s[18:19]
	global_load_ushort v222, v[234:235], off
	v_mul_f32_e32 v5, v60, v5
	v_cvt_pk_bf16_f32 v5, v5, s0
	global_store_short v[94:95], v5, off
	v_lshlrev_b32_e32 v5, 16, v223
	v_mov_b32_e32 v233, v1
	v_or_b32_e32 v231,0x16c00,v3
	v_add_u32_e32 v232,v231,v4
	v_lshl_add_u64 v[234:235],v[232:233],1,s[18:19]
	global_load_ushort v223, v[234:235], off
	v_mul_f32_e32 v5, v61, v5
	v_cvt_pk_bf16_f32 v5, v5, s0
	s_waitcnt vmcnt(56)
	global_store_short v[112:113], v5, off
	v_lshlrev_b32_e32 v5, 16, v224
	v_mov_b32_e32 v233, v1
	v_or_b32_e32 v231,0x18000,v3
	v_add_u32_e32 v232,v231,v2
	v_lshl_add_u64 v[234:235],v[232:233],1,s[18:19]
	global_load_ushort v224, v[234:235], off
	v_lshlrev_b32_e32 v0, 16, v225
	v_mov_b32_e32 v233, v1
	v_or_b32_e32 v230,0x18400,v3
	v_add_u32_e32 v232,v230,v2
	v_lshl_add_u64 v[234:235],v[232:233],1,s[18:19]
	global_load_ushort v225, v[234:235], off
	v_mul_f32_e32 v5, v62, v5
	v_mul_f32_e32 v0, v63, v0
	v_cvt_pk_bf16_f32 v5, v5, s0
	v_cvt_pk_bf16_f32 v0, v0, s0
	global_store_short v[114:115], v5, off
	global_store_short v[116:117], v0, off
	v_or_b32_e32 v5, 0x10000, v3
	v_add_u32_e32 v0, v5, v2
	v_or_b32_e32 v86, 0x10400, v3
	v_lshl_add_u64 v[6:7], v[0:1], 1, s[18:19]
	v_add_u32_e32 v0, v86, v2
	v_or_b32_e32 v89, 0x10800, v3
	v_lshl_add_u64 v[8:9], v[0:1], 1, s[18:19]
	v_add_u32_e32 v0, v89, v2
	v_or_b32_e32 v91, 0x10c00, v3
	v_lshl_add_u64 v[10:11], v[0:1], 1, s[18:19]
	v_add_u32_e32 v0, v91, v2
	v_or_b32_e32 v93, 0x12000, v3
	v_lshl_add_u64 v[12:13], v[0:1], 1, s[18:19]
	v_add_u32_e32 v0, v93, v2
	v_or_b32_e32 v95, 0x12400, v3
	v_lshl_add_u64 v[14:15], v[0:1], 1, s[18:19]
	v_add_u32_e32 v0, v95, v2
	v_or_b32_e32 v113, 0x12800, v3
	v_lshl_add_u64 v[48:49], v[0:1], 1, s[18:19]
	v_add_u32_e32 v0, v113, v2
	v_lshl_add_u64 v[50:51], v[0:1], 1, s[18:19]
	v_or_b32_e32 v115, 0x12c00, v3
	v_add_u32_e32 v0, v115, v2
	v_lshl_add_u64 v[52:53], v[0:1], 1, s[18:19]
	v_or_b32_e32 v117, 0x14000, v3
	v_add_u32_e32 v0, v117, v2
	v_lshl_add_u64 v[54:55], v[0:1], 1, s[18:19]
	v_or_b32_e32 v119, 0x14400, v3
	v_add_u32_e32 v0, v119, v2
	v_lshl_add_u64 v[56:57], v[0:1], 1, s[18:19]
	v_or_b32_e32 v121, 0x14800, v3
	v_add_u32_e32 v0, v121, v2
	v_lshl_add_u64 v[58:59], v[0:1], 1, s[18:19]
	v_or_b32_e32 v123, 0x14c00, v3
	v_add_u32_e32 v0, v123, v2
	v_lshl_add_u64 v[60:61], v[0:1], 1, s[18:19]
	v_or_b32_e32 v125, 0x16000, v3
	v_add_u32_e32 v0, v125, v2
	v_lshl_add_u64 v[62:63], v[0:1], 1, s[18:19]
	v_or_b32_e32 v127, 0x16400, v3
	v_add_u32_e32 v0, v127, v2
	v_or_b32_e32 v129, 0x16800, v3
	v_lshl_add_u64 v[80:81], v[0:1], 1, s[18:19]
	v_add_u32_e32 v0, v129, v2
	v_or_b32_e32 v131, 0x16c00, v3
	v_lshl_add_u64 v[82:83], v[0:1], 1, s[18:19]
	v_add_u32_e32 v0, v131, v2
	v_lshl_add_u64 v[84:85], v[0:1], 1, s[18:19]
	v_lshlrev_b32_e32 v87, 16, v226
	v_mov_b32_e32 v233, v1
	v_or_b32_e32 v231,0x18800,v3
	v_add_u32_e32 v232,v231,v2
	v_lshl_add_u64 v[234:235],v[232:233],1,s[18:19]
	global_load_ushort v226, v[234:235], off
	v_mul_f32_e32 v87, v96, v87
	v_lshlrev_b32_e32 v88, 16, v227
	v_mov_b32_e32 v233, v1
	v_or_b32_e32 v231,0x18c00,v3
	v_add_u32_e32 v232,v231,v2
	v_lshl_add_u64 v[234:235],v[232:233],1,s[18:19]
	s_waitcnt vmcnt(56)
	global_load_ushort v227, v[234:235], off
	v_cvt_pk_bf16_f32 v87, v87, s0
	v_mul_f32_e32 v88, v97, v88
	v_lshlrev_b32_e32 v90, 16, v228
	v_mov_b32_e32 v233, v1
	v_or_b32_e32 v231,0x1a000,v3
	v_add_u32_e32 v232,v231,v2
	v_lshl_add_u64 v[234:235],v[232:233],1,s[18:19]
	global_load_ushort v228, v[234:235], off
	global_store_short v[6:7], v87, off
	v_cvt_pk_bf16_f32 v6, v88, s0
	v_mul_f32_e32 v7, v98, v90
	v_lshlrev_b32_e32 v87, 16, v229
	v_mov_b32_e32 v233, v1
	v_or_b32_e32 v231,0x1a400,v3
	v_add_u32_e32 v232,v231,v2
	v_lshl_add_u64 v[234:235],v[232:233],1,s[18:19]
	global_load_ushort v229, v[234:235], off
	global_store_short v[8:9], v6, off
	v_cvt_pk_bf16_f32 v6, v7, s0
	v_mul_f32_e32 v7, v99, v87
	v_lshlrev_b32_e32 v8, 16, v194
	v_mov_b32_e32 v233, v1
	v_or_b32_e32 v231,0x1a800,v3
	v_add_u32_e32 v232,v231,v2
	v_lshl_add_u64 v[234:235],v[232:233],1,s[18:19]
	global_load_ushort v194, v[234:235], off
	s_waitcnt vmcnt(56)
	global_store_short v[10:11], v6, off
	v_cvt_pk_bf16_f32 v6, v7, s0
	v_mul_f32_e32 v7, v100, v8
	v_lshlrev_b32_e32 v8, 16, v195
	v_mov_b32_e32 v233, v1
	v_or_b32_e32 v231,0x1ac00,v3
	v_add_u32_e32 v232,v231,v2
	v_lshl_add_u64 v[234:235],v[232:233],1,s[18:19]
	global_load_ushort v195, v[234:235], off
	global_store_short v[12:13], v6, off
	v_cvt_pk_bf16_f32 v6, v7, s0
	v_mul_f32_e32 v7, v101, v8
	v_lshlrev_b32_e32 v8, 16, v196
	v_mov_b32_e32 v233, v1
	v_or_b32_e32 v231,0x1c000,v3
	v_add_u32_e32 v232,v231,v2
	v_lshl_add_u64 v[234:235],v[232:233],1,s[18:19]
	global_load_ushort v196, v[234:235], off
	global_store_short v[14:15], v6, off
	v_cvt_pk_bf16_f32 v6, v7, s0
	v_mul_f32_e32 v7, v102, v8
	v_lshlrev_b32_e32 v8, 16, v197
	v_mov_b32_e32 v233, v1
	v_or_b32_e32 v231,0x1c400,v3
	v_add_u32_e32 v232,v231,v2
	v_lshl_add_u64 v[234:235],v[232:233],1,s[18:19]
	global_load_ushort v197, v[234:235], off
	s_waitcnt vmcnt(56)
	global_store_short v[48:49], v6, off
	v_cvt_pk_bf16_f32 v6, v7, s0
	global_store_short v[50:51], v6, off
	v_mul_f32_e32 v6, v103, v8
	v_cvt_pk_bf16_f32 v6, v6, s0
	global_store_short v[52:53], v6, off
	v_lshlrev_b32_e32 v6, 16, v198
	v_mov_b32_e32 v233, v1
	v_or_b32_e32 v231,0x1c800,v3
	v_add_u32_e32 v232,v231,v2
	v_lshl_add_u64 v[234:235],v[232:233],1,s[18:19]
	global_load_ushort v198, v[234:235], off
	v_mul_f32_e32 v6, v104, v6
	v_cvt_pk_bf16_f32 v6, v6, s0
	global_store_short v[54:55], v6, off
	v_lshlrev_b32_e32 v6, 16, v199
	v_mov_b32_e32 v233, v1
	v_or_b32_e32 v231,0x1cc00,v3
	v_add_u32_e32 v232,v231,v2
	v_lshl_add_u64 v[234:235],v[232:233],1,s[18:19]
	global_load_ushort v199, v[234:235], off
	v_mul_f32_e32 v6, v105, v6
	v_cvt_pk_bf16_f32 v6, v6, s0
	s_waitcnt vmcnt(56)
	global_store_short v[56:57], v6, off
	v_lshlrev_b32_e32 v6, 16, v201
	v_mov_b32_e32 v233, v1
	v_or_b32_e32 v231,0x1e000,v3
	v_add_u32_e32 v232,v231,v2
	v_lshl_add_u64 v[234:235],v[232:233],1,s[18:19]
	global_load_ushort v201, v[234:235], off
	v_mul_f32_e32 v6, v106, v6
	v_cvt_pk_bf16_f32 v6, v6, s0
	global_store_short v[58:59], v6, off
	v_lshlrev_b32_e32 v6, 16, v202
	v_mov_b32_e32 v233, v1
	v_or_b32_e32 v231,0x1e400,v3
	v_add_u32_e32 v232,v231,v2
	v_lshl_add_u64 v[234:235],v[232:233],1,s[18:19]
	global_load_ushort v202, v[234:235], off
	v_mul_f32_e32 v6, v107, v6
	v_cvt_pk_bf16_f32 v6, v6, s0
	global_store_short v[60:61], v6, off
	v_lshlrev_b32_e32 v6, 16, v203
	v_mov_b32_e32 v233, v1
	v_or_b32_e32 v231,0x1e800,v3
	v_add_u32_e32 v232,v231,v2
	v_lshl_add_u64 v[234:235],v[232:233],1,s[18:19]
	global_load_ushort v203, v[234:235], off
	v_mul_f32_e32 v6, v108, v6
	v_cvt_pk_bf16_f32 v6, v6, s0
	s_waitcnt vmcnt(56)
	global_store_short v[62:63], v6, off
	v_lshlrev_b32_e32 v6, 16, v204
	v_mov_b32_e32 v233, v1
	v_or_b32_e32 v231,0x1ec00,v3
	v_add_u32_e32 v232,v231,v2
	v_lshl_add_u64 v[234:235],v[232:233],1,s[18:19]
	global_load_ushort v204, v[234:235], off
	v_mul_f32_e32 v6, v109, v6
	v_cvt_pk_bf16_f32 v6, v6, s0
	v_lshlrev_b32_e32 v0, 16, v206
	v_mov_b32_e32 v233, v1
	v_or_b32_e32 v231,0x18000,v3
	v_add_u32_e32 v232,v231,v4
	v_lshl_add_u64 v[234:235],v[232:233],1,s[18:19]
	global_load_ushort v206, v[234:235], off
	global_store_short v[80:81], v6, off
	v_lshlrev_b32_e32 v6, 16, v205
	v_mov_b32_e32 v233, v1
	v_or_b32_e32 v230,0x18400,v3
	v_add_u32_e32 v232,v230,v4
	v_lshl_add_u64 v[234:235],v[232:233],1,s[18:19]
	global_load_ushort v205, v[234:235], off
	v_mul_f32_e32 v0, v111, v0
	v_mul_f32_e32 v6, v110, v6
	v_cvt_pk_bf16_f32 v0, v0, s0
	v_cvt_pk_bf16_f32 v6, v6, s0
	global_store_short v[84:85], v0, off
	v_add_u32_e32 v0, v5, v4
	s_waitcnt vmcnt(56)
	global_store_short v[82:83], v6, off
	v_lshl_add_u64 v[6:7], v[0:1], 1, s[18:19]
	v_add_u32_e32 v0, v86, v4
	v_lshl_add_u64 v[8:9], v[0:1], 1, s[18:19]
	v_add_u32_e32 v0, v89, v4
	v_lshl_add_u64 v[10:11], v[0:1], 1, s[18:19]
	v_add_u32_e32 v0, v91, v4
	v_lshl_add_u64 v[12:13], v[0:1], 1, s[18:19]
	v_add_u32_e32 v0, v93, v4
	v_lshl_add_u64 v[14:15], v[0:1], 1, s[18:19]
	v_add_u32_e32 v0, v95, v4
	v_lshl_add_u64 v[48:49], v[0:1], 1, s[18:19]
	v_add_u32_e32 v0, v113, v4
	v_lshl_add_u64 v[50:51], v[0:1], 1, s[18:19]
	v_add_u32_e32 v0, v115, v4
	v_lshl_add_u64 v[52:53], v[0:1], 1, s[18:19]
	v_add_u32_e32 v0, v117, v4
	v_lshl_add_u64 v[54:55], v[0:1], 1, s[18:19]
	v_add_u32_e32 v0, v119, v4
	v_lshl_add_u64 v[56:57], v[0:1], 1, s[18:19]
	v_add_u32_e32 v0, v121, v4
	v_lshl_add_u64 v[58:59], v[0:1], 1, s[18:19]
	v_add_u32_e32 v0, v123, v4
	v_lshl_add_u64 v[60:61], v[0:1], 1, s[18:19]
	v_add_u32_e32 v0, v125, v4
	v_lshl_add_u64 v[62:63], v[0:1], 1, s[18:19]
	v_add_u32_e32 v0, v127, v4
	v_lshl_add_u64 v[80:81], v[0:1], 1, s[18:19]
	v_add_u32_e32 v0, v129, v4
	v_lshl_add_u64 v[82:83], v[0:1], 1, s[18:19]
	v_add_u32_e32 v0, v131, v4
	v_lshl_add_u64 v[84:85], v[0:1], 1, s[18:19]
	v_lshlrev_b32_e32 v5, 16, v209
	v_mov_b32_e32 v233, v1
	v_or_b32_e32 v231,0x18800,v3
	v_add_u32_e32 v232,v231,v4
	v_lshl_add_u64 v[234:235],v[232:233],1,s[18:19]
	global_load_ushort v209, v[234:235], off
	v_lshlrev_b32_e32 v86, 16, v207
	v_mov_b32_e32 v233, v1
	v_or_b32_e32 v231,0x18c00,v3
	v_add_u32_e32 v232,v231,v4
	v_lshl_add_u64 v[234:235],v[232:233],1,s[18:19]
	global_load_ushort v207, v[234:235], off
	v_lshlrev_b32_e32 v87, 16, v210
	v_mov_b32_e32 v233, v1
	v_or_b32_e32 v231,0x1a000,v3
	v_add_u32_e32 v232,v231,v4
	v_lshl_add_u64 v[234:235],v[232:233],1,s[18:19]
	global_load_ushort v210, v[234:235], off
	v_mul_f32_e32 v5, v64, v5
	v_mul_f32_e32 v64, v65, v86
	v_mul_f32_e32 v65, v66, v87
	v_cvt_pk_bf16_f32 v5, v5, s0
	v_cvt_pk_bf16_f32 v64, v64, s0
	global_store_short v[6:7], v5, off
	global_store_short v[8:9], v64, off
	v_cvt_pk_bf16_f32 v5, v65, s0
	s_waitcnt vmcnt(56)
	global_store_short v[10:11], v5, off
	v_lshlrev_b32_e32 v5, 16, v211
	v_mov_b32_e32 v233, v1
	v_or_b32_e32 v231,0x1a400,v3
	v_add_u32_e32 v232,v231,v4
	v_lshl_add_u64 v[234:235],v[232:233],1,s[18:19]
	global_load_ushort v211, v[234:235], off
	v_mul_f32_e32 v5, v67, v5
	v_cvt_pk_bf16_f32 v5, v5, s0
	global_store_short v[12:13], v5, off
	v_lshlrev_b32_e32 v5, 16, v212
	v_mov_b32_e32 v233, v1
	v_or_b32_e32 v231,0x1a800,v3
	v_add_u32_e32 v232,v231,v4
	v_lshl_add_u64 v[234:235],v[232:233],1,s[18:19]
	global_load_ushort v212, v[234:235], off
	v_mul_f32_e32 v5, v68, v5
	v_cvt_pk_bf16_f32 v5, v5, s0
	global_store_short v[14:15], v5, off
	v_lshlrev_b32_e32 v5, 16, v219
	v_mov_b32_e32 v233, v1
	v_or_b32_e32 v231,0x1ac00,v3
	v_add_u32_e32 v232,v231,v4
	v_lshl_add_u64 v[234:235],v[232:233],1,s[18:19]
	global_load_ushort v219, v[234:235], off
	v_mul_f32_e32 v5, v69, v5
	v_cvt_pk_bf16_f32 v5, v5, s0
	s_waitcnt vmcnt(56)
	global_store_short v[48:49], v5, off
	v_lshlrev_b32_e32 v5, 16, v213
	v_mov_b32_e32 v233, v1
	v_or_b32_e32 v231,0x1c000,v3
	v_add_u32_e32 v232,v231,v4
	v_lshl_add_u64 v[234:235],v[232:233],1,s[18:19]
	global_load_ushort v213, v[234:235], off
	v_mul_f32_e32 v5, v70, v5
	v_cvt_pk_bf16_f32 v5, v5, s0
	global_store_short v[50:51], v5, off
	v_lshlrev_b32_e32 v5, 16, v214
	v_mov_b32_e32 v233, v1
	v_or_b32_e32 v231,0x1c400,v3
	v_add_u32_e32 v232,v231,v4
	v_lshl_add_u64 v[234:235],v[232:233],1,s[18:19]
	global_load_ushort v214, v[234:235], off
	v_mul_f32_e32 v5, v71, v5
	v_cvt_pk_bf16_f32 v5, v5, s0
	global_store_short v[52:53], v5, off
	v_lshlrev_b32_e32 v5, 16, v215
	v_mov_b32_e32 v233, v1
	v_or_b32_e32 v231,0x1c800,v3
	v_add_u32_e32 v232,v231,v4
	v_lshl_add_u64 v[234:235],v[232:233],1,s[18:19]
	global_load_ushort v215, v[234:235], off
	v_mul_f32_e32 v5, v72, v5
	v_cvt_pk_bf16_f32 v5, v5, s0
	s_waitcnt vmcnt(56)
	global_store_short v[54:55], v5, off
	v_lshlrev_b32_e32 v5, 16, v216
	v_mov_b32_e32 v233, v1
	v_or_b32_e32 v231,0x1cc00,v3
	v_add_u32_e32 v232,v231,v4
	v_lshl_add_u64 v[234:235],v[232:233],1,s[18:19]
	global_load_ushort v216, v[234:235], off
	v_mul_f32_e32 v5, v73, v5
	v_cvt_pk_bf16_f32 v5, v5, s0
	global_store_short v[56:57], v5, off
	v_lshlrev_b32_e32 v5, 16, v217
	v_mov_b32_e32 v233, v1
	v_or_b32_e32 v231,0x1e000,v3
	v_add_u32_e32 v232,v231,v4
	v_lshl_add_u64 v[234:235],v[232:233],1,s[18:19]
	global_load_ushort v217, v[234:235], off
	v_mul_f32_e32 v5, v74, v5
	v_cvt_pk_bf16_f32 v5, v5, s0
	global_store_short v[58:59], v5, off
	v_lshlrev_b32_e32 v5, 16, v218
	v_mov_b32_e32 v233, v1
	v_or_b32_e32 v231,0x1e400,v3
	v_add_u32_e32 v232,v231,v4
	v_lshl_add_u64 v[234:235],v[232:233],1,s[18:19]
	global_load_ushort v218, v[234:235], off
	v_mul_f32_e32 v5, v75, v5
	v_cvt_pk_bf16_f32 v5, v5, s0
	s_waitcnt vmcnt(56)
	global_store_short v[60:61], v5, off
	v_lshlrev_b32_e32 v5, 16, v220
	v_mov_b32_e32 v233, v1
	v_or_b32_e32 v231,0x1e800,v3
	v_add_u32_e32 v232,v231,v4
	v_lshl_add_u64 v[234:235],v[232:233],1,s[18:19]
	global_load_ushort v220, v[234:235], off
	v_mul_f32_e32 v5, v76, v5
	v_cvt_pk_bf16_f32 v5, v5, s0
	global_store_short v[62:63], v5, off
	v_lshlrev_b32_e32 v5, 16, v221
	v_mov_b32_e32 v233, v1
	v_or_b32_e32 v231,0x1ec00,v3
	v_add_u32_e32 v232,v231,v4
	v_lshl_add_u64 v[234:235],v[232:233],1,s[18:19]
	global_load_ushort v221, v[234:235], off
	v_mul_f32_e32 v5, v77, v5
	v_cvt_pk_bf16_f32 v5, v5, s0
	global_store_short v[80:81], v5, off
	v_lshlrev_b32_e32 v5, 16, v222
	v_lshlrev_b32_e32 v0, 16, v223
	v_mul_f32_e32 v5, v78, v5
	v_mul_f32_e32 v0, v79, v0
	v_cvt_pk_bf16_f32 v5, v5, s0
	v_cvt_pk_bf16_f32 v0, v0, s0
	global_store_short v[82:83], v5, off
	s_waitcnt vmcnt(56)
	global_store_short v[84:85], v0, off
	v_or_b32_e32 v5, 0x18000, v3
	v_add_u32_e32 v0, v5, v2
	v_or_b32_e32 v68, 0x18400, v3
	v_lshl_add_u64 v[6:7], v[0:1], 1, s[18:19]
	v_add_u32_e32 v0, v68, v2
	v_or_b32_e32 v71, 0x18800, v3
	v_lshl_add_u64 v[8:9], v[0:1], 1, s[18:19]
	v_add_u32_e32 v0, v71, v2
	v_or_b32_e32 v73, 0x18c00, v3
	v_lshl_add_u64 v[10:11], v[0:1], 1, s[18:19]
	v_add_u32_e32 v0, v73, v2
	v_or_b32_e32 v75, 0x1a000, v3
	v_lshl_add_u64 v[12:13], v[0:1], 1, s[18:19]
	v_add_u32_e32 v0, v75, v2
	v_or_b32_e32 v77, 0x1a400, v3
	v_lshl_add_u64 v[14:15], v[0:1], 1, s[18:19]
	v_add_u32_e32 v0, v77, v2
	v_or_b32_e32 v79, 0x1a800, v3
	v_lshl_add_u64 v[48:49], v[0:1], 1, s[18:19]
	v_add_u32_e32 v0, v79, v2
	v_lshl_add_u64 v[50:51], v[0:1], 1, s[18:19]
	v_or_b32_e32 v81, 0x1ac00, v3
	v_add_u32_e32 v0, v81, v2
	v_lshl_add_u64 v[52:53], v[0:1], 1, s[18:19]
	v_or_b32_e32 v83, 0x1c000, v3
	v_add_u32_e32 v0, v83, v2
	v_lshl_add_u64 v[54:55], v[0:1], 1, s[18:19]
	v_or_b32_e32 v85, 0x1c400, v3
	v_add_u32_e32 v0, v85, v2
	v_lshl_add_u64 v[56:57], v[0:1], 1, s[18:19]
	v_or_b32_e32 v87, 0x1c800, v3
	v_add_u32_e32 v0, v87, v2
	v_lshl_add_u64 v[58:59], v[0:1], 1, s[18:19]
	v_or_b32_e32 v89, 0x1cc00, v3
	v_add_u32_e32 v0, v89, v2
	v_lshl_add_u64 v[60:61], v[0:1], 1, s[18:19]
	v_or_b32_e32 v91, 0x1e000, v3
	v_add_u32_e32 v0, v91, v2
	v_lshl_add_u64 v[62:63], v[0:1], 1, s[18:19]
	v_or_b32_e32 v93, 0x1e400, v3
	v_add_u32_e32 v0, v93, v2
	v_or_b32_e32 v95, 0x1e800, v3
	v_lshl_add_u64 v[64:65], v[0:1], 1, s[18:19]
	v_add_u32_e32 v0, v95, v2
	v_or_b32_e32 v97, 0x1ec00, v3
	v_lshl_add_u64 v[66:67], v[0:1], 1, s[18:19]
	v_add_u32_e32 v0, v97, v2
	v_lshl_add_u64 v[2:3], v[0:1], 1, s[18:19]
	v_lshlrev_b32_e32 v69, 16, v224
	v_mul_f32_e32 v32, v32, v69
	v_lshlrev_b32_e32 v69, 16, v225
	v_cvt_pk_bf16_f32 v32, v32, s0
	v_mul_f32_e32 v33, v33, v69
	v_lshlrev_b32_e32 v69, 16, v226
	global_store_short v[6:7], v32, off
	v_cvt_pk_bf16_f32 v6, v33, s0
	v_mul_f32_e32 v7, v34, v69
	v_lshlrev_b32_e32 v32, 16, v227
	global_store_short v[8:9], v6, off
	v_cvt_pk_bf16_f32 v6, v7, s0
	v_mul_f32_e32 v7, v35, v32
	v_lshlrev_b32_e32 v8, 16, v228
	global_store_short v[10:11], v6, off
	v_cvt_pk_bf16_f32 v6, v7, s0
	v_mul_f32_e32 v7, v36, v8
	v_lshlrev_b32_e32 v8, 16, v229
	global_store_short v[12:13], v6, off
	v_cvt_pk_bf16_f32 v6, v7, s0
	v_mul_f32_e32 v7, v37, v8
	s_waitcnt vmcnt(59)
	v_lshlrev_b32_e32 v8, 16, v194
	global_store_short v[14:15], v6, off
	v_cvt_pk_bf16_f32 v6, v7, s0
	v_mul_f32_e32 v7, v38, v8
	s_waitcnt vmcnt(58)
	v_lshlrev_b32_e32 v8, 16, v195
	global_store_short v[48:49], v6, off
	v_cvt_pk_bf16_f32 v6, v7, s0
	global_store_short v[50:51], v6, off
	v_mul_f32_e32 v6, v39, v8
	v_cvt_pk_bf16_f32 v6, v6, s0
	global_store_short v[52:53], v6, off
	s_waitcnt vmcnt(59)
	v_lshlrev_b32_e32 v6, 16, v196
	v_mul_f32_e32 v6, v40, v6
	v_cvt_pk_bf16_f32 v6, v6, s0
	global_store_short v[54:55], v6, off
	s_waitcnt vmcnt(58)
	v_lshlrev_b32_e32 v6, 16, v197
	v_mul_f32_e32 v6, v41, v6
	v_cvt_pk_bf16_f32 v6, v6, s0
	global_store_short v[56:57], v6, off
	s_waitcnt vmcnt(55)
	v_lshlrev_b32_e32 v6, 16, v198
	v_mul_f32_e32 v6, v42, v6
	v_cvt_pk_bf16_f32 v6, v6, s0
	global_store_short v[58:59], v6, off
	s_waitcnt vmcnt(54)
	v_lshlrev_b32_e32 v6, 16, v199
	v_mul_f32_e32 v6, v43, v6
	v_cvt_pk_bf16_f32 v6, v6, s0
	global_store_short v[60:61], v6, off
	s_waitcnt vmcnt(53)
	v_lshlrev_b32_e32 v6, 16, v201
	v_mul_f32_e32 v6, v44, v6
	v_cvt_pk_bf16_f32 v6, v6, s0
	global_store_short v[62:63], v6, off
	s_waitcnt vmcnt(52)
	v_lshlrev_b32_e32 v6, 16, v202
	v_mul_f32_e32 v6, v45, v6
	s_waitcnt vmcnt(48)
	v_lshlrev_b32_e32 v0, 16, v204
	v_cvt_pk_bf16_f32 v6, v6, s0
	v_mul_f32_e32 v0, v47, v0
	global_store_short v[64:65], v6, off
	v_lshlrev_b32_e32 v6, 16, v203
	v_cvt_pk_bf16_f32 v0, v0, s0
	v_mul_f32_e32 v6, v46, v6
	global_store_short v[2:3], v0, off
	v_add_u32_e32 v0, v5, v4
	v_cvt_pk_bf16_f32 v6, v6, s0
	v_lshl_add_u64 v[2:3], v[0:1], 1, s[18:19]
	v_add_u32_e32 v0, v68, v4
	global_store_short v[66:67], v6, off
	v_lshl_add_u64 v[6:7], v[0:1], 1, s[18:19]
	v_add_u32_e32 v0, v71, v4
	v_lshl_add_u64 v[8:9], v[0:1], 1, s[18:19]
	v_add_u32_e32 v0, v73, v4
	v_lshl_add_u64 v[10:11], v[0:1], 1, s[18:19]
	v_add_u32_e32 v0, v75, v4
	v_lshl_add_u64 v[12:13], v[0:1], 1, s[18:19]
	v_add_u32_e32 v0, v77, v4
	v_lshl_add_u64 v[14:15], v[0:1], 1, s[18:19]
	v_add_u32_e32 v0, v79, v4
	v_lshl_add_u64 v[32:33], v[0:1], 1, s[18:19]
	v_add_u32_e32 v0, v81, v4
	v_lshl_add_u64 v[34:35], v[0:1], 1, s[18:19]
	v_add_u32_e32 v0, v83, v4
	v_lshl_add_u64 v[36:37], v[0:1], 1, s[18:19]
	v_add_u32_e32 v0, v85, v4
	v_lshl_add_u64 v[38:39], v[0:1], 1, s[18:19]
	v_add_u32_e32 v0, v87, v4
	v_lshl_add_u64 v[40:41], v[0:1], 1, s[18:19]
	v_add_u32_e32 v0, v89, v4
	v_lshl_add_u64 v[42:43], v[0:1], 1, s[18:19]
	v_add_u32_e32 v0, v91, v4
	v_lshl_add_u64 v[44:45], v[0:1], 1, s[18:19]
	v_add_u32_e32 v0, v93, v4
	v_lshl_add_u64 v[46:47], v[0:1], 1, s[18:19]
	v_add_u32_e32 v0, v95, v4
	v_lshl_add_u64 v[48:49], v[0:1], 1, s[18:19]
	v_add_u32_e32 v0, v97, v4
	v_lshl_add_u64 v[4:5], v[0:1], 1, s[18:19]
	s_waitcnt vmcnt(50)
	v_lshlrev_b32_e32 v50, 16, v206
	s_waitcnt vmcnt(48)
	v_lshlrev_b32_e32 v51, 16, v205
	s_waitcnt vmcnt(45)
	v_lshlrev_b32_e32 v52, 16, v209
	v_mul_f32_e32 v16, v16, v50
	v_mul_f32_e32 v17, v17, v51
	v_mul_f32_e32 v18, v18, v52
	v_cvt_pk_bf16_f32 v16, v16, s0
	v_cvt_pk_bf16_f32 v17, v17, s0
	global_store_short v[2:3], v16, off
	global_store_short v[6:7], v17, off
	v_cvt_pk_bf16_f32 v2, v18, s0
	global_store_short v[8:9], v2, off
	s_waitcnt vmcnt(47)
	v_lshlrev_b32_e32 v2, 16, v207
	v_mul_f32_e32 v2, v19, v2
	v_cvt_pk_bf16_f32 v2, v2, s0
	global_store_short v[10:11], v2, off
	s_waitcnt vmcnt(47)
	v_lshlrev_b32_e32 v2, 16, v210
	v_mul_f32_e32 v2, v20, v2
	v_cvt_pk_bf16_f32 v2, v2, s0
	global_store_short v[12:13], v2, off
	s_waitcnt vmcnt(44)
	v_lshlrev_b32_e32 v2, 16, v211
	v_mul_f32_e32 v2, v21, v2
	v_cvt_pk_bf16_f32 v2, v2, s0
	global_store_short v[14:15], v2, off
	s_waitcnt vmcnt(43)
	v_lshlrev_b32_e32 v2, 16, v212
	v_mul_f32_e32 v2, v22, v2
	v_cvt_pk_bf16_f32 v2, v2, s0
	global_store_short v[32:33], v2, off
	s_waitcnt vmcnt(42)
	v_lshlrev_b32_e32 v2, 16, v219
	v_mul_f32_e32 v2, v23, v2
	v_cvt_pk_bf16_f32 v2, v2, s0
	global_store_short v[34:35], v2, off
	s_waitcnt vmcnt(41)
	v_lshlrev_b32_e32 v2, 16, v213
	v_mul_f32_e32 v2, v24, v2
	v_cvt_pk_bf16_f32 v2, v2, s0
	global_store_short v[36:37], v2, off
	s_waitcnt vmcnt(40)
	v_lshlrev_b32_e32 v2, 16, v214
	v_mul_f32_e32 v2, v25, v2
	v_cvt_pk_bf16_f32 v2, v2, s0
	global_store_short v[38:39], v2, off
	s_waitcnt vmcnt(39)
	v_lshlrev_b32_e32 v2, 16, v215
	v_mul_f32_e32 v2, v26, v2
	v_cvt_pk_bf16_f32 v2, v2, s0
	global_store_short v[40:41], v2, off
	s_waitcnt vmcnt(38)
	v_lshlrev_b32_e32 v2, 16, v216
	v_mul_f32_e32 v2, v27, v2
	v_cvt_pk_bf16_f32 v2, v2, s0
	global_store_short v[42:43], v2, off
	s_waitcnt vmcnt(37)
	v_lshlrev_b32_e32 v2, 16, v217
	v_mul_f32_e32 v2, v28, v2
	v_cvt_pk_bf16_f32 v2, v2, s0
	global_store_short v[44:45], v2, off
	s_waitcnt vmcnt(36)
	v_lshlrev_b32_e32 v2, 16, v218
	v_mul_f32_e32 v2, v29, v2
	v_cvt_pk_bf16_f32 v2, v2, s0
	global_store_short v[46:47], v2, off
	s_waitcnt vmcnt(35)
	v_lshlrev_b32_e32 v2, 16, v220
	s_waitcnt vmcnt(33)
	v_lshlrev_b32_e32 v0, 16, v221
	v_mul_f32_e32 v2, v30, v2
	v_mul_f32_e32 v0, v31, v0
	v_cvt_pk_bf16_f32 v2, v2, s0
	v_cvt_pk_bf16_f32 v0, v0, s0
	global_store_short v[48:49], v2, off
	global_store_short v[4:5], v0, off
	v_mov_b32_e32 v0, v208
	s_lshl_b64 s[14:15], s[14:15], 1
	s_mov_b32 s1, 8
	s_add_u32 s14, s42, s14
	v_bfe_u32 v184, v0, 6, 2
	v_and_b32_e32 v185, 31, v0
	v_bfe_u32 v186, v0, 5, 1
	v_ashrrev_i32_e32 v2, 1, v0
	v_ashrrev_i32_e32 v35, 3, v0
	s_addc_u32 s15, s43, s15
	s_lshl_b64 s[4:5], s[4:5], 1
	v_lshlrev_b32_e32 v0, 4, v0
	s_add_u32 s4, s24, s4
	v_and_b32_e32 v34, 0x70, v0
	v_and_b32_e32 v187, 0xffffff80, v2
	s_addc_u32 s5, s25, s5
	v_lshl_or_b32 v0, v35, 10, v34
	s_cmp_gt_i32 s1, 1
	s_cselect_b32 s7, 0x80, 0
	v_add_u32_e32 v178, 0x10000, v0
	v_add_u32_e32 v180, 0x20000, v0
	v_add_u32_e32 v182, 0x30000, v0
	global_load_dwordx4 v[2:5], v0, s[14:15]
	global_load_dwordx4 v[6:9], v0, s[4:5]
	global_load_dwordx4 v[10:13], v178, s[14:15]
	global_load_dwordx4 v[14:17], v178, s[4:5]
	global_load_dwordx4 v[18:21], v180, s[14:15]
	global_load_dwordx4 v[22:25], v180, s[4:5]
	global_load_dwordx4 v[26:29], v182, s[14:15]
	global_load_dwordx4 v[30:33], v182, s[4:5]
	s_add_u32 s14, s14, s7
	s_addc_u32 s15, s15, 0
	s_add_u32 s4, s4, s7
	s_addc_u32 s5, s5, 0
	global_load_dwordx4 v[144:147], v0, s[14:15]
	global_load_dwordx4 v[156:159], v0, s[4:5]
	global_load_dwordx4 v[148:151], v178, s[14:15]
	global_load_dwordx4 v[152:155], v178, s[4:5]
	global_load_dwordx4 v[172:175], v180, s[14:15]
	global_load_dwordx4 v[160:163], v180, s[4:5]
	global_load_dwordx4 v[164:167], v182, s[14:15]
	global_load_dwordx4 v[168:171], v182, s[4:5]
	s_add_i32 s7, s1, -2
	v_mad_u64_u32 v[176:177], s[4:5], v35, s30, v[34:35]
	s_cmp_gt_i32 s1, 2
	s_cselect_b64 s[4:5], -1, 0
	v_mov_b32_e32 v179, v1
	v_mov_b32_e32 v181, v1
	v_mov_b32_e32 v183, v1
	s_mov_b64 s[14:15], -1
	s_and_b64 vcc, exec, s[12:13]
	s_waitcnt vmcnt(15)
	ds_write_b128 v176, v[2:5]
	s_waitcnt vmcnt(14)
	ds_write_b128 v176, v[6:9] offset:36864
	s_waitcnt vmcnt(13)
	ds_write_b128 v176, v[10:13] offset:9216
	s_waitcnt vmcnt(11)
	ds_write_b128 v176, v[18:21] offset:18432
	s_waitcnt vmcnt(9)
	ds_write_b128 v176, v[26:29] offset:27648
	ds_write_b128 v176, v[14:17] offset:46080
	ds_write_b128 v176, v[22:25] offset:55296
	s_waitcnt vmcnt(8)
	ds_write_b128 v176, v[30:33] offset:64512
	v_cndmask_b32_e64 v2, 0, 1, s[4:5]
	v_cmp_ne_u32_e64 s[4:5], 1, v2
	s_waitcnt lgkmcnt(0)
	s_cbranch_vccz .LBB0_3406
	s_and_b64 vcc, exec, s[4:5]
	s_barrier
	s_cbranch_vccnz .LBB0_3402
	s_add_u32 s12, s8, 0x13dbb00
	v_or_b32_e32 v2, v187, v185
	s_addc_u32 s13, s9, 0
	v_mul_lo_u32 v50, v2, s30
	v_lshlrev_b32_e32 v2, 3, v186
	v_lshl_or_b32 v3, v184, 6, v185
	v_lshl_add_u64 v[34:35], s[12:13], 0, v[0:1]
	v_lshl_add_u64 v[36:37], s[12:13], 0, v[178:179]
	v_lshl_add_u64 v[38:39], s[12:13], 0, v[180:181]
	v_lshl_add_u64 v[40:41], s[12:13], 0, v[182:183]
	s_add_u32 s12, s10, 0x4a0100
	v_mul_u32_u24_e32 v51, 0x90, v3
	s_addc_u32 s13, s11, 0
	v_mov_b32_e32 v80, 0
	v_lshlrev_b32_e32 v52, 1, v2
	s_waitcnt vmcnt(7)
	v_mov_b64_e32 v[2:3], v[144:145]
	s_waitcnt vmcnt(5)
	v_mov_b64_e32 v[6:7], v[148:149]
	s_waitcnt vmcnt(3)
	v_mov_b64_e32 v[10:11], v[172:173]
	s_waitcnt vmcnt(1)
	v_mov_b64_e32 v[14:15], v[164:165]
	v_mov_b64_e32 v[18:19], v[156:157]
	v_mov_b64_e32 v[26:27], v[152:153]
	v_mov_b64_e32 v[22:23], v[160:161]
	s_waitcnt vmcnt(0)
	v_mov_b64_e32 v[30:31], v[168:169]
	v_lshl_add_u64 v[42:43], s[12:13], 0, v[0:1]
	v_lshl_add_u64 v[44:45], s[12:13], 0, v[178:179]
	v_lshl_add_u64 v[46:47], s[12:13], 0, v[180:181]
	v_lshl_add_u64 v[48:49], s[12:13], 0, v[182:183]
	s_mov_b32 s14, 0
	s_mov_b64 s[12:13], s[90:91]
	v_mov_b64_e32 v[4:5], v[146:147]
	v_mov_b64_e32 v[8:9], v[150:151]
	v_mov_b64_e32 v[12:13], v[174:175]
	v_mov_b64_e32 v[16:17], v[166:167]
	v_mov_b64_e32 v[20:21], v[158:159]
	v_mov_b64_e32 v[28:29], v[154:155]
	v_mov_b64_e32 v[24:25], v[162:163]
	v_mov_b64_e32 v[32:33], v[170:171]
	v_mov_b32_e32 v81, v80
	v_mov_b32_e32 v82, v80
	v_mov_b32_e32 v83, v80
	v_mov_b32_e32 v84, v80
	v_mov_b32_e32 v85, v80
	v_mov_b32_e32 v86, v80
	v_mov_b32_e32 v87, v80
	v_mov_b32_e32 v88, v80
	v_mov_b32_e32 v89, v80
	v_mov_b32_e32 v90, v80
	v_mov_b32_e32 v91, v80
	v_mov_b32_e32 v92, v80
	v_mov_b32_e32 v93, v80
	v_mov_b32_e32 v94, v80
	v_mov_b32_e32 v95, v80
	v_mov_b32_e32 v96, v80
	v_mov_b32_e32 v97, v80
	v_mov_b32_e32 v98, v80
	v_mov_b32_e32 v99, v80
	v_mov_b32_e32 v100, v80
	v_mov_b32_e32 v101, v80
	v_mov_b32_e32 v102, v80
	v_mov_b32_e32 v103, v80
	v_mov_b32_e32 v104, v80
	v_mov_b32_e32 v105, v80
	v_mov_b32_e32 v106, v80
	v_mov_b32_e32 v107, v80
	v_mov_b32_e32 v108, v80
	v_mov_b32_e32 v109, v80
	v_mov_b32_e32 v110, v80
	v_mov_b32_e32 v111, v80
	v_mov_b32_e32 v112, v80
	v_mov_b32_e32 v113, v80
	v_mov_b32_e32 v114, v80
	v_mov_b32_e32 v115, v80
	v_mov_b32_e32 v116, v80
	v_mov_b32_e32 v117, v80
	v_mov_b32_e32 v118, v80
	v_mov_b32_e32 v119, v80
	v_mov_b32_e32 v120, v80
	v_mov_b32_e32 v121, v80
	v_mov_b32_e32 v122, v80
	v_mov_b32_e32 v123, v80
	v_mov_b32_e32 v124, v80
	v_mov_b32_e32 v125, v80
	v_mov_b32_e32 v126, v80
	v_mov_b32_e32 v127, v80
	v_mov_b32_e32 v128, v80
	v_mov_b32_e32 v129, v80
	v_mov_b32_e32 v130, v80
	v_mov_b32_e32 v131, v80
	v_mov_b32_e32 v132, v80
	v_mov_b32_e32 v133, v80
	v_mov_b32_e32 v134, v80
	v_mov_b32_e32 v135, v80
	v_mov_b32_e32 v136, v80
	v_mov_b32_e32 v137, v80
	v_mov_b32_e32 v138, v80
	v_mov_b32_e32 v139, v80
	v_mov_b32_e32 v140, v80
	v_mov_b32_e32 v141, v80
	v_mov_b32_e32 v142, v80
	v_mov_b32_e32 v143, v80
